# ds_reads hoisted to the front of every K-loop load segment (on saddr + equal priority + peeled iteration)
# speedup vs baseline: 1.0015x; 1.0015x over previous
; #define PG8_STAGE(bufoff, gbase, voff) do { _Pragma("unroll") for (int _i = 0; _i < 2; ++_i) \
;         __builtin_amdgcn_global_load_lds((const unsigned*)((const char*)(gbase) + (voff)[_i]), (LAS unsigned*)(lds + (bufoff) + ldsw + _i * 8192), 16, 0, 0); } while (0)
; #define PG8_LDA(dst, b, h) do { _Pragma("unroll") for (int m = 0; m < 4; ++m) _Pragma("unroll") for (int k = 0; k < 2; ++k) dst[m][k] = *(const LAS bf16x8*)(lds + PG8_SA(b, h) + aoff + m * 2048 + k * 1024); } while (0)
; #define PG8_LDB(dst, b, h) do { _Pragma("unroll") for (int n = 0; n < 2; ++n) _Pragma("unroll") for (int k = 0; k < 2; ++k) dst[n][k] = *(const LAS bf16x8*)(lds + PG8_SB(b, h) + boff + n * 2048 + k * 1024); } while (0)
; #define PG8_MMA(ai, bj, At, Bt) do { __builtin_amdgcn_s_setprio(1); _Pragma("unroll") for (int m = 0; m < 4; ++m) _Pragma("unroll") for (int n = 0; n < 2; ++n) _Pragma("unroll") for (int k = 0; k < 2; ++k) \
;         acc[ai][bj][m][n] = __builtin_amdgcn_mfma_f32_16x16x32_bf16(Bt[n][k], At[m][k], acc[ai][bj][m][n], 0, 0, 0); __builtin_amdgcn_s_setprio(0); } while (0)
; #define PG8_BAR __builtin_amdgcn_s_barrier()
; template <class Epi, class Sched, int KC, bool ALIGN_EPI = false, bool SP2 = false, bool ATILED = false>
; __device__ __forceinline__ void gemm_phase(LAS unsigned char* lds, const Gemm g, const Sched& S, const Epi& E, int wave_s) {
;     ...
;         for (int t = 0; t < nt; t += 2) {
;             const bool last = (t == nt - 2);
;             const char* a1 = cA + PG8_AOFF(t + 1);
;             const char* a2 = last ? nA : cA + PG8_AOFF(t + 2); const char* b2 = last ? nB : cB + (size_t)(t + 2) * kstep;
;             const char* a3 = a2 + kstep; const char* b3 = b2 + kstep;
;             if (last && has_next) S.a_ready(nxt);
;             if constexpr (SP2) {
;             PG8_LDB(B0, 0, 0); PG8_LDB(B1, 0, 1); PG8_SCHED; PG8_LDA(At, 0, 0); PG8_STAGE(PG8_SA(1, 1), a1 + hstepA, voffA);
;             PG8_WAIT_V(8); PG8_WAIT_L(0); PG8_BAR; PG8_MMA(0, 0, At, B0); PG8_MMA(0, 1, At, B1); PG8_BAR; PG8_SCHED;
;     ...
; #pragma unroll
;         for (int a = 0; a < 2; ++a)
; #pragma unroll
;             for (int b = 0; b < 2; ++b)
; #pragma unroll
;                 for (int m = 0; m < 4; ++m)
; #pragma unroll
;                     for (int n = 0; n < 2; ++n) acc[a][b][m][n] = (f32x4){0.f, 0.f, 0.f, 0.f};
;         cur = nxt; cA = nA; cB = nB; ++ui;
.LBB0_232:
	s_ashr_i32 s19, s18, 31
	s_lshl_b64 s[20:21], s[18:19], 17
	s_add_u32 s20, s39, s20
	s_addc_u32 s21, s40, s21
	s_and_b64 s[22:23], s[6:7], exec
	s_cselect_b32 s19, s21, s27
	s_cselect_b32 s53, s20, s26
	s_ashr_i32 s17, s16, 31
	s_lshl_b64 s[22:23], s[16:17], 20
	s_add_u32 s22, s41, s22
	s_addc_u32 s23, s42, s23
	s_and_b64 s[30:31], s[6:7], exec
	s_cselect_b32 s17, s23, s29
	s_cselect_b32 s54, s22, s28
	s_add_u32 s55, s28, 0x100
	v_mov_b32_e32 v2, 0
	s_addc_u32 s56, s29, 0
	s_mov_b32 s57, -2
	s_mov_b64 s[28:29], 0
	s_mov_b32 s58, 0x400000
	v_mov_b32_e32 v3, v2
	v_mov_b32_e32 v4, v2
	v_mov_b32_e32 v5, v2
	v_mov_b32_e32 v14, v2
	v_mov_b32_e32 v15, v2
	v_mov_b32_e32 v16, v2
	v_mov_b32_e32 v17, v2
	v_mov_b32_e32 v22, v2
	v_mov_b32_e32 v23, v2
	v_mov_b32_e32 v24, v2
	v_mov_b32_e32 v25, v2
	v_mov_b32_e32 v30, v2
	v_mov_b32_e32 v31, v2
	v_mov_b32_e32 v32, v2
	v_mov_b32_e32 v33, v2
	v_mov_b32_e32 v38, v2
	v_mov_b32_e32 v39, v2
	v_mov_b32_e32 v40, v2
	v_mov_b32_e32 v41, v2
	v_mov_b32_e32 v46, v2
	v_mov_b32_e32 v47, v2
	v_mov_b32_e32 v48, v2
	v_mov_b32_e32 v49, v2
	v_mov_b32_e32 v54, v2
	v_mov_b32_e32 v55, v2
	v_mov_b32_e32 v56, v2
	v_mov_b32_e32 v57, v2
	v_mov_b32_e32 v62, v2
	v_mov_b32_e32 v63, v2
	v_mov_b32_e32 v64, v2
	v_mov_b32_e32 v65, v2
	v_mov_b32_e32 v6, v2
	v_mov_b32_e32 v7, v2
	v_mov_b32_e32 v8, v2
	v_mov_b32_e32 v9, v2
	v_mov_b32_e32 v10, v2
	v_mov_b32_e32 v11, v2
	v_mov_b32_e32 v12, v2
	v_mov_b32_e32 v13, v2
	v_mov_b32_e32 v18, v2
	v_mov_b32_e32 v19, v2
	v_mov_b32_e32 v20, v2
	v_mov_b32_e32 v21, v2
	v_mov_b32_e32 v26, v2
	v_mov_b32_e32 v27, v2
	v_mov_b32_e32 v28, v2
	v_mov_b32_e32 v29, v2
	v_mov_b32_e32 v34, v2
	v_mov_b32_e32 v35, v2
	v_mov_b32_e32 v36, v2
	v_mov_b32_e32 v37, v2
	v_mov_b32_e32 v42, v2
	v_mov_b32_e32 v43, v2
	v_mov_b32_e32 v44, v2
	v_mov_b32_e32 v45, v2
	v_mov_b32_e32 v50, v2
	v_mov_b32_e32 v51, v2
	v_mov_b32_e32 v52, v2
	v_mov_b32_e32 v53, v2
	v_mov_b32_e32 v58, v2
	v_mov_b32_e32 v59, v2
	v_mov_b32_e32 v60, v2
	v_mov_b32_e32 v61, v2
	v_mov_b32_e32 v70, v2
	v_mov_b32_e32 v71, v2
	v_mov_b32_e32 v72, v2
	v_mov_b32_e32 v73, v2
	v_mov_b32_e32 v78, v2
	v_mov_b32_e32 v79, v2
	v_mov_b32_e32 v80, v2
	v_mov_b32_e32 v81, v2
	v_mov_b32_e32 v86, v2
	v_mov_b32_e32 v87, v2
	v_mov_b32_e32 v88, v2
	v_mov_b32_e32 v89, v2
	v_mov_b32_e32 v94, v2
	v_mov_b32_e32 v95, v2
	v_mov_b32_e32 v96, v2
	v_mov_b32_e32 v97, v2
	v_mov_b32_e32 v102, v2
	v_mov_b32_e32 v103, v2
	v_mov_b32_e32 v104, v2
	v_mov_b32_e32 v105, v2
	v_mov_b32_e32 v110, v2
	v_mov_b32_e32 v111, v2
	v_mov_b32_e32 v112, v2
	v_mov_b32_e32 v113, v2
	v_mov_b32_e32 v118, v2
	v_mov_b32_e32 v119, v2
	v_mov_b32_e32 v120, v2
	v_mov_b32_e32 v121, v2
	v_mov_b32_e32 v126, v2
	v_mov_b32_e32 v127, v2
	v_mov_b32_e32 v128, v2
	v_mov_b32_e32 v129, v2
	v_mov_b32_e32 v66, v2
	v_mov_b32_e32 v67, v2
	v_mov_b32_e32 v68, v2
	v_mov_b32_e32 v69, v2
	v_mov_b32_e32 v74, v2
	v_mov_b32_e32 v75, v2
	v_mov_b32_e32 v76, v2
	v_mov_b32_e32 v77, v2
	v_mov_b32_e32 v82, v2
	v_mov_b32_e32 v83, v2
	v_mov_b32_e32 v84, v2
	v_mov_b32_e32 v85, v2
	v_mov_b32_e32 v90, v2
	v_mov_b32_e32 v91, v2
	v_mov_b32_e32 v92, v2
	v_mov_b32_e32 v93, v2
	v_mov_b32_e32 v98, v2
	v_mov_b32_e32 v99, v2
	v_mov_b32_e32 v100, v2
	v_mov_b32_e32 v101, v2
	v_mov_b32_e32 v106, v2
	v_mov_b32_e32 v107, v2
	v_mov_b32_e32 v108, v2
	v_mov_b32_e32 v109, v2
	v_mov_b32_e32 v114, v2
	v_mov_b32_e32 v115, v2
	v_mov_b32_e32 v116, v2
	v_mov_b32_e32 v117, v2
	v_mov_b32_e32 v122, v2
	v_mov_b32_e32 v123, v2
	v_mov_b32_e32 v124, v2
	v_mov_b32_e32 v125, v2
	s_add_i32 s62, 0, 0x10000
	v_add_u32_e32 v139, s62, v163
	ds_read_b128 v[152:155], v139
	ds_read_b128 v[156:159], v139 offset:1024
	ds_read_b128 v[168:171], v139 offset:2048
	ds_read_b128 v[172:175], v139 offset:3072
	s_add_i32 s63, 0, 0x14000
	v_add_u32_e32 v139, s63, v163
	ds_read_b128 v[176:179], v139
	ds_read_b128 v[180:183], v139 offset:1024
	ds_read_b128 v[184:187], v139 offset:2048
	ds_read_b128 v[188:191], v139 offset:3072
	ds_read_b128 v[198:201], v166
	ds_read_b128 v[202:205], v166 offset:1024
	ds_read_b128 v[206:209], v166 offset:2048
	ds_read_b128 v[210:213], v166 offset:3072
	ds_read_b128 v[214:217], v166 offset:4096
	ds_read_b128 v[218:221], v166 offset:5120
	ds_read_b128 v[222:225], v166 offset:6144
	ds_read_b128 v[226:229], v166 offset:7168
	s_add_i32 s30, s58, 0xffc00000
	s_and_b32 s30, s30, 0x3800000
	s_and_b32 s31, s28, 0x100
	s_or_b32 s59, s31, s30
	s_and_b32 s34, s58, 0x7800000
	s_add_u32 s30, s28, 0x100
	s_addc_u32 s31, s29, 0
	s_and_b32 s35, s30, 0x100
	s_or_b32 s34, s34, s35
	s_add_u32 s34, s26, s34
	s_addc_u32 s35, s27, 0
	s_add_u32 s28, s55, s28
	s_addc_u32 s29, s56, s29
	s_cmp_eq_u32 s57, 28
	s_cselect_b32 s35, s19, s35
	s_cselect_b32 s34, s53, s34
	s_cselect_b32 s29, s17, s29
	s_cselect_b32 s28, s54, s28
	s_add_u32 s59, s26, s59
	s_addc_u32 s61, s27, 0
	s_add_u32 s60, s59, 0x10080
	s_addc_u32 s61, s61, 0
	s_add_i32 m0, s44, 0xc000
	s_nop 0
	global_load_lds_dwordx4 v136, s[60:61]
	s_add_i32 m0, s44, 0xe000
	s_nop 0
	global_load_lds_dwordx4 v132, s[60:61]
	s_waitcnt vmcnt(16)
	s_waitcnt lgkmcnt(0)
	s_barrier
; #define PG8_STAGE(bufoff, gbase, voff) do { _Pragma("unroll") for (int _i = 0; _i < 2; ++_i) \
;         __builtin_amdgcn_global_load_lds((const unsigned*)((const char*)(gbase) + (voff)[_i]), (LAS unsigned*)(lds + (bufoff) + ldsw + _i * 8192), 16, 0, 0); } while (0)
; #define PG8_LDA(dst, b, h) do { _Pragma("unroll") for (int m = 0; m < 4; ++m) _Pragma("unroll") for (int k = 0; k < 2; ++k) dst[m][k] = *(const LAS bf16x8*)(lds + PG8_SA(b, h) + aoff + m * 2048 + k * 1024); } while (0)
; #define PG8_MMA(ai, bj, At, Bt) do { __builtin_amdgcn_s_setprio(1); _Pragma("unroll") for (int m = 0; m < 4; ++m) _Pragma("unroll") for (int n = 0; n < 2; ++n) _Pragma("unroll") for (int k = 0; k < 2; ++k) \
;         acc[ai][bj][m][n] = __builtin_amdgcn_mfma_f32_16x16x32_bf16(Bt[n][k], At[m][k], acc[ai][bj][m][n], 0, 0, 0); __builtin_amdgcn_s_setprio(0); } while (0)
; #define PG8_WAIT_V(n) asm volatile("s_waitcnt vmcnt(" #n ")" ::: "memory")
; #define PG8_WAIT_L(n) asm volatile("s_waitcnt lgkmcnt(" #n ")" ::: "memory")
; #define PG8_BAR __builtin_amdgcn_s_barrier()
; #define PG8_SCHED __builtin_amdgcn_sched_barrier(0)
; template <class Epi, class Sched, int KC, bool ALIGN_EPI = false, bool SP2 = false, bool ATILED = false>
; __device__ __forceinline__ void gemm_phase(LAS unsigned char* lds, const Gemm g, const Sched& S, const Epi& E, int wave_s) {
;     ...
;             PG8_WAIT_V(8); PG8_WAIT_L(0); PG8_BAR; PG8_MMA(0, 0, At, B0); PG8_MMA(0, 1, At, B1); PG8_BAR; PG8_SCHED;
;             PG8_LDA(At, 0, 1); PG8_STAGE(PG8_SB(0, 0), b2, voffB); PG8_STAGE(PG8_SB(0, 1), b2 + hstepB, voffB); PG8_STAGE(PG8_SA(0, 0), a2, voffA);
;             PG8_WAIT_V(8); PG8_WAIT_L(0); PG8_BAR; PG8_MMA(1, 0, At, B0); PG8_MMA(1, 1, At, B1); PG8_BAR; PG8_SCHED;
	s_waitcnt lgkmcnt(0)
	v_mfma_f32_16x16x32_bf16 v[122:125], v[152:155], v[198:201], v[122:125]
	v_mfma_f32_16x16x32_bf16 v[114:117], v[168:171], v[198:201], v[114:117]
	v_mfma_f32_16x16x32_bf16 v[106:109], v[152:155], v[206:209], v[106:109]
	v_mfma_f32_16x16x32_bf16 v[98:101], v[168:171], v[206:209], v[98:101]
	v_mfma_f32_16x16x32_bf16 v[90:93], v[152:155], v[214:217], v[90:93]
	v_mfma_f32_16x16x32_bf16 v[82:85], v[168:171], v[214:217], v[82:85]
	v_mfma_f32_16x16x32_bf16 v[74:77], v[152:155], v[222:225], v[74:77]
	v_mfma_f32_16x16x32_bf16 v[66:69], v[168:171], v[222:225], v[66:69]
	v_mfma_f32_16x16x32_bf16 v[122:125], v[156:159], v[202:205], v[122:125]
	v_mfma_f32_16x16x32_bf16 v[114:117], v[172:175], v[202:205], v[114:117]
	v_mfma_f32_16x16x32_bf16 v[106:109], v[156:159], v[210:213], v[106:109]
	v_mfma_f32_16x16x32_bf16 v[98:101], v[172:175], v[210:213], v[98:101]
	v_mfma_f32_16x16x32_bf16 v[90:93], v[156:159], v[218:221], v[90:93]
	v_mfma_f32_16x16x32_bf16 v[82:85], v[172:175], v[218:221], v[82:85]
	v_mfma_f32_16x16x32_bf16 v[74:77], v[156:159], v[226:229], v[74:77]
	v_mfma_f32_16x16x32_bf16 v[66:69], v[172:175], v[226:229], v[66:69]
	v_mfma_f32_16x16x32_bf16 v[126:129], v[176:179], v[198:201], v[126:129]
	v_mfma_f32_16x16x32_bf16 v[118:121], v[184:187], v[198:201], v[118:121]
	v_mfma_f32_16x16x32_bf16 v[110:113], v[176:179], v[206:209], v[110:113]
	v_mfma_f32_16x16x32_bf16 v[102:105], v[184:187], v[206:209], v[102:105]
	v_mfma_f32_16x16x32_bf16 v[94:97], v[176:179], v[214:217], v[94:97]
	v_mfma_f32_16x16x32_bf16 v[86:89], v[184:187], v[214:217], v[86:89]
	v_mfma_f32_16x16x32_bf16 v[78:81], v[176:179], v[222:225], v[78:81]
	v_mfma_f32_16x16x32_bf16 v[70:73], v[184:187], v[222:225], v[70:73]
	v_mfma_f32_16x16x32_bf16 v[126:129], v[180:183], v[202:205], v[126:129]
	v_mfma_f32_16x16x32_bf16 v[118:121], v[188:191], v[202:205], v[118:121]
	v_mfma_f32_16x16x32_bf16 v[110:113], v[180:183], v[210:213], v[110:113]
	v_mfma_f32_16x16x32_bf16 v[102:105], v[188:191], v[210:213], v[102:105]
	v_mfma_f32_16x16x32_bf16 v[94:97], v[180:183], v[218:221], v[94:97]
	v_mfma_f32_16x16x32_bf16 v[86:89], v[188:191], v[218:221], v[86:89]
	v_mfma_f32_16x16x32_bf16 v[78:81], v[180:183], v[226:229], v[78:81]
	v_mfma_f32_16x16x32_bf16 v[70:73], v[188:191], v[226:229], v[70:73]
	s_barrier
	ds_read_b128 v[198:201], v166 offset:16384
	ds_read_b128 v[202:205], v166 offset:17408
	ds_read_b128 v[206:209], v166 offset:18432
	ds_read_b128 v[210:213], v166 offset:19456
	ds_read_b128 v[214:217], v166 offset:20480
	ds_read_b128 v[218:221], v166 offset:21504
	ds_read_b128 v[222:225], v166 offset:22528
	ds_read_b128 v[226:229], v166 offset:23552
	s_add_u32 s100, s34, 0x80
	s_addc_u32 s101, s35, 0
	s_add_i32 s59, s62, s38
	s_mov_b32 m0, s59
	s_nop 0
	global_load_lds_dwordx4 v134, s[28:29]
	s_add_i32 m0, s59, 0x2000
	s_add_u32 s60, s28, 0x80000
	s_addc_u32 s61, s29, 0
	s_add_i32 s59, s63, s38
	global_load_lds_dwordx4 v130, s[28:29]
	s_mov_b32 m0, s59
	s_nop 0
	global_load_lds_dwordx4 v134, s[60:61]
	s_add_i32 m0, s59, 0x2000
	s_nop 0
	global_load_lds_dwordx4 v130, s[60:61]
	s_mov_b32 m0, s44
	s_nop 0
	global_load_lds_dwordx4 v136, s[34:35]
	s_mov_b32 m0, s45
	s_nop 0
	global_load_lds_dwordx4 v132, s[34:35]
	s_waitcnt vmcnt(16)
	s_waitcnt lgkmcnt(0)
	s_barrier
	s_waitcnt lgkmcnt(0)
	v_mfma_f32_16x16x32_bf16 v[58:61], v[152:155], v[198:201], v[58:61]
	v_mfma_f32_16x16x32_bf16 v[50:53], v[168:171], v[198:201], v[50:53]
	v_mfma_f32_16x16x32_bf16 v[42:45], v[152:155], v[206:209], v[42:45]
	v_mfma_f32_16x16x32_bf16 v[34:37], v[168:171], v[206:209], v[34:37]
	v_mfma_f32_16x16x32_bf16 v[26:29], v[152:155], v[214:217], v[26:29]
	v_mfma_f32_16x16x32_bf16 v[18:21], v[168:171], v[214:217], v[18:21]
	v_mfma_f32_16x16x32_bf16 v[10:13], v[152:155], v[222:225], v[10:13]
	v_mfma_f32_16x16x32_bf16 v[6:9], v[168:171], v[222:225], v[6:9]
	v_mfma_f32_16x16x32_bf16 v[58:61], v[156:159], v[202:205], v[58:61]
	v_mfma_f32_16x16x32_bf16 v[50:53], v[172:175], v[202:205], v[50:53]
	v_mfma_f32_16x16x32_bf16 v[42:45], v[156:159], v[210:213], v[42:45]
	v_mfma_f32_16x16x32_bf16 v[34:37], v[172:175], v[210:213], v[34:37]
	v_mfma_f32_16x16x32_bf16 v[26:29], v[156:159], v[218:221], v[26:29]
	v_mfma_f32_16x16x32_bf16 v[18:21], v[172:175], v[218:221], v[18:21]
	v_mfma_f32_16x16x32_bf16 v[10:13], v[156:159], v[226:229], v[10:13]
	v_mfma_f32_16x16x32_bf16 v[6:9], v[172:175], v[226:229], v[6:9]
	v_mfma_f32_16x16x32_bf16 v[62:65], v[176:179], v[198:201], v[62:65]
	v_mfma_f32_16x16x32_bf16 v[54:57], v[184:187], v[198:201], v[54:57]
	v_mfma_f32_16x16x32_bf16 v[46:49], v[176:179], v[206:209], v[46:49]
	v_mfma_f32_16x16x32_bf16 v[38:41], v[184:187], v[206:209], v[38:41]
	v_mfma_f32_16x16x32_bf16 v[30:33], v[176:179], v[214:217], v[30:33]
	v_mfma_f32_16x16x32_bf16 v[22:25], v[184:187], v[214:217], v[22:25]
	v_mfma_f32_16x16x32_bf16 v[14:17], v[176:179], v[222:225], v[14:17]
	v_mfma_f32_16x16x32_bf16 v[2:5], v[184:187], v[222:225], v[2:5]
	v_mfma_f32_16x16x32_bf16 v[62:65], v[180:183], v[202:205], v[62:65]
	v_mfma_f32_16x16x32_bf16 v[54:57], v[188:191], v[202:205], v[54:57]
	v_mfma_f32_16x16x32_bf16 v[46:49], v[180:183], v[210:213], v[46:49]
	v_mfma_f32_16x16x32_bf16 v[38:41], v[188:191], v[210:213], v[38:41]
	v_mfma_f32_16x16x32_bf16 v[30:33], v[180:183], v[218:221], v[30:33]
	v_mfma_f32_16x16x32_bf16 v[22:25], v[188:191], v[218:221], v[22:25]
	v_mfma_f32_16x16x32_bf16 v[14:17], v[180:183], v[226:229], v[14:17]
	v_mfma_f32_16x16x32_bf16 v[2:5], v[188:191], v[226:229], v[2:5]
	s_barrier
; #define PG8_STAGE(bufoff, gbase, voff) do { _Pragma("unroll") for (int _i = 0; _i < 2; ++_i) \
;         __builtin_amdgcn_global_load_lds((const unsigned*)((const char*)(gbase) + (voff)[_i]), (LAS unsigned*)(lds + (bufoff) + ldsw + _i * 8192), 16, 0, 0); } while (0)
; #define PG8_LDA(dst, b, h) do { _Pragma("unroll") for (int m = 0; m < 4; ++m) _Pragma("unroll") for (int k = 0; k < 2; ++k) dst[m][k] = *(const LAS bf16x8*)(lds + PG8_SA(b, h) + aoff + m * 2048 + k * 1024); } while (0)
; #define PG8_LDB(dst, b, h) do { _Pragma("unroll") for (int n = 0; n < 2; ++n) _Pragma("unroll") for (int k = 0; k < 2; ++k) dst[n][k] = *(const LAS bf16x8*)(lds + PG8_SB(b, h) + boff + n * 2048 + k * 1024); } while (0)
; #define PG8_MMA(ai, bj, At, Bt) do { __builtin_amdgcn_s_setprio(1); _Pragma("unroll") for (int m = 0; m < 4; ++m) _Pragma("unroll") for (int n = 0; n < 2; ++n) _Pragma("unroll") for (int k = 0; k < 2; ++k) \
;         acc[ai][bj][m][n] = __builtin_amdgcn_mfma_f32_16x16x32_bf16(Bt[n][k], At[m][k], acc[ai][bj][m][n], 0, 0, 0); __builtin_amdgcn_s_setprio(0); } while (0)
; #define PG8_WAIT_V(n) asm volatile("s_waitcnt vmcnt(" #n ")" ::: "memory")
; #define PG8_WAIT_L(n) asm volatile("s_waitcnt lgkmcnt(" #n ")" ::: "memory")
; #define PG8_BAR __builtin_amdgcn_s_barrier()
; #define PG8_SCHED __builtin_amdgcn_sched_barrier(0)
; template <class Epi, class Sched, int KC, bool ALIGN_EPI = false, bool SP2 = false, bool ATILED = false>
; __device__ __forceinline__ void gemm_phase(LAS unsigned char* lds, const Gemm g, const Sched& S, const Epi& E, int wave_s) {
;     ...
;             PG8_LDB(B0, 1, 0); PG8_LDB(B1, 1, 1); PG8_SCHED; PG8_LDA(At, 1, 0); PG8_STAGE(PG8_SA(0, 1), a2 + hstepA, voffA);
;             PG8_WAIT_V(8); PG8_WAIT_L(0); PG8_BAR; PG8_MMA(0, 0, At, B0); PG8_MMA(0, 1, At, B1); PG8_BAR; PG8_SCHED;
;             PG8_LDA(At, 1, 1); PG8_STAGE(PG8_SB(1, 0), b3, voffB); PG8_STAGE(PG8_SB(1, 1), b3 + hstepB, voffB); PG8_STAGE(PG8_SA(1, 0), a3, voffA);
;             PG8_WAIT_V(8); PG8_WAIT_L(0); PG8_BAR; PG8_MMA(1, 0, At, B0); PG8_MMA(1, 1, At, B1); PG8_BAR; PG8_SCHED;
	s_add_i32 s59, 0, 0x18000
	v_add_u32_e32 v139, s59, v163
	ds_read_b128 v[152:155], v139
	ds_read_b128 v[156:159], v139 offset:1024
	ds_read_b128 v[168:171], v139 offset:2048
	ds_read_b128 v[172:175], v139 offset:3072
	s_add_i32 s60, 0, 0x1c000
	v_add_u32_e32 v139, s60, v163
	ds_read_b128 v[176:179], v139
	ds_read_b128 v[180:183], v139 offset:1024
	ds_read_b128 v[184:187], v139 offset:2048
	ds_read_b128 v[188:191], v139 offset:3072
	ds_read_b128 v[198:201], v166 offset:32768
	ds_read_b128 v[202:205], v166 offset:33792
	ds_read_b128 v[206:209], v166 offset:34816
	ds_read_b128 v[210:213], v166 offset:35840
	ds_read_b128 v[214:217], v166 offset:36864
	ds_read_b128 v[218:221], v166 offset:37888
	ds_read_b128 v[222:225], v166 offset:38912
	ds_read_b128 v[226:229], v166 offset:39936
	s_add_u32 s34, s34, 0x10000
	s_addc_u32 s35, s35, 0
	s_mov_b32 m0, s46
	s_nop 0
	global_load_lds_dwordx4 v136, s[34:35]
	s_mov_b32 m0, s47
	s_nop 0
	global_load_lds_dwordx4 v132, s[34:35]
	s_waitcnt vmcnt(8)
	s_waitcnt lgkmcnt(0)
	s_barrier
	s_waitcnt lgkmcnt(0)
	v_mfma_f32_16x16x32_bf16 v[122:125], v[152:155], v[198:201], v[122:125]
	v_mfma_f32_16x16x32_bf16 v[114:117], v[168:171], v[198:201], v[114:117]
	v_mfma_f32_16x16x32_bf16 v[106:109], v[152:155], v[206:209], v[106:109]
	v_mfma_f32_16x16x32_bf16 v[98:101], v[168:171], v[206:209], v[98:101]
	v_mfma_f32_16x16x32_bf16 v[90:93], v[152:155], v[214:217], v[90:93]
	v_mfma_f32_16x16x32_bf16 v[82:85], v[168:171], v[214:217], v[82:85]
	v_mfma_f32_16x16x32_bf16 v[74:77], v[152:155], v[222:225], v[74:77]
	v_mfma_f32_16x16x32_bf16 v[66:69], v[168:171], v[222:225], v[66:69]
	v_mfma_f32_16x16x32_bf16 v[122:125], v[156:159], v[202:205], v[122:125]
	v_mfma_f32_16x16x32_bf16 v[114:117], v[172:175], v[202:205], v[114:117]
	v_mfma_f32_16x16x32_bf16 v[106:109], v[156:159], v[210:213], v[106:109]
	v_mfma_f32_16x16x32_bf16 v[98:101], v[172:175], v[210:213], v[98:101]
	v_mfma_f32_16x16x32_bf16 v[90:93], v[156:159], v[218:221], v[90:93]
	v_mfma_f32_16x16x32_bf16 v[82:85], v[172:175], v[218:221], v[82:85]
	v_mfma_f32_16x16x32_bf16 v[74:77], v[156:159], v[226:229], v[74:77]
	v_mfma_f32_16x16x32_bf16 v[66:69], v[172:175], v[226:229], v[66:69]
	v_mfma_f32_16x16x32_bf16 v[126:129], v[176:179], v[198:201], v[126:129]
	v_mfma_f32_16x16x32_bf16 v[118:121], v[184:187], v[198:201], v[118:121]
	v_mfma_f32_16x16x32_bf16 v[110:113], v[176:179], v[206:209], v[110:113]
	v_mfma_f32_16x16x32_bf16 v[102:105], v[184:187], v[206:209], v[102:105]
	v_mfma_f32_16x16x32_bf16 v[94:97], v[176:179], v[214:217], v[94:97]
	v_mfma_f32_16x16x32_bf16 v[86:89], v[184:187], v[214:217], v[86:89]
	v_mfma_f32_16x16x32_bf16 v[78:81], v[176:179], v[222:225], v[78:81]
	v_mfma_f32_16x16x32_bf16 v[70:73], v[184:187], v[222:225], v[70:73]
	v_mfma_f32_16x16x32_bf16 v[126:129], v[180:183], v[202:205], v[126:129]
	v_mfma_f32_16x16x32_bf16 v[118:121], v[188:191], v[202:205], v[118:121]
	v_mfma_f32_16x16x32_bf16 v[110:113], v[180:183], v[210:213], v[110:113]
	v_mfma_f32_16x16x32_bf16 v[102:105], v[188:191], v[210:213], v[102:105]
	v_mfma_f32_16x16x32_bf16 v[94:97], v[180:183], v[218:221], v[94:97]
	v_mfma_f32_16x16x32_bf16 v[86:89], v[188:191], v[218:221], v[86:89]
	v_mfma_f32_16x16x32_bf16 v[78:81], v[180:183], v[226:229], v[78:81]
	v_mfma_f32_16x16x32_bf16 v[70:73], v[188:191], v[226:229], v[70:73]
	s_barrier
	ds_read_b128 v[198:201], v166 offset:49152
	ds_read_b128 v[202:205], v166 offset:50176
	ds_read_b128 v[206:209], v166 offset:51200
	ds_read_b128 v[210:213], v166 offset:52224
	ds_read_b128 v[214:217], v166 offset:53248
	ds_read_b128 v[218:221], v166 offset:54272
	ds_read_b128 v[222:225], v166 offset:55296
	ds_read_b128 v[226:229], v166 offset:56320
	s_add_u32 s98, s28, 0x80
	s_addc_u32 s99, s29, 0
	s_add_i32 s34, s59, s38
	s_mov_b32 m0, s34
	s_nop 0
	global_load_lds_dwordx4 v134, s[98:99]
	s_add_i32 m0, s34, 0x2000
	s_add_u32 s28, s28, 0x80080
	s_addc_u32 s29, s29, 0
	s_add_i32 s34, s60, s38
	global_load_lds_dwordx4 v130, s[98:99]
	s_mov_b32 m0, s34
	s_nop 0
	global_load_lds_dwordx4 v134, s[28:29]
	s_add_i32 m0, s34, 0x2000
	s_nop 0
	global_load_lds_dwordx4 v130, s[28:29]
	s_mov_b32 m0, s48
	s_nop 0
	global_load_lds_dwordx4 v136, s[100:101]
	s_mov_b32 m0, s49
	s_nop 0
	global_load_lds_dwordx4 v132, s[100:101]
	s_waitcnt vmcnt(8)
	s_waitcnt lgkmcnt(0)
	s_barrier
	s_waitcnt lgkmcnt(0)
	v_mfma_f32_16x16x32_bf16 v[58:61], v[152:155], v[198:201], v[58:61]
	v_mfma_f32_16x16x32_bf16 v[50:53], v[168:171], v[198:201], v[50:53]
	v_mfma_f32_16x16x32_bf16 v[42:45], v[152:155], v[206:209], v[42:45]
	v_mfma_f32_16x16x32_bf16 v[34:37], v[168:171], v[206:209], v[34:37]
	v_mfma_f32_16x16x32_bf16 v[26:29], v[152:155], v[214:217], v[26:29]
	v_mfma_f32_16x16x32_bf16 v[18:21], v[168:171], v[214:217], v[18:21]
	v_mfma_f32_16x16x32_bf16 v[10:13], v[152:155], v[222:225], v[10:13]
	v_mfma_f32_16x16x32_bf16 v[6:9], v[168:171], v[222:225], v[6:9]
	v_mfma_f32_16x16x32_bf16 v[58:61], v[156:159], v[202:205], v[58:61]
	v_mfma_f32_16x16x32_bf16 v[50:53], v[172:175], v[202:205], v[50:53]
	v_mfma_f32_16x16x32_bf16 v[42:45], v[156:159], v[210:213], v[42:45]
	v_mfma_f32_16x16x32_bf16 v[34:37], v[172:175], v[210:213], v[34:37]
	v_mfma_f32_16x16x32_bf16 v[26:29], v[156:159], v[218:221], v[26:29]
	v_mfma_f32_16x16x32_bf16 v[18:21], v[172:175], v[218:221], v[18:21]
	v_mfma_f32_16x16x32_bf16 v[10:13], v[156:159], v[226:229], v[10:13]
	v_mfma_f32_16x16x32_bf16 v[6:9], v[172:175], v[226:229], v[6:9]
	v_mfma_f32_16x16x32_bf16 v[62:65], v[176:179], v[198:201], v[62:65]
	v_mfma_f32_16x16x32_bf16 v[54:57], v[184:187], v[198:201], v[54:57]
	v_mfma_f32_16x16x32_bf16 v[46:49], v[176:179], v[206:209], v[46:49]
	v_mfma_f32_16x16x32_bf16 v[38:41], v[184:187], v[206:209], v[38:41]
	v_mfma_f32_16x16x32_bf16 v[30:33], v[176:179], v[214:217], v[30:33]
	v_mfma_f32_16x16x32_bf16 v[22:25], v[184:187], v[214:217], v[22:25]
	v_mfma_f32_16x16x32_bf16 v[14:17], v[176:179], v[222:225], v[14:17]
	v_mfma_f32_16x16x32_bf16 v[2:5], v[184:187], v[222:225], v[2:5]
	v_mfma_f32_16x16x32_bf16 v[62:65], v[180:183], v[202:205], v[62:65]
	v_mfma_f32_16x16x32_bf16 v[54:57], v[188:191], v[202:205], v[54:57]
	v_mfma_f32_16x16x32_bf16 v[46:49], v[180:183], v[210:213], v[46:49]
	v_mfma_f32_16x16x32_bf16 v[38:41], v[188:191], v[210:213], v[38:41]
	v_mfma_f32_16x16x32_bf16 v[30:33], v[180:183], v[218:221], v[30:33]
	v_mfma_f32_16x16x32_bf16 v[22:25], v[188:191], v[218:221], v[22:25]
	v_mfma_f32_16x16x32_bf16 v[14:17], v[180:183], v[226:229], v[14:17]
	v_mfma_f32_16x16x32_bf16 v[2:5], v[188:191], v[226:229], v[2:5]
	s_barrier
	s_add_i32 s57, s57, 2
	s_add_i32 s58, s58, 0x400000
	s_cmp_gt_u32 s57, 29
	s_mov_b64 s[28:29], s[30:31]
; #define PG8_STAGE(bufoff, gbase, voff) do { _Pragma("unroll") for (int _i = 0; _i < 2; ++_i) \
;         __builtin_amdgcn_global_load_lds((const unsigned*)((const char*)(gbase) + (voff)[_i]), (LAS unsigned*)(lds + (bufoff) + ldsw + _i * 8192), 16, 0, 0); } while (0)
; #define PG8_LDA(dst, b, h) do { _Pragma("unroll") for (int m = 0; m < 4; ++m) _Pragma("unroll") for (int k = 0; k < 2; ++k) dst[m][k] = *(const LAS bf16x8*)(lds + PG8_SA(b, h) + aoff + m * 2048 + k * 1024); } while (0)
; #define PG8_LDB(dst, b, h) do { _Pragma("unroll") for (int n = 0; n < 2; ++n) _Pragma("unroll") for (int k = 0; k < 2; ++k) dst[n][k] = *(const LAS bf16x8*)(lds + PG8_SB(b, h) + boff + n * 2048 + k * 1024); } while (0)
; #define PG8_MMA(ai, bj, At, Bt) do { __builtin_amdgcn_s_setprio(1); _Pragma("unroll") for (int m = 0; m < 4; ++m) _Pragma("unroll") for (int n = 0; n < 2; ++n) _Pragma("unroll") for (int k = 0; k < 2; ++k) \
;         acc[ai][bj][m][n] = __builtin_amdgcn_mfma_f32_16x16x32_bf16(Bt[n][k], At[m][k], acc[ai][bj][m][n], 0, 0, 0); __builtin_amdgcn_s_setprio(0); } while (0)
; #define PG8_WAIT_V(n) asm volatile("s_waitcnt vmcnt(" #n ")" ::: "memory")
; #define PG8_BAR __builtin_amdgcn_s_barrier()
; template <class Epi, class Sched, int KC, bool ALIGN_EPI = false, bool SP2 = false, bool ATILED = false>
; __device__ __forceinline__ void gemm_phase(LAS unsigned char* lds, const Gemm g, const Sched& S, const Epi& E, int wave_s) {
;     ...
;         for (int t = 0; t < nt; t += 2) {
;             const bool last = (t == nt - 2);
;             const char* a1 = cA + PG8_AOFF(t + 1);
;             const char* a2 = last ? nA : cA + PG8_AOFF(t + 2); const char* b2 = last ? nB : cB + (size_t)(t + 2) * kstep;
;             const char* a3 = a2 + kstep; const char* b3 = b2 + kstep;
;             if (last && has_next) S.a_ready(nxt);
;             if constexpr (SP2) {
;             PG8_LDB(B0, 0, 0); PG8_LDB(B1, 0, 1); PG8_SCHED; PG8_LDA(At, 0, 0); PG8_STAGE(PG8_SA(1, 1), a1 + hstepA, voffA);
;             PG8_WAIT_V(8); PG8_WAIT_L(0); PG8_BAR; PG8_MMA(0, 0, At, B0); PG8_MMA(0, 1, At, B1); PG8_BAR; PG8_SCHED;
;             PG8_LDA(At, 0, 1); PG8_STAGE(PG8_SB(0, 0), b2, voffB); PG8_STAGE(PG8_SB(0, 1), b2 + hstepB, voffB); PG8_STAGE(PG8_SA(0, 0), a2, voffA);
;             PG8_WAIT_V(8); PG8_WAIT_L(0); PG8_BAR; PG8_MMA(1, 0, At, B0); PG8_MMA(1, 1, At, B1); PG8_BAR; PG8_SCHED;
.LBB0_233:
	s_add_i32 s62, 0, 0x10000
	v_add_u32_e32 v139, s62, v163
	ds_read_b128 v[152:155], v139
	ds_read_b128 v[156:159], v139 offset:1024
	ds_read_b128 v[168:171], v139 offset:2048
	ds_read_b128 v[172:175], v139 offset:3072
	s_add_i32 s63, 0, 0x14000
	v_add_u32_e32 v139, s63, v163
	ds_read_b128 v[176:179], v139
	ds_read_b128 v[180:183], v139 offset:1024
	ds_read_b128 v[184:187], v139 offset:2048
	ds_read_b128 v[188:191], v139 offset:3072
	ds_read_b128 v[198:201], v166
	ds_read_b128 v[202:205], v166 offset:1024
	ds_read_b128 v[206:209], v166 offset:2048
	ds_read_b128 v[210:213], v166 offset:3072
	ds_read_b128 v[214:217], v166 offset:4096
	ds_read_b128 v[218:221], v166 offset:5120
	ds_read_b128 v[222:225], v166 offset:6144
	ds_read_b128 v[226:229], v166 offset:7168
	s_add_i32 s30, s58, 0xffc00000
	s_and_b32 s30, s30, 0x3800000
	s_and_b32 s31, s28, 0x100
	s_or_b32 s59, s31, s30
	s_and_b32 s34, s58, 0x7800000
	s_add_u32 s30, s28, 0x100
	s_addc_u32 s31, s29, 0
	s_and_b32 s35, s30, 0x100
	s_or_b32 s34, s34, s35
	s_add_u32 s34, s26, s34
	s_addc_u32 s35, s27, 0
	s_add_u32 s28, s55, s28
	s_addc_u32 s29, s56, s29
	s_cmp_eq_u32 s57, 28
	s_cselect_b32 s35, s19, s35
	s_cselect_b32 s34, s53, s34
	s_cselect_b32 s29, s17, s29
	s_cselect_b32 s28, s54, s28
	s_add_u32 s59, s26, s59
	s_addc_u32 s61, s27, 0
	s_add_u32 s60, s59, 0x10080
	s_addc_u32 s61, s61, 0
	s_add_i32 m0, s44, 0xc000
	s_nop 0
	global_load_lds_dwordx4 v136, s[60:61]
	s_add_i32 m0, s44, 0xe000
	s_nop 0
	global_load_lds_dwordx4 v132, s[60:61]
	s_waitcnt vmcnt(8)
	s_waitcnt lgkmcnt(0)
	s_barrier
	s_waitcnt lgkmcnt(0)
	v_mfma_f32_16x16x32_bf16 v[122:125], v[152:155], v[198:201], v[122:125]
	v_mfma_f32_16x16x32_bf16 v[114:117], v[168:171], v[198:201], v[114:117]
	v_mfma_f32_16x16x32_bf16 v[106:109], v[152:155], v[206:209], v[106:109]
	v_mfma_f32_16x16x32_bf16 v[98:101], v[168:171], v[206:209], v[98:101]
	v_mfma_f32_16x16x32_bf16 v[90:93], v[152:155], v[214:217], v[90:93]
	v_mfma_f32_16x16x32_bf16 v[82:85], v[168:171], v[214:217], v[82:85]
	v_mfma_f32_16x16x32_bf16 v[74:77], v[152:155], v[222:225], v[74:77]
	v_mfma_f32_16x16x32_bf16 v[66:69], v[168:171], v[222:225], v[66:69]
	v_mfma_f32_16x16x32_bf16 v[122:125], v[156:159], v[202:205], v[122:125]
	v_mfma_f32_16x16x32_bf16 v[114:117], v[172:175], v[202:205], v[114:117]
	v_mfma_f32_16x16x32_bf16 v[106:109], v[156:159], v[210:213], v[106:109]
	v_mfma_f32_16x16x32_bf16 v[98:101], v[172:175], v[210:213], v[98:101]
	v_mfma_f32_16x16x32_bf16 v[90:93], v[156:159], v[218:221], v[90:93]
	v_mfma_f32_16x16x32_bf16 v[82:85], v[172:175], v[218:221], v[82:85]
	v_mfma_f32_16x16x32_bf16 v[74:77], v[156:159], v[226:229], v[74:77]
	v_mfma_f32_16x16x32_bf16 v[66:69], v[172:175], v[226:229], v[66:69]
	v_mfma_f32_16x16x32_bf16 v[126:129], v[176:179], v[198:201], v[126:129]
	v_mfma_f32_16x16x32_bf16 v[118:121], v[184:187], v[198:201], v[118:121]
	v_mfma_f32_16x16x32_bf16 v[110:113], v[176:179], v[206:209], v[110:113]
	v_mfma_f32_16x16x32_bf16 v[102:105], v[184:187], v[206:209], v[102:105]
	v_mfma_f32_16x16x32_bf16 v[94:97], v[176:179], v[214:217], v[94:97]
	v_mfma_f32_16x16x32_bf16 v[86:89], v[184:187], v[214:217], v[86:89]
	v_mfma_f32_16x16x32_bf16 v[78:81], v[176:179], v[222:225], v[78:81]
	v_mfma_f32_16x16x32_bf16 v[70:73], v[184:187], v[222:225], v[70:73]
	v_mfma_f32_16x16x32_bf16 v[126:129], v[180:183], v[202:205], v[126:129]
	v_mfma_f32_16x16x32_bf16 v[118:121], v[188:191], v[202:205], v[118:121]
	v_mfma_f32_16x16x32_bf16 v[110:113], v[180:183], v[210:213], v[110:113]
	v_mfma_f32_16x16x32_bf16 v[102:105], v[188:191], v[210:213], v[102:105]
	v_mfma_f32_16x16x32_bf16 v[94:97], v[180:183], v[218:221], v[94:97]
	v_mfma_f32_16x16x32_bf16 v[86:89], v[188:191], v[218:221], v[86:89]
	v_mfma_f32_16x16x32_bf16 v[78:81], v[180:183], v[226:229], v[78:81]
	v_mfma_f32_16x16x32_bf16 v[70:73], v[188:191], v[226:229], v[70:73]
	s_barrier
	ds_read_b128 v[198:201], v166 offset:16384
	ds_read_b128 v[202:205], v166 offset:17408
	ds_read_b128 v[206:209], v166 offset:18432
	ds_read_b128 v[210:213], v166 offset:19456
	ds_read_b128 v[214:217], v166 offset:20480
	ds_read_b128 v[218:221], v166 offset:21504
	ds_read_b128 v[222:225], v166 offset:22528
	ds_read_b128 v[226:229], v166 offset:23552
	s_add_u32 s100, s34, 0x80
	s_addc_u32 s101, s35, 0
	s_add_i32 s59, s62, s38
	s_mov_b32 m0, s59
	s_nop 0
	global_load_lds_dwordx4 v134, s[28:29]
	s_add_i32 m0, s59, 0x2000
	s_add_u32 s60, s28, 0x80000
	s_addc_u32 s61, s29, 0
	s_add_i32 s59, s63, s38
	global_load_lds_dwordx4 v130, s[28:29]
	s_mov_b32 m0, s59
	s_nop 0
	global_load_lds_dwordx4 v134, s[60:61]
	s_add_i32 m0, s59, 0x2000
	s_nop 0
	global_load_lds_dwordx4 v130, s[60:61]
	s_mov_b32 m0, s44
	s_nop 0
	global_load_lds_dwordx4 v136, s[34:35]
	s_mov_b32 m0, s45
	s_nop 0
	global_load_lds_dwordx4 v132, s[34:35]
	s_waitcnt vmcnt(8)
	s_waitcnt lgkmcnt(0)
	s_barrier
; #define PG8_STAGE(bufoff, gbase, voff) do { _Pragma("unroll") for (int _i = 0; _i < 2; ++_i) \
;         __builtin_amdgcn_global_load_lds((const unsigned*)((const char*)(gbase) + (voff)[_i]), (LAS unsigned*)(lds + (bufoff) + ldsw + _i * 8192), 16, 0, 0); } while (0)
; #define PG8_LDA(dst, b, h) do { _Pragma("unroll") for (int m = 0; m < 4; ++m) _Pragma("unroll") for (int k = 0; k < 2; ++k) dst[m][k] = *(const LAS bf16x8*)(lds + PG8_SA(b, h) + aoff + m * 2048 + k * 1024); } while (0)
; #define PG8_LDB(dst, b, h) do { _Pragma("unroll") for (int n = 0; n < 2; ++n) _Pragma("unroll") for (int k = 0; k < 2; ++k) dst[n][k] = *(const LAS bf16x8*)(lds + PG8_SB(b, h) + boff + n * 2048 + k * 1024); } while (0)
; #define PG8_MMA(ai, bj, At, Bt) do { __builtin_amdgcn_s_setprio(1); _Pragma("unroll") for (int m = 0; m < 4; ++m) _Pragma("unroll") for (int n = 0; n < 2; ++n) _Pragma("unroll") for (int k = 0; k < 2; ++k) \
;         acc[ai][bj][m][n] = __builtin_amdgcn_mfma_f32_16x16x32_bf16(Bt[n][k], At[m][k], acc[ai][bj][m][n], 0, 0, 0); __builtin_amdgcn_s_setprio(0); } while (0)
; #define PG8_WAIT_V(n) asm volatile("s_waitcnt vmcnt(" #n ")" ::: "memory")
; #define PG8_WAIT_L(n) asm volatile("s_waitcnt lgkmcnt(" #n ")" ::: "memory")
; #define PG8_BAR __builtin_amdgcn_s_barrier()
; #define PG8_SCHED __builtin_amdgcn_sched_barrier(0)
; template <class Epi, class Sched, int KC, bool ALIGN_EPI = false, bool SP2 = false, bool ATILED = false>
; __device__ __forceinline__ void gemm_phase(LAS unsigned char* lds, const Gemm g, const Sched& S, const Epi& E, int wave_s) {
;     ...
;             PG8_WAIT_V(8); PG8_WAIT_L(0); PG8_BAR; PG8_MMA(1, 0, At, B0); PG8_MMA(1, 1, At, B1); PG8_BAR; PG8_SCHED;
;             PG8_LDB(B0, 1, 0); PG8_LDB(B1, 1, 1); PG8_SCHED; PG8_LDA(At, 1, 0); PG8_STAGE(PG8_SA(0, 1), a2 + hstepA, voffA);
;             PG8_WAIT_V(8); PG8_WAIT_L(0); PG8_BAR; PG8_MMA(0, 0, At, B0); PG8_MMA(0, 1, At, B1); PG8_BAR; PG8_SCHED;
	s_waitcnt lgkmcnt(0)
	v_mfma_f32_16x16x32_bf16 v[58:61], v[152:155], v[198:201], v[58:61]
	v_mfma_f32_16x16x32_bf16 v[50:53], v[168:171], v[198:201], v[50:53]
	v_mfma_f32_16x16x32_bf16 v[42:45], v[152:155], v[206:209], v[42:45]
	v_mfma_f32_16x16x32_bf16 v[34:37], v[168:171], v[206:209], v[34:37]
	v_mfma_f32_16x16x32_bf16 v[26:29], v[152:155], v[214:217], v[26:29]
	v_mfma_f32_16x16x32_bf16 v[18:21], v[168:171], v[214:217], v[18:21]
	v_mfma_f32_16x16x32_bf16 v[10:13], v[152:155], v[222:225], v[10:13]
	v_mfma_f32_16x16x32_bf16 v[6:9], v[168:171], v[222:225], v[6:9]
	v_mfma_f32_16x16x32_bf16 v[58:61], v[156:159], v[202:205], v[58:61]
	v_mfma_f32_16x16x32_bf16 v[50:53], v[172:175], v[202:205], v[50:53]
	v_mfma_f32_16x16x32_bf16 v[42:45], v[156:159], v[210:213], v[42:45]
	v_mfma_f32_16x16x32_bf16 v[34:37], v[172:175], v[210:213], v[34:37]
	v_mfma_f32_16x16x32_bf16 v[26:29], v[156:159], v[218:221], v[26:29]
	v_mfma_f32_16x16x32_bf16 v[18:21], v[172:175], v[218:221], v[18:21]
	v_mfma_f32_16x16x32_bf16 v[10:13], v[156:159], v[226:229], v[10:13]
	v_mfma_f32_16x16x32_bf16 v[6:9], v[172:175], v[226:229], v[6:9]
	v_mfma_f32_16x16x32_bf16 v[62:65], v[176:179], v[198:201], v[62:65]
	v_mfma_f32_16x16x32_bf16 v[54:57], v[184:187], v[198:201], v[54:57]
	v_mfma_f32_16x16x32_bf16 v[46:49], v[176:179], v[206:209], v[46:49]
	v_mfma_f32_16x16x32_bf16 v[38:41], v[184:187], v[206:209], v[38:41]
	v_mfma_f32_16x16x32_bf16 v[30:33], v[176:179], v[214:217], v[30:33]
	v_mfma_f32_16x16x32_bf16 v[22:25], v[184:187], v[214:217], v[22:25]
	v_mfma_f32_16x16x32_bf16 v[14:17], v[176:179], v[222:225], v[14:17]
	v_mfma_f32_16x16x32_bf16 v[2:5], v[184:187], v[222:225], v[2:5]
	v_mfma_f32_16x16x32_bf16 v[62:65], v[180:183], v[202:205], v[62:65]
	v_mfma_f32_16x16x32_bf16 v[54:57], v[188:191], v[202:205], v[54:57]
	v_mfma_f32_16x16x32_bf16 v[46:49], v[180:183], v[210:213], v[46:49]
	v_mfma_f32_16x16x32_bf16 v[38:41], v[188:191], v[210:213], v[38:41]
	v_mfma_f32_16x16x32_bf16 v[30:33], v[180:183], v[218:221], v[30:33]
	v_mfma_f32_16x16x32_bf16 v[22:25], v[188:191], v[218:221], v[22:25]
	v_mfma_f32_16x16x32_bf16 v[14:17], v[180:183], v[226:229], v[14:17]
	v_mfma_f32_16x16x32_bf16 v[2:5], v[188:191], v[226:229], v[2:5]
	s_barrier
	s_add_i32 s59, 0, 0x18000
	v_add_u32_e32 v139, s59, v163
	ds_read_b128 v[152:155], v139
	ds_read_b128 v[156:159], v139 offset:1024
	ds_read_b128 v[168:171], v139 offset:2048
	ds_read_b128 v[172:175], v139 offset:3072
	s_add_i32 s60, 0, 0x1c000
	v_add_u32_e32 v139, s60, v163
	ds_read_b128 v[176:179], v139
	ds_read_b128 v[180:183], v139 offset:1024
	ds_read_b128 v[184:187], v139 offset:2048
	ds_read_b128 v[188:191], v139 offset:3072
	ds_read_b128 v[198:201], v166 offset:32768
	ds_read_b128 v[202:205], v166 offset:33792
	ds_read_b128 v[206:209], v166 offset:34816
	ds_read_b128 v[210:213], v166 offset:35840
	ds_read_b128 v[214:217], v166 offset:36864
	ds_read_b128 v[218:221], v166 offset:37888
	ds_read_b128 v[222:225], v166 offset:38912
	ds_read_b128 v[226:229], v166 offset:39936
	s_add_u32 s34, s34, 0x10000
	s_addc_u32 s35, s35, 0
	s_mov_b32 m0, s46
	s_nop 0
	global_load_lds_dwordx4 v136, s[34:35]
	s_mov_b32 m0, s47
	s_nop 0
	global_load_lds_dwordx4 v132, s[34:35]
	s_waitcnt vmcnt(8)
	s_waitcnt lgkmcnt(0)
	s_barrier
	s_waitcnt lgkmcnt(0)
	v_mfma_f32_16x16x32_bf16 v[122:125], v[152:155], v[198:201], v[122:125]
	v_mfma_f32_16x16x32_bf16 v[114:117], v[168:171], v[198:201], v[114:117]
	v_mfma_f32_16x16x32_bf16 v[106:109], v[152:155], v[206:209], v[106:109]
	v_mfma_f32_16x16x32_bf16 v[98:101], v[168:171], v[206:209], v[98:101]
	v_mfma_f32_16x16x32_bf16 v[90:93], v[152:155], v[214:217], v[90:93]
	v_mfma_f32_16x16x32_bf16 v[82:85], v[168:171], v[214:217], v[82:85]
	v_mfma_f32_16x16x32_bf16 v[74:77], v[152:155], v[222:225], v[74:77]
	v_mfma_f32_16x16x32_bf16 v[66:69], v[168:171], v[222:225], v[66:69]
	v_mfma_f32_16x16x32_bf16 v[122:125], v[156:159], v[202:205], v[122:125]
	v_mfma_f32_16x16x32_bf16 v[114:117], v[172:175], v[202:205], v[114:117]
	v_mfma_f32_16x16x32_bf16 v[106:109], v[156:159], v[210:213], v[106:109]
	v_mfma_f32_16x16x32_bf16 v[98:101], v[172:175], v[210:213], v[98:101]
	v_mfma_f32_16x16x32_bf16 v[90:93], v[156:159], v[218:221], v[90:93]
	v_mfma_f32_16x16x32_bf16 v[82:85], v[172:175], v[218:221], v[82:85]
	v_mfma_f32_16x16x32_bf16 v[74:77], v[156:159], v[226:229], v[74:77]
	v_mfma_f32_16x16x32_bf16 v[66:69], v[172:175], v[226:229], v[66:69]
	v_mfma_f32_16x16x32_bf16 v[126:129], v[176:179], v[198:201], v[126:129]
	v_mfma_f32_16x16x32_bf16 v[118:121], v[184:187], v[198:201], v[118:121]
	v_mfma_f32_16x16x32_bf16 v[110:113], v[176:179], v[206:209], v[110:113]
	v_mfma_f32_16x16x32_bf16 v[102:105], v[184:187], v[206:209], v[102:105]
	v_mfma_f32_16x16x32_bf16 v[94:97], v[176:179], v[214:217], v[94:97]
	v_mfma_f32_16x16x32_bf16 v[86:89], v[184:187], v[214:217], v[86:89]
	v_mfma_f32_16x16x32_bf16 v[78:81], v[176:179], v[222:225], v[78:81]
	v_mfma_f32_16x16x32_bf16 v[70:73], v[184:187], v[222:225], v[70:73]
	v_mfma_f32_16x16x32_bf16 v[126:129], v[180:183], v[202:205], v[126:129]
	v_mfma_f32_16x16x32_bf16 v[118:121], v[188:191], v[202:205], v[118:121]
	v_mfma_f32_16x16x32_bf16 v[110:113], v[180:183], v[210:213], v[110:113]
	v_mfma_f32_16x16x32_bf16 v[102:105], v[188:191], v[210:213], v[102:105]
	v_mfma_f32_16x16x32_bf16 v[94:97], v[180:183], v[218:221], v[94:97]
	v_mfma_f32_16x16x32_bf16 v[86:89], v[188:191], v[218:221], v[86:89]
	v_mfma_f32_16x16x32_bf16 v[78:81], v[180:183], v[226:229], v[78:81]
	v_mfma_f32_16x16x32_bf16 v[70:73], v[188:191], v[226:229], v[70:73]
	s_barrier
; #define PG8_STAGE(bufoff, gbase, voff) do { _Pragma("unroll") for (int _i = 0; _i < 2; ++_i) \
;         __builtin_amdgcn_global_load_lds((const unsigned*)((const char*)(gbase) + (voff)[_i]), (LAS unsigned*)(lds + (bufoff) + ldsw + _i * 8192), 16, 0, 0); } while (0)
; #define PG8_LDA(dst, b, h) do { _Pragma("unroll") for (int m = 0; m < 4; ++m) _Pragma("unroll") for (int k = 0; k < 2; ++k) dst[m][k] = *(const LAS bf16x8*)(lds + PG8_SA(b, h) + aoff + m * 2048 + k * 1024); } while (0)
; #define PG8_MMA(ai, bj, At, Bt) do { __builtin_amdgcn_s_setprio(1); _Pragma("unroll") for (int m = 0; m < 4; ++m) _Pragma("unroll") for (int n = 0; n < 2; ++n) _Pragma("unroll") for (int k = 0; k < 2; ++k) \
;         acc[ai][bj][m][n] = __builtin_amdgcn_mfma_f32_16x16x32_bf16(Bt[n][k], At[m][k], acc[ai][bj][m][n], 0, 0, 0); __builtin_amdgcn_s_setprio(0); } while (0)
; #define PG8_WAIT_V(n) asm volatile("s_waitcnt vmcnt(" #n ")" ::: "memory")
; #define PG8_WAIT_L(n) asm volatile("s_waitcnt lgkmcnt(" #n ")" ::: "memory")
; #define PG8_BAR __builtin_amdgcn_s_barrier()
; #define PG8_SCHED __builtin_amdgcn_sched_barrier(0)
; template <class Epi, class Sched, int KC, bool ALIGN_EPI = false, bool SP2 = false, bool ATILED = false>
; __device__ __forceinline__ void gemm_phase(LAS unsigned char* lds, const Gemm g, const Sched& S, const Epi& E, int wave_s) {
;     ...
;             PG8_LDA(At, 1, 1); PG8_STAGE(PG8_SB(1, 0), b3, voffB); PG8_STAGE(PG8_SB(1, 1), b3 + hstepB, voffB); PG8_STAGE(PG8_SA(1, 0), a3, voffA);
;             PG8_WAIT_V(8); PG8_WAIT_L(0); PG8_BAR; PG8_MMA(1, 0, At, B0); PG8_MMA(1, 1, At, B1); PG8_BAR; PG8_SCHED;
;     ...
;         if constexpr (ALIGN_EPI) { if (wr == 0) PG8_BAR; }
	ds_read_b128 v[198:201], v166 offset:49152
	ds_read_b128 v[202:205], v166 offset:50176
	ds_read_b128 v[206:209], v166 offset:51200
	ds_read_b128 v[210:213], v166 offset:52224
	ds_read_b128 v[214:217], v166 offset:53248
	ds_read_b128 v[218:221], v166 offset:54272
	ds_read_b128 v[222:225], v166 offset:55296
	ds_read_b128 v[226:229], v166 offset:56320
	s_add_u32 s98, s28, 0x80
	s_addc_u32 s99, s29, 0
	s_add_i32 s34, s59, s38
	s_mov_b32 m0, s34
	s_nop 0
	global_load_lds_dwordx4 v134, s[98:99]
	s_add_i32 m0, s34, 0x2000
	s_add_u32 s28, s28, 0x80080
	s_addc_u32 s29, s29, 0
	s_add_i32 s34, s60, s38
	global_load_lds_dwordx4 v130, s[98:99]
	s_mov_b32 m0, s34
	s_nop 0
	global_load_lds_dwordx4 v134, s[28:29]
	s_add_i32 m0, s34, 0x2000
	s_nop 0
	global_load_lds_dwordx4 v130, s[28:29]
	s_mov_b32 m0, s48
	s_nop 0
	global_load_lds_dwordx4 v136, s[100:101]
	s_mov_b32 m0, s49
	s_nop 0
	global_load_lds_dwordx4 v132, s[100:101]
	s_waitcnt vmcnt(8)
	s_waitcnt lgkmcnt(0)
	s_barrier
	s_waitcnt lgkmcnt(0)
	v_mfma_f32_16x16x32_bf16 v[58:61], v[152:155], v[198:201], v[58:61]
	v_mfma_f32_16x16x32_bf16 v[50:53], v[168:171], v[198:201], v[50:53]
	v_mfma_f32_16x16x32_bf16 v[42:45], v[152:155], v[206:209], v[42:45]
	v_mfma_f32_16x16x32_bf16 v[34:37], v[168:171], v[206:209], v[34:37]
	v_mfma_f32_16x16x32_bf16 v[26:29], v[152:155], v[214:217], v[26:29]
	v_mfma_f32_16x16x32_bf16 v[18:21], v[168:171], v[214:217], v[18:21]
	v_mfma_f32_16x16x32_bf16 v[10:13], v[152:155], v[222:225], v[10:13]
	v_mfma_f32_16x16x32_bf16 v[6:9], v[168:171], v[222:225], v[6:9]
	v_mfma_f32_16x16x32_bf16 v[58:61], v[156:159], v[202:205], v[58:61]
	v_mfma_f32_16x16x32_bf16 v[50:53], v[172:175], v[202:205], v[50:53]
	v_mfma_f32_16x16x32_bf16 v[42:45], v[156:159], v[210:213], v[42:45]
	v_mfma_f32_16x16x32_bf16 v[34:37], v[172:175], v[210:213], v[34:37]
	v_mfma_f32_16x16x32_bf16 v[26:29], v[156:159], v[218:221], v[26:29]
	v_mfma_f32_16x16x32_bf16 v[18:21], v[172:175], v[218:221], v[18:21]
	v_mfma_f32_16x16x32_bf16 v[10:13], v[156:159], v[226:229], v[10:13]
	v_mfma_f32_16x16x32_bf16 v[6:9], v[172:175], v[226:229], v[6:9]
	v_mfma_f32_16x16x32_bf16 v[62:65], v[176:179], v[198:201], v[62:65]
	v_mfma_f32_16x16x32_bf16 v[54:57], v[184:187], v[198:201], v[54:57]
	v_mfma_f32_16x16x32_bf16 v[46:49], v[176:179], v[206:209], v[46:49]
	v_mfma_f32_16x16x32_bf16 v[38:41], v[184:187], v[206:209], v[38:41]
	v_mfma_f32_16x16x32_bf16 v[30:33], v[176:179], v[214:217], v[30:33]
	v_mfma_f32_16x16x32_bf16 v[22:25], v[184:187], v[214:217], v[22:25]
	v_mfma_f32_16x16x32_bf16 v[14:17], v[176:179], v[222:225], v[14:17]
	v_mfma_f32_16x16x32_bf16 v[2:5], v[184:187], v[222:225], v[2:5]
	v_mfma_f32_16x16x32_bf16 v[62:65], v[180:183], v[202:205], v[62:65]
	v_mfma_f32_16x16x32_bf16 v[54:57], v[188:191], v[202:205], v[54:57]
	v_mfma_f32_16x16x32_bf16 v[46:49], v[180:183], v[210:213], v[46:49]
	v_mfma_f32_16x16x32_bf16 v[38:41], v[188:191], v[210:213], v[38:41]
	v_mfma_f32_16x16x32_bf16 v[30:33], v[180:183], v[218:221], v[30:33]
	v_mfma_f32_16x16x32_bf16 v[22:25], v[188:191], v[218:221], v[22:25]
	v_mfma_f32_16x16x32_bf16 v[14:17], v[180:183], v[226:229], v[14:17]
	v_mfma_f32_16x16x32_bf16 v[2:5], v[188:191], v[226:229], v[2:5]
	s_barrier
	s_add_i32 s57, s57, 2
	s_add_i32 s58, s58, 0x400000
	s_cmp_gt_u32 s57, 29
	s_mov_b64 s[28:29], s[30:31]
	s_cbranch_scc0 .LBB0_233
	s_and_b64 vcc, exec, s[14:15]
	s_cbranch_vccz .LBB0_236
	s_barrier

; #define PG8_STAGE(bufoff, gbase, voff) do { _Pragma("unroll") for (int _i = 0; _i < 2; ++_i) \
;         __builtin_amdgcn_global_load_lds((const unsigned*)((const char*)(gbase) + (voff)[_i]), (LAS unsigned*)(lds + (bufoff) + ldsw + _i * 8192), 16, 0, 0); } while (0)
; #define PG8_LDA(dst, b, h) do { _Pragma("unroll") for (int m = 0; m < 4; ++m) _Pragma("unroll") for (int k = 0; k < 2; ++k) dst[m][k] = *(const LAS bf16x8*)(lds + PG8_SA(b, h) + aoff + m * 2048 + k * 1024); } while (0)
; #define PG8_LDB(dst, b, h) do { _Pragma("unroll") for (int n = 0; n < 2; ++n) _Pragma("unroll") for (int k = 0; k < 2; ++k) dst[n][k] = *(const LAS bf16x8*)(lds + PG8_SB(b, h) + boff + n * 2048 + k * 1024); } while (0)
; #define PG8_MMA(ai, bj, At, Bt) do { __builtin_amdgcn_s_setprio(1); _Pragma("unroll") for (int m = 0; m < 4; ++m) _Pragma("unroll") for (int n = 0; n < 2; ++n) _Pragma("unroll") for (int k = 0; k < 2; ++k) \
;         acc[ai][bj][m][n] = __builtin_amdgcn_mfma_f32_16x16x32_bf16(Bt[n][k], At[m][k], acc[ai][bj][m][n], 0, 0, 0); __builtin_amdgcn_s_setprio(0); } while (0)
; #define PG8_BAR __builtin_amdgcn_s_barrier()
; template <class Epi, class Sched, int KC, bool ALIGN_EPI = false, bool SP2 = false, bool ATILED = false>
; __device__ __forceinline__ void gemm_phase(LAS unsigned char* lds, const Gemm g, const Sched& S, const Epi& E, int wave_s) {
;     ...
;         for (int t = 0; t < nt; t += 2) {
;             const bool last = (t == nt - 2);
;             const char* a1 = cA + PG8_AOFF(t + 1);
;             const char* a2 = last ? nA : cA + PG8_AOFF(t + 2); const char* b2 = last ? nB : cB + (size_t)(t + 2) * kstep;
;             const char* a3 = a2 + kstep; const char* b3 = b2 + kstep;
;             if (last && has_next) S.a_ready(nxt);
;             if constexpr (SP2) {
;             PG8_LDB(B0, 0, 0); PG8_LDB(B1, 0, 1); PG8_SCHED; PG8_LDA(At, 0, 0); PG8_STAGE(PG8_SA(1, 1), a1 + hstepA, voffA);
;             PG8_WAIT_V(8); PG8_WAIT_L(0); PG8_BAR; PG8_MMA(0, 0, At, B0); PG8_MMA(0, 1, At, B1); PG8_BAR; PG8_SCHED;
;     ...
; #pragma unroll
;         for (int a = 0; a < 2; ++a)
; #pragma unroll
;             for (int b = 0; b < 2; ++b)
; #pragma unroll
;                 for (int m = 0; m < 4; ++m)
; #pragma unroll
;                     for (int n = 0; n < 2; ++n) acc[a][b][m][n] = (f32x4){0.f, 0.f, 0.f, 0.f};
;         cur = nxt; cA = nA; cB = nB; ++ui;
.LBB0_317:
	s_add_u32 s50, s22, 0x100
	v_mov_b32_e32 v2, 0
	s_addc_u32 s51, s23, 0
	s_mov_b32 s52, -2
	v_mov_b32_e32 v3, v2
	v_mov_b32_e32 v4, v2
	v_mov_b32_e32 v5, v2
	v_mov_b32_e32 v6, v2
	v_mov_b32_e32 v7, v2
	v_mov_b32_e32 v8, v2
	v_mov_b32_e32 v9, v2
	v_mov_b32_e32 v18, v2
	v_mov_b32_e32 v19, v2
	v_mov_b32_e32 v20, v2
	v_mov_b32_e32 v21, v2
	v_mov_b32_e32 v22, v2
	v_mov_b32_e32 v23, v2
	v_mov_b32_e32 v24, v2
	v_mov_b32_e32 v25, v2
	v_mov_b32_e32 v34, v2
	v_mov_b32_e32 v35, v2
	v_mov_b32_e32 v36, v2
	v_mov_b32_e32 v37, v2
	v_mov_b32_e32 v38, v2
	v_mov_b32_e32 v39, v2
	v_mov_b32_e32 v40, v2
	v_mov_b32_e32 v41, v2
	v_mov_b32_e32 v50, v2
	v_mov_b32_e32 v51, v2
	v_mov_b32_e32 v52, v2
	v_mov_b32_e32 v53, v2
	v_mov_b32_e32 v54, v2
	v_mov_b32_e32 v55, v2
	v_mov_b32_e32 v56, v2
	v_mov_b32_e32 v57, v2
	v_mov_b32_e32 v10, v2
	v_mov_b32_e32 v11, v2
	v_mov_b32_e32 v12, v2
	v_mov_b32_e32 v13, v2
	v_mov_b32_e32 v14, v2
	v_mov_b32_e32 v15, v2
	v_mov_b32_e32 v16, v2
	v_mov_b32_e32 v17, v2
	v_mov_b32_e32 v26, v2
	v_mov_b32_e32 v27, v2
	v_mov_b32_e32 v28, v2
	v_mov_b32_e32 v29, v2
	v_mov_b32_e32 v30, v2
	v_mov_b32_e32 v31, v2
	v_mov_b32_e32 v32, v2
	v_mov_b32_e32 v33, v2
	v_mov_b32_e32 v42, v2
	v_mov_b32_e32 v43, v2
	v_mov_b32_e32 v44, v2
	v_mov_b32_e32 v45, v2
	v_mov_b32_e32 v46, v2
	v_mov_b32_e32 v47, v2
	v_mov_b32_e32 v48, v2
	v_mov_b32_e32 v49, v2
	v_mov_b32_e32 v58, v2
	v_mov_b32_e32 v59, v2
	v_mov_b32_e32 v60, v2
	v_mov_b32_e32 v61, v2
	v_mov_b32_e32 v62, v2
	v_mov_b32_e32 v63, v2
	v_mov_b32_e32 v64, v2
	v_mov_b32_e32 v65, v2
	v_mov_b32_e32 v66, v2
	v_mov_b32_e32 v67, v2
	v_mov_b32_e32 v68, v2
	v_mov_b32_e32 v69, v2
	v_mov_b32_e32 v70, v2
	v_mov_b32_e32 v71, v2
	v_mov_b32_e32 v72, v2
	v_mov_b32_e32 v73, v2
	v_mov_b32_e32 v86, v2
	v_mov_b32_e32 v87, v2
	v_mov_b32_e32 v88, v2
	v_mov_b32_e32 v89, v2
	v_mov_b32_e32 v90, v2
	v_mov_b32_e32 v91, v2
	v_mov_b32_e32 v92, v2
	v_mov_b32_e32 v93, v2
	v_mov_b32_e32 v110, v2
	v_mov_b32_e32 v111, v2
	v_mov_b32_e32 v112, v2
	v_mov_b32_e32 v113, v2
	v_mov_b32_e32 v118, v2
	v_mov_b32_e32 v119, v2
	v_mov_b32_e32 v120, v2
	v_mov_b32_e32 v121, v2
	v_mov_b32_e32 v138, v2
	v_mov_b32_e32 v139, v2
	v_mov_b32_e32 v140, v2
	v_mov_b32_e32 v141, v2
	v_mov_b32_e32 v142, v2
	v_mov_b32_e32 v143, v2
	v_mov_b32_e32 v144, v2
	v_mov_b32_e32 v145, v2
	v_mov_b32_e32 v74, v2
	v_mov_b32_e32 v75, v2
	v_mov_b32_e32 v76, v2
	v_mov_b32_e32 v77, v2
	v_mov_b32_e32 v78, v2
	v_mov_b32_e32 v79, v2
	v_mov_b32_e32 v80, v2
	v_mov_b32_e32 v81, v2
	v_mov_b32_e32 v98, v2
	v_mov_b32_e32 v99, v2
	v_mov_b32_e32 v100, v2
	v_mov_b32_e32 v101, v2
	v_mov_b32_e32 v102, v2
	v_mov_b32_e32 v103, v2
	v_mov_b32_e32 v104, v2
	v_mov_b32_e32 v105, v2
	v_mov_b32_e32 v122, v2
	v_mov_b32_e32 v123, v2
	v_mov_b32_e32 v124, v2
	v_mov_b32_e32 v125, v2
	v_mov_b32_e32 v126, v2
	v_mov_b32_e32 v127, v2
	v_mov_b32_e32 v128, v2
	v_mov_b32_e32 v129, v2
	v_mov_b32_e32 v158, v2
	v_mov_b32_e32 v159, v2
	v_mov_b32_e32 v160, v2
	v_mov_b32_e32 v161, v2
	v_mov_b32_e32 v162, v2
	v_mov_b32_e32 v163, v2
	v_mov_b32_e32 v164, v2
	v_mov_b32_e32 v165, v2
	s_add_i32 s53, 0, 0x10000
	v_add_u32_e32 v114, s53, v249
	s_add_i32 s54, 0, 0x14000
	v_add_u32_e32 v150, s54, v249
	ds_read_b128 v[82:85], v114
	ds_read_b128 v[94:97], v114 offset:1024
	ds_read_b128 v[106:109], v114 offset:2048
	ds_read_b128 v[114:117], v114 offset:3072
	ds_read_b128 v[130:133], v150
	ds_read_b128 v[134:137], v150 offset:1024
	ds_read_b128 v[146:149], v150 offset:2048
	ds_read_b128 v[150:153], v150 offset:3072
	ds_read_b128 v[154:157], v251
	ds_read_b128 v[166:169], v251 offset:1024
	ds_read_b128 v[170:173], v251 offset:2048
	ds_read_b128 v[174:177], v251 offset:3072
	ds_read_b128 v[178:181], v251 offset:4096
	ds_read_b128 v[182:185], v251 offset:5120
	ds_read_b128 v[186:189], v251 offset:6144
	ds_read_b128 v[194:197], v251 offset:7168
	s_add_u32 s8, s20, 0x100
	s_addc_u32 s9, s21, 0
	s_cmpk_eq_i32 s52, 0x54
	s_cselect_b32 s25, s17, s9
	s_cselect_b32 s24, s16, s8
	s_cselect_b32 s23, s11, s51
	s_cselect_b32 s22, s10, s50
	s_add_i32 m0, s36, 0xc000
	s_nop 0
	global_load_lds_dwordx4 v204, s[20:21]
	s_add_i32 m0, s36, 0xe000
	s_nop 0
	global_load_lds_dwordx4 v202, s[20:21]
	s_waitcnt vmcnt(32)
	s_waitcnt lgkmcnt(0)
	s_barrier
	s_waitcnt lgkmcnt(0)
	v_mfma_f32_16x16x32_bf16 v[162:165], v[82:85], v[154:157], v[162:165]
	v_mfma_f32_16x16x32_bf16 v[158:161], v[106:109], v[154:157], v[158:161]
	v_mfma_f32_16x16x32_bf16 v[126:129], v[82:85], v[170:173], v[126:129]
	v_mfma_f32_16x16x32_bf16 v[122:125], v[106:109], v[170:173], v[122:125]
	v_mfma_f32_16x16x32_bf16 v[102:105], v[82:85], v[178:181], v[102:105]
	v_mfma_f32_16x16x32_bf16 v[98:101], v[106:109], v[178:181], v[98:101]
	v_mfma_f32_16x16x32_bf16 v[78:81], v[82:85], v[186:189], v[78:81]
	v_mfma_f32_16x16x32_bf16 v[74:77], v[106:109], v[186:189], v[74:77]
	v_mfma_f32_16x16x32_bf16 v[162:165], v[94:97], v[166:169], v[162:165]
	v_mfma_f32_16x16x32_bf16 v[158:161], v[114:117], v[166:169], v[158:161]
	v_mfma_f32_16x16x32_bf16 v[126:129], v[94:97], v[174:177], v[126:129]
	v_mfma_f32_16x16x32_bf16 v[122:125], v[114:117], v[174:177], v[122:125]
	v_mfma_f32_16x16x32_bf16 v[102:105], v[94:97], v[182:185], v[102:105]
	v_mfma_f32_16x16x32_bf16 v[98:101], v[114:117], v[182:185], v[98:101]
	v_mfma_f32_16x16x32_bf16 v[78:81], v[94:97], v[194:197], v[78:81]
	v_mfma_f32_16x16x32_bf16 v[74:77], v[114:117], v[194:197], v[74:77]
	v_mfma_f32_16x16x32_bf16 v[142:145], v[130:133], v[154:157], v[142:145]
	v_mfma_f32_16x16x32_bf16 v[138:141], v[146:149], v[154:157], v[138:141]
	v_mfma_f32_16x16x32_bf16 v[118:121], v[130:133], v[170:173], v[118:121]
	v_mfma_f32_16x16x32_bf16 v[110:113], v[146:149], v[170:173], v[110:113]
	v_mfma_f32_16x16x32_bf16 v[90:93], v[130:133], v[178:181], v[90:93]
	v_mfma_f32_16x16x32_bf16 v[86:89], v[146:149], v[178:181], v[86:89]
	v_mfma_f32_16x16x32_bf16 v[70:73], v[130:133], v[186:189], v[70:73]
	v_mfma_f32_16x16x32_bf16 v[66:69], v[146:149], v[186:189], v[66:69]
	v_mfma_f32_16x16x32_bf16 v[142:145], v[134:137], v[166:169], v[142:145]
	v_mfma_f32_16x16x32_bf16 v[138:141], v[150:153], v[166:169], v[138:141]
	v_mfma_f32_16x16x32_bf16 v[118:121], v[134:137], v[174:177], v[118:121]
	v_mfma_f32_16x16x32_bf16 v[110:113], v[150:153], v[174:177], v[110:113]
	v_mfma_f32_16x16x32_bf16 v[90:93], v[134:137], v[182:185], v[90:93]
	v_mfma_f32_16x16x32_bf16 v[86:89], v[150:153], v[182:185], v[86:89]
	v_mfma_f32_16x16x32_bf16 v[70:73], v[134:137], v[194:197], v[70:73]
	v_mfma_f32_16x16x32_bf16 v[66:69], v[150:153], v[194:197], v[66:69]
	s_barrier
; #define PG8_STAGE(bufoff, gbase, voff) do { _Pragma("unroll") for (int _i = 0; _i < 2; ++_i) \
;         __builtin_amdgcn_global_load_lds((const unsigned*)((const char*)(gbase) + (voff)[_i]), (LAS unsigned*)(lds + (bufoff) + ldsw + _i * 8192), 16, 0, 0); } while (0)
; #define PG8_LDA(dst, b, h) do { _Pragma("unroll") for (int m = 0; m < 4; ++m) _Pragma("unroll") for (int k = 0; k < 2; ++k) dst[m][k] = *(const LAS bf16x8*)(lds + PG8_SA(b, h) + aoff + m * 2048 + k * 1024); } while (0)
; #define PG8_LDB(dst, b, h) do { _Pragma("unroll") for (int n = 0; n < 2; ++n) _Pragma("unroll") for (int k = 0; k < 2; ++k) dst[n][k] = *(const LAS bf16x8*)(lds + PG8_SB(b, h) + boff + n * 2048 + k * 1024); } while (0)
; #define PG8_MMA(ai, bj, At, Bt) do { __builtin_amdgcn_s_setprio(1); _Pragma("unroll") for (int m = 0; m < 4; ++m) _Pragma("unroll") for (int n = 0; n < 2; ++n) _Pragma("unroll") for (int k = 0; k < 2; ++k) \
;         acc[ai][bj][m][n] = __builtin_amdgcn_mfma_f32_16x16x32_bf16(Bt[n][k], At[m][k], acc[ai][bj][m][n], 0, 0, 0); __builtin_amdgcn_s_setprio(0); } while (0)
; #define PG8_WAIT_V(n) asm volatile("s_waitcnt vmcnt(" #n ")" ::: "memory")
; #define PG8_WAIT_L(n) asm volatile("s_waitcnt lgkmcnt(" #n ")" ::: "memory")
; #define PG8_BAR __builtin_amdgcn_s_barrier()
; #define PG8_SCHED __builtin_amdgcn_sched_barrier(0)
; template <class Epi, class Sched, int KC, bool ALIGN_EPI = false, bool SP2 = false, bool ATILED = false>
; __device__ __forceinline__ void gemm_phase(LAS unsigned char* lds, const Gemm g, const Sched& S, const Epi& E, int wave_s) {
;     ...
;             PG8_LDA(At, 0, 1); PG8_STAGE(PG8_SB(0, 0), b2, voffB); PG8_STAGE(PG8_SB(0, 1), b2 + hstepB, voffB); PG8_STAGE(PG8_SA(0, 0), a2, voffA);
;             PG8_WAIT_V(8); PG8_WAIT_L(0); PG8_BAR; PG8_MMA(1, 0, At, B0); PG8_MMA(1, 1, At, B1); PG8_BAR; PG8_SCHED;
;             PG8_LDB(B0, 1, 0); PG8_LDB(B1, 1, 1); PG8_SCHED; PG8_LDA(At, 1, 0); PG8_STAGE(PG8_SA(0, 1), a2 + hstepA, voffA);
;             PG8_WAIT_V(8); PG8_WAIT_L(0); PG8_BAR; PG8_MMA(0, 0, At, B0); PG8_MMA(0, 1, At, B1); PG8_BAR; PG8_SCHED;
	ds_read_b128 v[154:157], v251 offset:16384
	ds_read_b128 v[166:169], v251 offset:17408
	ds_read_b128 v[170:173], v251 offset:18432
	ds_read_b128 v[174:177], v251 offset:19456
	ds_read_b128 v[178:181], v251 offset:20480
	ds_read_b128 v[182:185], v251 offset:21504
	ds_read_b128 v[186:189], v251 offset:22528
	ds_read_b128 v[194:197], v251 offset:23552
	s_add_i32 s20, s53, s35
	s_mov_b32 m0, s20
	s_nop 0
	global_load_lds_dwordx4 v0, s[22:23]
	s_add_i32 m0, s20, 0x2000
	s_add_u32 s20, s22, 0x58000
	s_addc_u32 s21, s23, 0
	s_add_i32 s53, s54, s35
	global_load_lds_dwordx4 v198, s[22:23]
	s_mov_b32 m0, s53
	s_nop 0
	global_load_lds_dwordx4 v0, s[20:21]
	s_add_i32 m0, s53, 0x2000
	s_nop 0
	global_load_lds_dwordx4 v198, s[20:21]
	s_mov_b32 m0, s36
	s_nop 0
	global_load_lds_dwordx4 v190, s[24:25]
	s_mov_b32 m0, s37
	s_nop 0
	global_load_lds_dwordx4 v192, s[24:25]
	s_waitcnt vmcnt(32)
	s_waitcnt lgkmcnt(0)
	s_barrier
	s_waitcnt lgkmcnt(0)
	v_mfma_f32_16x16x32_bf16 v[62:65], v[82:85], v[154:157], v[62:65]
	v_mfma_f32_16x16x32_bf16 v[58:61], v[106:109], v[154:157], v[58:61]
	v_mfma_f32_16x16x32_bf16 v[46:49], v[82:85], v[170:173], v[46:49]
	v_mfma_f32_16x16x32_bf16 v[42:45], v[106:109], v[170:173], v[42:45]
	v_mfma_f32_16x16x32_bf16 v[30:33], v[82:85], v[178:181], v[30:33]
	v_mfma_f32_16x16x32_bf16 v[26:29], v[106:109], v[178:181], v[26:29]
	v_mfma_f32_16x16x32_bf16 v[14:17], v[82:85], v[186:189], v[14:17]
	v_mfma_f32_16x16x32_bf16 v[10:13], v[106:109], v[186:189], v[10:13]
	v_mfma_f32_16x16x32_bf16 v[62:65], v[94:97], v[166:169], v[62:65]
	v_mfma_f32_16x16x32_bf16 v[58:61], v[114:117], v[166:169], v[58:61]
	v_mfma_f32_16x16x32_bf16 v[46:49], v[94:97], v[174:177], v[46:49]
	v_mfma_f32_16x16x32_bf16 v[42:45], v[114:117], v[174:177], v[42:45]
	v_mfma_f32_16x16x32_bf16 v[30:33], v[94:97], v[182:185], v[30:33]
	v_mfma_f32_16x16x32_bf16 v[26:29], v[114:117], v[182:185], v[26:29]
	v_mfma_f32_16x16x32_bf16 v[14:17], v[94:97], v[194:197], v[14:17]
	v_mfma_f32_16x16x32_bf16 v[10:13], v[114:117], v[194:197], v[10:13]
	v_mfma_f32_16x16x32_bf16 v[54:57], v[130:133], v[154:157], v[54:57]
	v_mfma_f32_16x16x32_bf16 v[50:53], v[146:149], v[154:157], v[50:53]
	v_mfma_f32_16x16x32_bf16 v[38:41], v[130:133], v[170:173], v[38:41]
	v_mfma_f32_16x16x32_bf16 v[34:37], v[146:149], v[170:173], v[34:37]
	v_mfma_f32_16x16x32_bf16 v[22:25], v[130:133], v[178:181], v[22:25]
	v_mfma_f32_16x16x32_bf16 v[18:21], v[146:149], v[178:181], v[18:21]
	v_mfma_f32_16x16x32_bf16 v[6:9], v[130:133], v[186:189], v[6:9]
	v_mfma_f32_16x16x32_bf16 v[2:5], v[146:149], v[186:189], v[2:5]
	v_mfma_f32_16x16x32_bf16 v[54:57], v[134:137], v[166:169], v[54:57]
	v_mfma_f32_16x16x32_bf16 v[50:53], v[150:153], v[166:169], v[50:53]
	v_mfma_f32_16x16x32_bf16 v[38:41], v[134:137], v[174:177], v[38:41]
	v_mfma_f32_16x16x32_bf16 v[34:37], v[150:153], v[174:177], v[34:37]
	v_mfma_f32_16x16x32_bf16 v[22:25], v[134:137], v[182:185], v[22:25]
	v_mfma_f32_16x16x32_bf16 v[18:21], v[150:153], v[182:185], v[18:21]
	v_mfma_f32_16x16x32_bf16 v[6:9], v[134:137], v[194:197], v[6:9]
	v_mfma_f32_16x16x32_bf16 v[2:5], v[150:153], v[194:197], v[2:5]
	s_barrier
	s_add_i32 s53, 0, 0x18000
	v_add_u32_e32 v114, s53, v249
	s_add_i32 s54, 0, 0x1c000
	v_add_u32_e32 v150, s54, v249
	ds_read_b128 v[82:85], v114
	ds_read_b128 v[94:97], v114 offset:1024
	ds_read_b128 v[106:109], v114 offset:2048
	ds_read_b128 v[114:117], v114 offset:3072
	ds_read_b128 v[130:133], v150
	ds_read_b128 v[134:137], v150 offset:1024
	ds_read_b128 v[146:149], v150 offset:2048
	ds_read_b128 v[150:153], v150 offset:3072
	ds_read_b128 v[154:157], v251 offset:32768
	ds_read_b128 v[166:169], v251 offset:33792
	ds_read_b128 v[170:173], v251 offset:34816
	ds_read_b128 v[174:177], v251 offset:35840
	ds_read_b128 v[178:181], v251 offset:36864
	ds_read_b128 v[182:185], v251 offset:37888
	ds_read_b128 v[186:189], v251 offset:38912
	ds_read_b128 v[194:197], v251 offset:39936
	s_add_u32 s20, s24, 0x160000
	s_addc_u32 s21, s25, 0
	s_mov_b32 m0, s38
	s_nop 0
	global_load_lds_dwordx4 v190, s[20:21]
	s_mov_b32 m0, s39
	s_nop 0
	global_load_lds_dwordx4 v192, s[20:21]
	s_waitcnt vmcnt(8)
	s_waitcnt lgkmcnt(0)
	s_barrier
	s_waitcnt lgkmcnt(0)
	v_mfma_f32_16x16x32_bf16 v[162:165], v[82:85], v[154:157], v[162:165]
	v_mfma_f32_16x16x32_bf16 v[158:161], v[106:109], v[154:157], v[158:161]
	v_mfma_f32_16x16x32_bf16 v[126:129], v[82:85], v[170:173], v[126:129]
	v_mfma_f32_16x16x32_bf16 v[122:125], v[106:109], v[170:173], v[122:125]
	v_mfma_f32_16x16x32_bf16 v[102:105], v[82:85], v[178:181], v[102:105]
	v_mfma_f32_16x16x32_bf16 v[98:101], v[106:109], v[178:181], v[98:101]
	v_mfma_f32_16x16x32_bf16 v[78:81], v[82:85], v[186:189], v[78:81]
	v_mfma_f32_16x16x32_bf16 v[74:77], v[106:109], v[186:189], v[74:77]
	v_mfma_f32_16x16x32_bf16 v[162:165], v[94:97], v[166:169], v[162:165]
	v_mfma_f32_16x16x32_bf16 v[158:161], v[114:117], v[166:169], v[158:161]
	v_mfma_f32_16x16x32_bf16 v[126:129], v[94:97], v[174:177], v[126:129]
	v_mfma_f32_16x16x32_bf16 v[122:125], v[114:117], v[174:177], v[122:125]
	v_mfma_f32_16x16x32_bf16 v[102:105], v[94:97], v[182:185], v[102:105]
	v_mfma_f32_16x16x32_bf16 v[98:101], v[114:117], v[182:185], v[98:101]
	v_mfma_f32_16x16x32_bf16 v[78:81], v[94:97], v[194:197], v[78:81]
	v_mfma_f32_16x16x32_bf16 v[74:77], v[114:117], v[194:197], v[74:77]
	v_mfma_f32_16x16x32_bf16 v[142:145], v[130:133], v[154:157], v[142:145]
	v_mfma_f32_16x16x32_bf16 v[138:141], v[146:149], v[154:157], v[138:141]
	v_mfma_f32_16x16x32_bf16 v[118:121], v[130:133], v[170:173], v[118:121]
	v_mfma_f32_16x16x32_bf16 v[110:113], v[146:149], v[170:173], v[110:113]
	v_mfma_f32_16x16x32_bf16 v[90:93], v[130:133], v[178:181], v[90:93]
	v_mfma_f32_16x16x32_bf16 v[86:89], v[146:149], v[178:181], v[86:89]
	v_mfma_f32_16x16x32_bf16 v[70:73], v[130:133], v[186:189], v[70:73]
	v_mfma_f32_16x16x32_bf16 v[66:69], v[146:149], v[186:189], v[66:69]
	v_mfma_f32_16x16x32_bf16 v[142:145], v[134:137], v[166:169], v[142:145]
	v_mfma_f32_16x16x32_bf16 v[138:141], v[150:153], v[166:169], v[138:141]
	v_mfma_f32_16x16x32_bf16 v[118:121], v[134:137], v[174:177], v[118:121]
	v_mfma_f32_16x16x32_bf16 v[110:113], v[150:153], v[174:177], v[110:113]
	v_mfma_f32_16x16x32_bf16 v[90:93], v[134:137], v[182:185], v[90:93]
	v_mfma_f32_16x16x32_bf16 v[86:89], v[150:153], v[182:185], v[86:89]
	v_mfma_f32_16x16x32_bf16 v[70:73], v[134:137], v[194:197], v[70:73]
	v_mfma_f32_16x16x32_bf16 v[66:69], v[150:153], v[194:197], v[66:69]
	s_barrier
; #define PG8_STAGE(bufoff, gbase, voff) do { _Pragma("unroll") for (int _i = 0; _i < 2; ++_i) \
;         __builtin_amdgcn_global_load_lds((const unsigned*)((const char*)(gbase) + (voff)[_i]), (LAS unsigned*)(lds + (bufoff) + ldsw + _i * 8192), 16, 0, 0); } while (0)
; #define PG8_LDA(dst, b, h) do { _Pragma("unroll") for (int m = 0; m < 4; ++m) _Pragma("unroll") for (int k = 0; k < 2; ++k) dst[m][k] = *(const LAS bf16x8*)(lds + PG8_SA(b, h) + aoff + m * 2048 + k * 1024); } while (0)
; #define PG8_LDB(dst, b, h) do { _Pragma("unroll") for (int n = 0; n < 2; ++n) _Pragma("unroll") for (int k = 0; k < 2; ++k) dst[n][k] = *(const LAS bf16x8*)(lds + PG8_SB(b, h) + boff + n * 2048 + k * 1024); } while (0)
; #define PG8_MMA(ai, bj, At, Bt) do { __builtin_amdgcn_s_setprio(1); _Pragma("unroll") for (int m = 0; m < 4; ++m) _Pragma("unroll") for (int n = 0; n < 2; ++n) _Pragma("unroll") for (int k = 0; k < 2; ++k) \
;         acc[ai][bj][m][n] = __builtin_amdgcn_mfma_f32_16x16x32_bf16(Bt[n][k], At[m][k], acc[ai][bj][m][n], 0, 0, 0); __builtin_amdgcn_s_setprio(0); } while (0)
; #define PG8_WAIT_V(n) asm volatile("s_waitcnt vmcnt(" #n ")" ::: "memory")
; #define PG8_BAR __builtin_amdgcn_s_barrier()
; template <class Epi, class Sched, int KC, bool ALIGN_EPI = false, bool SP2 = false, bool ATILED = false>
; __device__ __forceinline__ void gemm_phase(LAS unsigned char* lds, const Gemm g, const Sched& S, const Epi& E, int wave_s) {
;     ...
;         for (int t = 0; t < nt; t += 2) {
;             const bool last = (t == nt - 2);
;             const char* a1 = cA + PG8_AOFF(t + 1);
;             const char* a2 = last ? nA : cA + PG8_AOFF(t + 2); const char* b2 = last ? nB : cB + (size_t)(t + 2) * kstep;
;             const char* a3 = a2 + kstep; const char* b3 = b2 + kstep;
;             if (last && has_next) S.a_ready(nxt);
;             if constexpr (SP2) {
;             PG8_LDB(B0, 0, 0); PG8_LDB(B1, 0, 1); PG8_SCHED; PG8_LDA(At, 0, 0); PG8_STAGE(PG8_SA(1, 1), a1 + hstepA, voffA);
;             PG8_WAIT_V(8); PG8_WAIT_L(0); PG8_BAR; PG8_MMA(0, 0, At, B0); PG8_MMA(0, 1, At, B1); PG8_BAR; PG8_SCHED;
;     ...
;             PG8_LDA(At, 1, 1); PG8_STAGE(PG8_SB(1, 0), b3, voffB); PG8_STAGE(PG8_SB(1, 1), b3 + hstepB, voffB); PG8_STAGE(PG8_SA(1, 0), a3, voffA);
;             PG8_WAIT_V(8); PG8_WAIT_L(0); PG8_BAR; PG8_MMA(1, 0, At, B0); PG8_MMA(1, 1, At, B1); PG8_BAR; PG8_SCHED;
	ds_read_b128 v[154:157], v251 offset:49152
	ds_read_b128 v[166:169], v251 offset:50176
	ds_read_b128 v[170:173], v251 offset:51200
	ds_read_b128 v[174:177], v251 offset:52224
	ds_read_b128 v[178:181], v251 offset:53248
	ds_read_b128 v[182:185], v251 offset:54272
	ds_read_b128 v[186:189], v251 offset:55296
	ds_read_b128 v[194:197], v251 offset:56320
	s_add_u32 s98, s22, 0x80
	s_addc_u32 s99, s23, 0
	s_add_u32 s100, s24, 0x80
	s_addc_u32 s101, s25, 0
	s_add_i32 s20, s53, s35
	s_mov_b32 m0, s20
	s_nop 0
	global_load_lds_dwordx4 v0, s[98:99]
	s_add_i32 m0, s20, 0x2000
	s_add_u32 s20, s22, 0x58080
	s_addc_u32 s21, s23, 0
	s_add_i32 s22, s54, s35
	global_load_lds_dwordx4 v198, s[98:99]
	s_mov_b32 m0, s22
	s_nop 0
	global_load_lds_dwordx4 v0, s[20:21]
	s_add_i32 m0, s22, 0x2000
	s_nop 0
	global_load_lds_dwordx4 v198, s[20:21]
	s_mov_b32 m0, s43
	s_nop 0
	global_load_lds_dwordx4 v190, s[100:101]
	s_mov_b32 m0, s44
	s_nop 0
	global_load_lds_dwordx4 v192, s[100:101]
	s_waitcnt vmcnt(8)
	s_waitcnt lgkmcnt(0)
	s_barrier
	s_waitcnt lgkmcnt(0)
	v_mfma_f32_16x16x32_bf16 v[62:65], v[82:85], v[154:157], v[62:65]
	v_mfma_f32_16x16x32_bf16 v[58:61], v[106:109], v[154:157], v[58:61]
	v_mfma_f32_16x16x32_bf16 v[46:49], v[82:85], v[170:173], v[46:49]
	v_mfma_f32_16x16x32_bf16 v[42:45], v[106:109], v[170:173], v[42:45]
	v_mfma_f32_16x16x32_bf16 v[30:33], v[82:85], v[178:181], v[30:33]
	v_mfma_f32_16x16x32_bf16 v[26:29], v[106:109], v[178:181], v[26:29]
	v_mfma_f32_16x16x32_bf16 v[14:17], v[82:85], v[186:189], v[14:17]
	v_mfma_f32_16x16x32_bf16 v[10:13], v[106:109], v[186:189], v[10:13]
	v_mfma_f32_16x16x32_bf16 v[62:65], v[94:97], v[166:169], v[62:65]
	v_mfma_f32_16x16x32_bf16 v[58:61], v[114:117], v[166:169], v[58:61]
	v_mfma_f32_16x16x32_bf16 v[46:49], v[94:97], v[174:177], v[46:49]
	v_mfma_f32_16x16x32_bf16 v[42:45], v[114:117], v[174:177], v[42:45]
	v_mfma_f32_16x16x32_bf16 v[30:33], v[94:97], v[182:185], v[30:33]
	v_mfma_f32_16x16x32_bf16 v[26:29], v[114:117], v[182:185], v[26:29]
	v_mfma_f32_16x16x32_bf16 v[14:17], v[94:97], v[194:197], v[14:17]
	v_mfma_f32_16x16x32_bf16 v[10:13], v[114:117], v[194:197], v[10:13]
	v_mfma_f32_16x16x32_bf16 v[54:57], v[130:133], v[154:157], v[54:57]
	v_mfma_f32_16x16x32_bf16 v[50:53], v[146:149], v[154:157], v[50:53]
	v_mfma_f32_16x16x32_bf16 v[38:41], v[130:133], v[170:173], v[38:41]
	v_mfma_f32_16x16x32_bf16 v[34:37], v[146:149], v[170:173], v[34:37]
	v_mfma_f32_16x16x32_bf16 v[22:25], v[130:133], v[178:181], v[22:25]
	v_mfma_f32_16x16x32_bf16 v[18:21], v[146:149], v[178:181], v[18:21]
	v_mfma_f32_16x16x32_bf16 v[6:9], v[130:133], v[186:189], v[6:9]
	v_mfma_f32_16x16x32_bf16 v[2:5], v[146:149], v[186:189], v[2:5]
	v_mfma_f32_16x16x32_bf16 v[54:57], v[134:137], v[166:169], v[54:57]
	v_mfma_f32_16x16x32_bf16 v[50:53], v[150:153], v[166:169], v[50:53]
	v_mfma_f32_16x16x32_bf16 v[38:41], v[134:137], v[174:177], v[38:41]
	v_mfma_f32_16x16x32_bf16 v[34:37], v[150:153], v[174:177], v[34:37]
	v_mfma_f32_16x16x32_bf16 v[22:25], v[134:137], v[182:185], v[22:25]
	v_mfma_f32_16x16x32_bf16 v[18:21], v[150:153], v[182:185], v[18:21]
	v_mfma_f32_16x16x32_bf16 v[6:9], v[134:137], v[194:197], v[6:9]
	v_mfma_f32_16x16x32_bf16 v[2:5], v[150:153], v[194:197], v[2:5]
	s_barrier
	s_add_i32 s52, s52, 2
	s_add_u32 s50, s50, 0x100
	s_addc_u32 s51, s51, 0
	s_cmpk_gt_u32 s52, 0x55
	s_mov_b64 s[20:21], s[8:9]
.LBB0_318:
	s_add_i32 s53, 0, 0x10000
	v_add_u32_e32 v114, s53, v249
	s_add_i32 s54, 0, 0x14000
	v_add_u32_e32 v150, s54, v249
	ds_read_b128 v[82:85], v114
	ds_read_b128 v[94:97], v114 offset:1024
	ds_read_b128 v[106:109], v114 offset:2048
	ds_read_b128 v[114:117], v114 offset:3072
	ds_read_b128 v[130:133], v150
	ds_read_b128 v[134:137], v150 offset:1024
	ds_read_b128 v[146:149], v150 offset:2048
	ds_read_b128 v[150:153], v150 offset:3072
	ds_read_b128 v[154:157], v251
	ds_read_b128 v[166:169], v251 offset:1024
	ds_read_b128 v[170:173], v251 offset:2048
	ds_read_b128 v[174:177], v251 offset:3072
	ds_read_b128 v[178:181], v251 offset:4096
	ds_read_b128 v[182:185], v251 offset:5120
	ds_read_b128 v[186:189], v251 offset:6144
	ds_read_b128 v[194:197], v251 offset:7168
	s_add_u32 s8, s20, 0x100
	s_addc_u32 s9, s21, 0
	s_cmpk_eq_i32 s52, 0x54
	s_cselect_b32 s25, s17, s9
	s_cselect_b32 s24, s16, s8
	s_cselect_b32 s23, s11, s51
	s_cselect_b32 s22, s10, s50
	s_add_i32 m0, s36, 0xc000
	s_nop 0
	global_load_lds_dwordx4 v204, s[20:21]
	s_add_i32 m0, s36, 0xe000
	s_nop 0
	global_load_lds_dwordx4 v202, s[20:21]
	s_waitcnt vmcnt(8)
	s_waitcnt lgkmcnt(0)
	s_barrier
; #define PG8_STAGE(bufoff, gbase, voff) do { _Pragma("unroll") for (int _i = 0; _i < 2; ++_i) \
;         __builtin_amdgcn_global_load_lds((const unsigned*)((const char*)(gbase) + (voff)[_i]), (LAS unsigned*)(lds + (bufoff) + ldsw + _i * 8192), 16, 0, 0); } while (0)
; #define PG8_LDA(dst, b, h) do { _Pragma("unroll") for (int m = 0; m < 4; ++m) _Pragma("unroll") for (int k = 0; k < 2; ++k) dst[m][k] = *(const LAS bf16x8*)(lds + PG8_SA(b, h) + aoff + m * 2048 + k * 1024); } while (0)
; #define PG8_MMA(ai, bj, At, Bt) do { __builtin_amdgcn_s_setprio(1); _Pragma("unroll") for (int m = 0; m < 4; ++m) _Pragma("unroll") for (int n = 0; n < 2; ++n) _Pragma("unroll") for (int k = 0; k < 2; ++k) \
;         acc[ai][bj][m][n] = __builtin_amdgcn_mfma_f32_16x16x32_bf16(Bt[n][k], At[m][k], acc[ai][bj][m][n], 0, 0, 0); __builtin_amdgcn_s_setprio(0); } while (0)
; #define PG8_WAIT_V(n) asm volatile("s_waitcnt vmcnt(" #n ")" ::: "memory")
; #define PG8_WAIT_L(n) asm volatile("s_waitcnt lgkmcnt(" #n ")" ::: "memory")
; #define PG8_BAR __builtin_amdgcn_s_barrier()
; #define PG8_SCHED __builtin_amdgcn_sched_barrier(0)
; template <class Epi, class Sched, int KC, bool ALIGN_EPI = false, bool SP2 = false, bool ATILED = false>
; __device__ __forceinline__ void gemm_phase(LAS unsigned char* lds, const Gemm g, const Sched& S, const Epi& E, int wave_s) {
;     ...
;             PG8_WAIT_V(8); PG8_WAIT_L(0); PG8_BAR; PG8_MMA(0, 0, At, B0); PG8_MMA(0, 1, At, B1); PG8_BAR; PG8_SCHED;
;             PG8_LDA(At, 0, 1); PG8_STAGE(PG8_SB(0, 0), b2, voffB); PG8_STAGE(PG8_SB(0, 1), b2 + hstepB, voffB); PG8_STAGE(PG8_SA(0, 0), a2, voffA);
;             PG8_WAIT_V(8); PG8_WAIT_L(0); PG8_BAR; PG8_MMA(1, 0, At, B0); PG8_MMA(1, 1, At, B1); PG8_BAR; PG8_SCHED;
	s_waitcnt lgkmcnt(0)
	v_mfma_f32_16x16x32_bf16 v[162:165], v[82:85], v[154:157], v[162:165]
	v_mfma_f32_16x16x32_bf16 v[158:161], v[106:109], v[154:157], v[158:161]
	v_mfma_f32_16x16x32_bf16 v[126:129], v[82:85], v[170:173], v[126:129]
	v_mfma_f32_16x16x32_bf16 v[122:125], v[106:109], v[170:173], v[122:125]
	v_mfma_f32_16x16x32_bf16 v[102:105], v[82:85], v[178:181], v[102:105]
	v_mfma_f32_16x16x32_bf16 v[98:101], v[106:109], v[178:181], v[98:101]
	v_mfma_f32_16x16x32_bf16 v[78:81], v[82:85], v[186:189], v[78:81]
	v_mfma_f32_16x16x32_bf16 v[74:77], v[106:109], v[186:189], v[74:77]
	v_mfma_f32_16x16x32_bf16 v[162:165], v[94:97], v[166:169], v[162:165]
	v_mfma_f32_16x16x32_bf16 v[158:161], v[114:117], v[166:169], v[158:161]
	v_mfma_f32_16x16x32_bf16 v[126:129], v[94:97], v[174:177], v[126:129]
	v_mfma_f32_16x16x32_bf16 v[122:125], v[114:117], v[174:177], v[122:125]
	v_mfma_f32_16x16x32_bf16 v[102:105], v[94:97], v[182:185], v[102:105]
	v_mfma_f32_16x16x32_bf16 v[98:101], v[114:117], v[182:185], v[98:101]
	v_mfma_f32_16x16x32_bf16 v[78:81], v[94:97], v[194:197], v[78:81]
	v_mfma_f32_16x16x32_bf16 v[74:77], v[114:117], v[194:197], v[74:77]
	v_mfma_f32_16x16x32_bf16 v[142:145], v[130:133], v[154:157], v[142:145]
	v_mfma_f32_16x16x32_bf16 v[138:141], v[146:149], v[154:157], v[138:141]
	v_mfma_f32_16x16x32_bf16 v[118:121], v[130:133], v[170:173], v[118:121]
	v_mfma_f32_16x16x32_bf16 v[110:113], v[146:149], v[170:173], v[110:113]
	v_mfma_f32_16x16x32_bf16 v[90:93], v[130:133], v[178:181], v[90:93]
	v_mfma_f32_16x16x32_bf16 v[86:89], v[146:149], v[178:181], v[86:89]
	v_mfma_f32_16x16x32_bf16 v[70:73], v[130:133], v[186:189], v[70:73]
	v_mfma_f32_16x16x32_bf16 v[66:69], v[146:149], v[186:189], v[66:69]
	v_mfma_f32_16x16x32_bf16 v[142:145], v[134:137], v[166:169], v[142:145]
	v_mfma_f32_16x16x32_bf16 v[138:141], v[150:153], v[166:169], v[138:141]
	v_mfma_f32_16x16x32_bf16 v[118:121], v[134:137], v[174:177], v[118:121]
	v_mfma_f32_16x16x32_bf16 v[110:113], v[150:153], v[174:177], v[110:113]
	v_mfma_f32_16x16x32_bf16 v[90:93], v[134:137], v[182:185], v[90:93]
	v_mfma_f32_16x16x32_bf16 v[86:89], v[150:153], v[182:185], v[86:89]
	v_mfma_f32_16x16x32_bf16 v[70:73], v[134:137], v[194:197], v[70:73]
	v_mfma_f32_16x16x32_bf16 v[66:69], v[150:153], v[194:197], v[66:69]
	s_barrier
	ds_read_b128 v[154:157], v251 offset:16384
	ds_read_b128 v[166:169], v251 offset:17408
	ds_read_b128 v[170:173], v251 offset:18432
	ds_read_b128 v[174:177], v251 offset:19456
	ds_read_b128 v[178:181], v251 offset:20480
	ds_read_b128 v[182:185], v251 offset:21504
	ds_read_b128 v[186:189], v251 offset:22528
	ds_read_b128 v[194:197], v251 offset:23552
	s_add_i32 s20, s53, s35
	s_mov_b32 m0, s20
	s_nop 0
	global_load_lds_dwordx4 v0, s[22:23]
	s_add_i32 m0, s20, 0x2000
	s_add_u32 s20, s22, 0x58000
	s_addc_u32 s21, s23, 0
	s_add_i32 s53, s54, s35
	global_load_lds_dwordx4 v198, s[22:23]
	s_mov_b32 m0, s53
	s_nop 0
	global_load_lds_dwordx4 v0, s[20:21]
	s_add_i32 m0, s53, 0x2000
	s_nop 0
	global_load_lds_dwordx4 v198, s[20:21]
	s_mov_b32 m0, s36
	s_nop 0
	global_load_lds_dwordx4 v190, s[24:25]
	s_mov_b32 m0, s37
	s_nop 0
	global_load_lds_dwordx4 v192, s[24:25]
	s_waitcnt vmcnt(8)
	s_waitcnt lgkmcnt(0)
	s_barrier
	s_waitcnt lgkmcnt(0)
	v_mfma_f32_16x16x32_bf16 v[62:65], v[82:85], v[154:157], v[62:65]
	v_mfma_f32_16x16x32_bf16 v[58:61], v[106:109], v[154:157], v[58:61]
	v_mfma_f32_16x16x32_bf16 v[46:49], v[82:85], v[170:173], v[46:49]
	v_mfma_f32_16x16x32_bf16 v[42:45], v[106:109], v[170:173], v[42:45]
	v_mfma_f32_16x16x32_bf16 v[30:33], v[82:85], v[178:181], v[30:33]
	v_mfma_f32_16x16x32_bf16 v[26:29], v[106:109], v[178:181], v[26:29]
	v_mfma_f32_16x16x32_bf16 v[14:17], v[82:85], v[186:189], v[14:17]
	v_mfma_f32_16x16x32_bf16 v[10:13], v[106:109], v[186:189], v[10:13]
	v_mfma_f32_16x16x32_bf16 v[62:65], v[94:97], v[166:169], v[62:65]
	v_mfma_f32_16x16x32_bf16 v[58:61], v[114:117], v[166:169], v[58:61]
	v_mfma_f32_16x16x32_bf16 v[46:49], v[94:97], v[174:177], v[46:49]
	v_mfma_f32_16x16x32_bf16 v[42:45], v[114:117], v[174:177], v[42:45]
	v_mfma_f32_16x16x32_bf16 v[30:33], v[94:97], v[182:185], v[30:33]
	v_mfma_f32_16x16x32_bf16 v[26:29], v[114:117], v[182:185], v[26:29]
	v_mfma_f32_16x16x32_bf16 v[14:17], v[94:97], v[194:197], v[14:17]
	v_mfma_f32_16x16x32_bf16 v[10:13], v[114:117], v[194:197], v[10:13]
	v_mfma_f32_16x16x32_bf16 v[54:57], v[130:133], v[154:157], v[54:57]
	v_mfma_f32_16x16x32_bf16 v[50:53], v[146:149], v[154:157], v[50:53]
	v_mfma_f32_16x16x32_bf16 v[38:41], v[130:133], v[170:173], v[38:41]
	v_mfma_f32_16x16x32_bf16 v[34:37], v[146:149], v[170:173], v[34:37]
	v_mfma_f32_16x16x32_bf16 v[22:25], v[130:133], v[178:181], v[22:25]
	v_mfma_f32_16x16x32_bf16 v[18:21], v[146:149], v[178:181], v[18:21]
	v_mfma_f32_16x16x32_bf16 v[6:9], v[130:133], v[186:189], v[6:9]
	v_mfma_f32_16x16x32_bf16 v[2:5], v[146:149], v[186:189], v[2:5]
	v_mfma_f32_16x16x32_bf16 v[54:57], v[134:137], v[166:169], v[54:57]
	v_mfma_f32_16x16x32_bf16 v[50:53], v[150:153], v[166:169], v[50:53]
	v_mfma_f32_16x16x32_bf16 v[38:41], v[134:137], v[174:177], v[38:41]
	v_mfma_f32_16x16x32_bf16 v[34:37], v[150:153], v[174:177], v[34:37]
	v_mfma_f32_16x16x32_bf16 v[22:25], v[134:137], v[182:185], v[22:25]
	v_mfma_f32_16x16x32_bf16 v[18:21], v[150:153], v[182:185], v[18:21]
	v_mfma_f32_16x16x32_bf16 v[6:9], v[134:137], v[194:197], v[6:9]
	v_mfma_f32_16x16x32_bf16 v[2:5], v[150:153], v[194:197], v[2:5]
	s_barrier
; #define PG8_STAGE(bufoff, gbase, voff) do { _Pragma("unroll") for (int _i = 0; _i < 2; ++_i) \
;         __builtin_amdgcn_global_load_lds((const unsigned*)((const char*)(gbase) + (voff)[_i]), (LAS unsigned*)(lds + (bufoff) + ldsw + _i * 8192), 16, 0, 0); } while (0)
; #define PG8_LDA(dst, b, h) do { _Pragma("unroll") for (int m = 0; m < 4; ++m) _Pragma("unroll") for (int k = 0; k < 2; ++k) dst[m][k] = *(const LAS bf16x8*)(lds + PG8_SA(b, h) + aoff + m * 2048 + k * 1024); } while (0)
; #define PG8_LDB(dst, b, h) do { _Pragma("unroll") for (int n = 0; n < 2; ++n) _Pragma("unroll") for (int k = 0; k < 2; ++k) dst[n][k] = *(const LAS bf16x8*)(lds + PG8_SB(b, h) + boff + n * 2048 + k * 1024); } while (0)
; #define PG8_MMA(ai, bj, At, Bt) do { __builtin_amdgcn_s_setprio(1); _Pragma("unroll") for (int m = 0; m < 4; ++m) _Pragma("unroll") for (int n = 0; n < 2; ++n) _Pragma("unroll") for (int k = 0; k < 2; ++k) \
;         acc[ai][bj][m][n] = __builtin_amdgcn_mfma_f32_16x16x32_bf16(Bt[n][k], At[m][k], acc[ai][bj][m][n], 0, 0, 0); __builtin_amdgcn_s_setprio(0); } while (0)
; #define PG8_WAIT_V(n) asm volatile("s_waitcnt vmcnt(" #n ")" ::: "memory")
; #define PG8_WAIT_L(n) asm volatile("s_waitcnt lgkmcnt(" #n ")" ::: "memory")
; #define PG8_BAR __builtin_amdgcn_s_barrier()
; #define PG8_SCHED __builtin_amdgcn_sched_barrier(0)
; template <class Epi, class Sched, int KC, bool ALIGN_EPI = false, bool SP2 = false, bool ATILED = false>
; __device__ __forceinline__ void gemm_phase(LAS unsigned char* lds, const Gemm g, const Sched& S, const Epi& E, int wave_s) {
;     ...
;             PG8_LDB(B0, 1, 0); PG8_LDB(B1, 1, 1); PG8_SCHED; PG8_LDA(At, 1, 0); PG8_STAGE(PG8_SA(0, 1), a2 + hstepA, voffA);
;             PG8_WAIT_V(8); PG8_WAIT_L(0); PG8_BAR; PG8_MMA(0, 0, At, B0); PG8_MMA(0, 1, At, B1); PG8_BAR; PG8_SCHED;
;             PG8_LDA(At, 1, 1); PG8_STAGE(PG8_SB(1, 0), b3, voffB); PG8_STAGE(PG8_SB(1, 1), b3 + hstepB, voffB); PG8_STAGE(PG8_SA(1, 0), a3, voffA);
;             PG8_WAIT_V(8); PG8_WAIT_L(0); PG8_BAR; PG8_MMA(1, 0, At, B0); PG8_MMA(1, 1, At, B1); PG8_BAR; PG8_SCHED;
	s_add_i32 s53, 0, 0x18000
	v_add_u32_e32 v114, s53, v249
	s_add_i32 s54, 0, 0x1c000
	v_add_u32_e32 v150, s54, v249
	ds_read_b128 v[82:85], v114
	ds_read_b128 v[94:97], v114 offset:1024
	ds_read_b128 v[106:109], v114 offset:2048
	ds_read_b128 v[114:117], v114 offset:3072
	ds_read_b128 v[130:133], v150
	ds_read_b128 v[134:137], v150 offset:1024
	ds_read_b128 v[146:149], v150 offset:2048
	ds_read_b128 v[150:153], v150 offset:3072
	ds_read_b128 v[154:157], v251 offset:32768
	ds_read_b128 v[166:169], v251 offset:33792
	ds_read_b128 v[170:173], v251 offset:34816
	ds_read_b128 v[174:177], v251 offset:35840
	ds_read_b128 v[178:181], v251 offset:36864
	ds_read_b128 v[182:185], v251 offset:37888
	ds_read_b128 v[186:189], v251 offset:38912
	ds_read_b128 v[194:197], v251 offset:39936
	s_add_u32 s20, s24, 0x160000
	s_addc_u32 s21, s25, 0
	s_mov_b32 m0, s38
	s_nop 0
	global_load_lds_dwordx4 v190, s[20:21]
	s_mov_b32 m0, s39
	s_nop 0
	global_load_lds_dwordx4 v192, s[20:21]
	s_waitcnt vmcnt(8)
	s_waitcnt lgkmcnt(0)
	s_barrier
	s_waitcnt lgkmcnt(0)
	v_mfma_f32_16x16x32_bf16 v[162:165], v[82:85], v[154:157], v[162:165]
	v_mfma_f32_16x16x32_bf16 v[158:161], v[106:109], v[154:157], v[158:161]
	v_mfma_f32_16x16x32_bf16 v[126:129], v[82:85], v[170:173], v[126:129]
	v_mfma_f32_16x16x32_bf16 v[122:125], v[106:109], v[170:173], v[122:125]
	v_mfma_f32_16x16x32_bf16 v[102:105], v[82:85], v[178:181], v[102:105]
	v_mfma_f32_16x16x32_bf16 v[98:101], v[106:109], v[178:181], v[98:101]
	v_mfma_f32_16x16x32_bf16 v[78:81], v[82:85], v[186:189], v[78:81]
	v_mfma_f32_16x16x32_bf16 v[74:77], v[106:109], v[186:189], v[74:77]
	v_mfma_f32_16x16x32_bf16 v[162:165], v[94:97], v[166:169], v[162:165]
	v_mfma_f32_16x16x32_bf16 v[158:161], v[114:117], v[166:169], v[158:161]
	v_mfma_f32_16x16x32_bf16 v[126:129], v[94:97], v[174:177], v[126:129]
	v_mfma_f32_16x16x32_bf16 v[122:125], v[114:117], v[174:177], v[122:125]
	v_mfma_f32_16x16x32_bf16 v[102:105], v[94:97], v[182:185], v[102:105]
	v_mfma_f32_16x16x32_bf16 v[98:101], v[114:117], v[182:185], v[98:101]
	v_mfma_f32_16x16x32_bf16 v[78:81], v[94:97], v[194:197], v[78:81]
	v_mfma_f32_16x16x32_bf16 v[74:77], v[114:117], v[194:197], v[74:77]
	v_mfma_f32_16x16x32_bf16 v[142:145], v[130:133], v[154:157], v[142:145]
	v_mfma_f32_16x16x32_bf16 v[138:141], v[146:149], v[154:157], v[138:141]
	v_mfma_f32_16x16x32_bf16 v[118:121], v[130:133], v[170:173], v[118:121]
	v_mfma_f32_16x16x32_bf16 v[110:113], v[146:149], v[170:173], v[110:113]
	v_mfma_f32_16x16x32_bf16 v[90:93], v[130:133], v[178:181], v[90:93]
	v_mfma_f32_16x16x32_bf16 v[86:89], v[146:149], v[178:181], v[86:89]
	v_mfma_f32_16x16x32_bf16 v[70:73], v[130:133], v[186:189], v[70:73]
	v_mfma_f32_16x16x32_bf16 v[66:69], v[146:149], v[186:189], v[66:69]
	v_mfma_f32_16x16x32_bf16 v[142:145], v[134:137], v[166:169], v[142:145]
	v_mfma_f32_16x16x32_bf16 v[138:141], v[150:153], v[166:169], v[138:141]
	v_mfma_f32_16x16x32_bf16 v[118:121], v[134:137], v[174:177], v[118:121]
	v_mfma_f32_16x16x32_bf16 v[110:113], v[150:153], v[174:177], v[110:113]
	v_mfma_f32_16x16x32_bf16 v[90:93], v[134:137], v[182:185], v[90:93]
	v_mfma_f32_16x16x32_bf16 v[86:89], v[150:153], v[182:185], v[86:89]
	v_mfma_f32_16x16x32_bf16 v[70:73], v[134:137], v[194:197], v[70:73]
	v_mfma_f32_16x16x32_bf16 v[66:69], v[150:153], v[194:197], v[66:69]
	s_barrier
	ds_read_b128 v[154:157], v251 offset:49152
	ds_read_b128 v[166:169], v251 offset:50176
	ds_read_b128 v[170:173], v251 offset:51200
	ds_read_b128 v[174:177], v251 offset:52224
	ds_read_b128 v[178:181], v251 offset:53248
	ds_read_b128 v[182:185], v251 offset:54272
	ds_read_b128 v[186:189], v251 offset:55296
	ds_read_b128 v[194:197], v251 offset:56320
	s_add_u32 s98, s22, 0x80
	s_addc_u32 s99, s23, 0
	s_add_u32 s100, s24, 0x80
	s_addc_u32 s101, s25, 0
	s_add_i32 s20, s53, s35
	s_mov_b32 m0, s20
	s_nop 0
	global_load_lds_dwordx4 v0, s[98:99]
	s_add_i32 m0, s20, 0x2000
	s_add_u32 s20, s22, 0x58080
	s_addc_u32 s21, s23, 0
	s_add_i32 s22, s54, s35
	global_load_lds_dwordx4 v198, s[98:99]
	s_mov_b32 m0, s22
	s_nop 0
	global_load_lds_dwordx4 v0, s[20:21]
	s_add_i32 m0, s22, 0x2000
	s_nop 0
	global_load_lds_dwordx4 v198, s[20:21]
	s_mov_b32 m0, s43
	s_nop 0
	global_load_lds_dwordx4 v190, s[100:101]
	s_mov_b32 m0, s44
	s_nop 0
	global_load_lds_dwordx4 v192, s[100:101]
	s_waitcnt vmcnt(8)
	s_waitcnt lgkmcnt(0)
	s_barrier
; #define GAS __attribute__((address_space(1)))
; #define PG8_WAIT_V(n) asm volatile("s_waitcnt vmcnt(" #n ")" ::: "memory")
;     DI void operator()(const f32x4 (&acc)[2][2][4][2], const Unit& u, int wr, int wc, int fr, int fq) const {
;     ...
;         u32x4 H[2][4][2];
; #pragma unroll
;         for (int ai = 0; ai < 2; ++ai)
; #pragma unroll
;             for (int m = 0; m < 4; ++m)
; #pragma unroll
;                 for (int bj = 0; bj < 2; ++bj) H[ai][m][bj] = *(const GAS u32x4*)(hi + hbase + (size_t)(row0 + ai * HALF + m * 16) * 256 + bj * 32);
;         asm volatile("" ::: "memory");
; #pragma unroll
;         for (int ai = 0; ai < 2; ++ai) {
; #pragma unroll
;             for (int m = 0; m < 4; ++m) {
;                 const int r = row0 + ai * HALF + m * 16; const size_t off = (size_t)r * DM + col0; float ss = 0.f;
; #pragma unroll
;                 for (int bj = 0; bj < 2; ++bj) {
;                     const u32x4 h = H[ai][m][bj];
;                     const f32x4 a0 = acc[ai][bj][m][0], a1 = acc[ai][bj][m][1];
;                     float v[8];
;                     v[0] = bflo(h.x) + a0[0] * scale; v[1] = bfhi(h.x) + a0[1] * scale;
;                     v[2] = bflo(h.y) + a0[2] * scale; v[3] = bfhi(h.y) + a0[3] * scale;
;                     v[4] = bflo(h.z) + a1[0] * scale; v[5] = bfhi(h.z) + a1[1] * scale;
;                     v[6] = bflo(h.w) + a1[2] * scale; v[7] = bfhi(h.w) + a1[3] * scale;
; #pragma unroll
;                     for (int e = 0; e < 8; ++e) ss += v[e] * v[e];
;                     u32x4 nh;
;                     nh.x = cvtpk(v[0], v[1]); nh.y = cvtpk(v[2], v[3]); nh.z = cvtpk(v[4], v[5]); nh.w = cvtpk(v[6], v[7]);
;                     *(GAS u32x4*)(hi + hbase + (size_t)r * 256 + bj * 32) = nh;
; template <class Epi, class Sched, int KC, bool ALIGN_EPI = false, bool SP2 = false, bool ATILED = false>
; __device__ __forceinline__ void gemm_phase(LAS unsigned char* lds, const Gemm g, const Sched& S, const Epi& E, int wave_s) {
;     ...
;             PG8_WAIT_V(8); PG8_WAIT_L(0); PG8_BAR; PG8_MMA(0, 0, At, B0); PG8_MMA(0, 1, At, B1); PG8_BAR; PG8_SCHED;
;             PG8_LDA(At, 1, 1); PG8_STAGE(PG8_SB(1, 0), b3, voffB); PG8_STAGE(PG8_SB(1, 1), b3 + hstepB, voffB); PG8_STAGE(PG8_SA(1, 0), a3, voffA);
;             PG8_WAIT_V(8); PG8_WAIT_L(0); PG8_BAR; PG8_MMA(1, 0, At, B0); PG8_MMA(1, 1, At, B1); PG8_BAR; PG8_SCHED;
	s_waitcnt lgkmcnt(0)
	v_mfma_f32_16x16x32_bf16 v[62:65], v[82:85], v[154:157], v[62:65]
	v_mfma_f32_16x16x32_bf16 v[58:61], v[106:109], v[154:157], v[58:61]
	v_mfma_f32_16x16x32_bf16 v[46:49], v[82:85], v[170:173], v[46:49]
	v_mfma_f32_16x16x32_bf16 v[42:45], v[106:109], v[170:173], v[42:45]
	v_mfma_f32_16x16x32_bf16 v[30:33], v[82:85], v[178:181], v[30:33]
	v_mfma_f32_16x16x32_bf16 v[26:29], v[106:109], v[178:181], v[26:29]
	v_mfma_f32_16x16x32_bf16 v[14:17], v[82:85], v[186:189], v[14:17]
	v_mfma_f32_16x16x32_bf16 v[10:13], v[106:109], v[186:189], v[10:13]
	v_mfma_f32_16x16x32_bf16 v[62:65], v[94:97], v[166:169], v[62:65]
	v_mfma_f32_16x16x32_bf16 v[58:61], v[114:117], v[166:169], v[58:61]
	v_mfma_f32_16x16x32_bf16 v[46:49], v[94:97], v[174:177], v[46:49]
	v_mfma_f32_16x16x32_bf16 v[42:45], v[114:117], v[174:177], v[42:45]
	v_mfma_f32_16x16x32_bf16 v[30:33], v[94:97], v[182:185], v[30:33]
	v_mfma_f32_16x16x32_bf16 v[26:29], v[114:117], v[182:185], v[26:29]
	v_mfma_f32_16x16x32_bf16 v[14:17], v[94:97], v[194:197], v[14:17]
	v_mfma_f32_16x16x32_bf16 v[10:13], v[114:117], v[194:197], v[10:13]
	v_mfma_f32_16x16x32_bf16 v[54:57], v[130:133], v[154:157], v[54:57]
	v_mfma_f32_16x16x32_bf16 v[50:53], v[146:149], v[154:157], v[50:53]
	v_mfma_f32_16x16x32_bf16 v[38:41], v[130:133], v[170:173], v[38:41]
	v_mfma_f32_16x16x32_bf16 v[34:37], v[146:149], v[170:173], v[34:37]
	v_mfma_f32_16x16x32_bf16 v[22:25], v[130:133], v[178:181], v[22:25]
	v_mfma_f32_16x16x32_bf16 v[18:21], v[146:149], v[178:181], v[18:21]
	v_mfma_f32_16x16x32_bf16 v[6:9], v[130:133], v[186:189], v[6:9]
	v_mfma_f32_16x16x32_bf16 v[2:5], v[146:149], v[186:189], v[2:5]
	v_mfma_f32_16x16x32_bf16 v[54:57], v[134:137], v[166:169], v[54:57]
	v_mfma_f32_16x16x32_bf16 v[50:53], v[150:153], v[166:169], v[50:53]
	v_mfma_f32_16x16x32_bf16 v[38:41], v[134:137], v[174:177], v[38:41]
	v_mfma_f32_16x16x32_bf16 v[34:37], v[150:153], v[174:177], v[34:37]
	v_mfma_f32_16x16x32_bf16 v[22:25], v[134:137], v[182:185], v[22:25]
	v_mfma_f32_16x16x32_bf16 v[18:21], v[150:153], v[182:185], v[18:21]
	v_mfma_f32_16x16x32_bf16 v[6:9], v[134:137], v[194:197], v[6:9]
	v_mfma_f32_16x16x32_bf16 v[2:5], v[150:153], v[194:197], v[2:5]
	s_barrier
	s_add_i32 s52, s52, 2
	s_add_u32 s50, s50, 0x100
	s_addc_u32 s51, s51, 0
	s_cmpk_gt_u32 s52, 0x55
	s_mov_b64 s[20:21], s[8:9]
	s_cbranch_scc0 .LBB0_318
	v_lshl_add_u32 v206, s19, 8, v248
	s_ashr_i32 s19, s18, 31
	s_lshl_b64 s[8:9], s[18:19], 23
	v_ashrrev_i32_e32 v207, 31, v206
	v_or_b32_e32 v236, 16, v206
	v_lshl_add_u64 v[82:83], v[200:201], 0, s[8:9]
	v_lshlrev_b64 v[84:85], 9, v[206:207]
	v_ashrrev_i32_e32 v237, 31, v236
	v_or_b32_e32 v232, 32, v206
	v_lshl_add_u64 v[238:239], v[82:83], 0, v[84:85]
	v_lshlrev_b64 v[84:85], 9, v[236:237]
	v_ashrrev_i32_e32 v233, 31, v232
	v_or_b32_e32 v228, 48, v206
	v_lshl_add_u64 v[234:235], v[82:83], 0, v[84:85]
	v_lshlrev_b64 v[84:85], 9, v[232:233]
	v_ashrrev_i32_e32 v229, 31, v228
	v_add_u32_e32 v224, 0x80, v206
	v_lshl_add_u64 v[230:231], v[82:83], 0, v[84:85]
	v_lshlrev_b64 v[84:85], 9, v[228:229]
	v_ashrrev_i32_e32 v225, 31, v224
	v_add_u32_e32 v220, 0x90, v206
	global_load_dwordx4 v[194:197], v[238:239], off
	global_load_dwordx4 v[186:189], v[238:239], off offset:64
	v_lshl_add_u64 v[226:227], v[82:83], 0, v[84:85]
	v_lshlrev_b64 v[84:85], 9, v[224:225]
	v_ashrrev_i32_e32 v221, 31, v220
	v_add_u32_e32 v216, 0xa0, v206
	v_lshl_add_u64 v[222:223], v[82:83], 0, v[84:85]
	v_lshlrev_b64 v[84:85], 9, v[220:221]
	v_ashrrev_i32_e32 v217, 31, v216
	v_add_u32_e32 v210, 0xb0, v206
	v_lshl_add_u64 v[218:219], v[82:83], 0, v[84:85]
	v_lshlrev_b64 v[84:85], 9, v[216:217]
	v_ashrrev_i32_e32 v211, 31, v210
	v_lshl_add_u64 v[214:215], v[82:83], 0, v[84:85]
	v_lshlrev_b64 v[84:85], 9, v[210:211]
	v_lshl_add_u64 v[208:209], v[82:83], 0, v[84:85]
	global_load_dwordx4 v[182:185], v[234:235], off
	global_load_dwordx4 v[178:181], v[234:235], off offset:64
	global_load_dwordx4 v[174:177], v[230:231], off
	global_load_dwordx4 v[170:173], v[230:231], off offset:64
	global_load_dwordx4 v[166:169], v[226:227], off
	global_load_dwordx4 v[154:157], v[226:227], off offset:64
	global_load_dwordx4 v[150:153], v[222:223], off
	global_load_dwordx4 v[146:149], v[222:223], off offset:64
	global_load_dwordx4 v[134:137], v[218:219], off
	global_load_dwordx4 v[130:133], v[218:219], off offset:64
	global_load_dwordx4 v[114:117], v[214:215], off
	global_load_dwordx4 v[106:109], v[214:215], off offset:64
	global_load_dwordx4 v[94:97], v[208:209], off
	global_load_dwordx4 v[82:85], v[208:209], off offset:64
	v_lshl_or_b32 v212, s18, 8, v250
	v_ashrrev_i32_e32 v213, 31, v212
	v_lshlrev_b64 v[240:241], 11, v[206:207]
	v_lshl_add_u64 v[240:241], v[240:241], 0, v[212:213]
	s_andn2_b64 vcc, exec, s[14:15]
	v_lshl_add_u64 v[240:241], v[240:241], 2, s[12:13]
	s_waitcnt vmcnt(0)
	v_lshlrev_b32_e32 v252, 16, v194
	v_and_b32_e32 v253, 0xffff0000, v194
	v_lshlrev_b32_e32 v194, 16, v195
	v_and_b32_e32 v195, 0xffff0000, v195
	v_pk_fma_f32 v[164:165], v[164:165], 0.5, v[194:195] op_sel_hi:[1,0,1]
	v_lshlrev_b32_e32 v194, 16, v196
	v_and_b32_e32 v195, 0xffff0000, v196
	v_pk_fma_f32 v[158:159], v[158:159], 0.5, v[194:195] op_sel_hi:[1,0,1]
	v_lshlrev_b32_e32 v194, 16, v197
	v_and_b32_e32 v195, 0xffff0000, v197
	v_pk_fma_f32 v[162:163], v[162:163], 0.5, v[252:253] op_sel_hi:[1,0,1]
	v_pk_fma_f32 v[160:161], v[160:161], 0.5, v[194:195] op_sel_hi:[1,0,1]
	v_cvt_pk_bf16_f32 v194, v162, v163
	v_cvt_pk_bf16_f32 v195, v164, v165
	v_cvt_pk_bf16_f32 v196, v158, v159
	s_nop 0
	v_cvt_pk_bf16_f32 v197, v160, v161
	global_store_dwordx4 v[238:239], v[194:197], off
	s_nop 1
	v_cndmask_b32_e64 v194, 0, 1, s[14:15]
	v_cmp_ne_u32_e64 s[8:9], 1, v194
	s_cbranch_vccnz .LBB0_321
	global_store_dwordx4 v[240:241], v[162:165], off
	global_store_dwordx4 v[240:241], v[158:161], off offset:16

; #define PG8_STAGE(bufoff, gbase, voff) do { _Pragma("unroll") for (int _i = 0; _i < 2; ++_i) \
;         __builtin_amdgcn_global_load_lds((const unsigned*)((const char*)(gbase) + (voff)[_i]), (LAS unsigned*)(lds + (bufoff) + ldsw + _i * 8192), 16, 0, 0); } while (0)
; #define PG8_LDA(dst, b, h) do { _Pragma("unroll") for (int m = 0; m < 4; ++m) _Pragma("unroll") for (int k = 0; k < 2; ++k) dst[m][k] = *(const LAS bf16x8*)(lds + PG8_SA(b, h) + aoff + m * 2048 + k * 1024); } while (0)
; #define PG8_LDB(dst, b, h) do { _Pragma("unroll") for (int n = 0; n < 2; ++n) _Pragma("unroll") for (int k = 0; k < 2; ++k) dst[n][k] = *(const LAS bf16x8*)(lds + PG8_SB(b, h) + boff + n * 2048 + k * 1024); } while (0)
; #define PG8_WAIT_V(n) asm volatile("s_waitcnt vmcnt(" #n ")" ::: "memory")
; #define PG8_WAIT_L(n) asm volatile("s_waitcnt lgkmcnt(" #n ")" ::: "memory")
; #define PG8_BAR __builtin_amdgcn_s_barrier()
; template <class Epi, class Sched, int KC, bool ALIGN_EPI = false, bool SP2 = false, bool ATILED = false>
; __device__ __forceinline__ void gemm_phase(LAS unsigned char* lds, const Gemm g, const Sched& S, const Epi& E, int wave_s) {
;     ...
;         const bool has_next = S.next(ui + 1, nxt);
;         const char* nA = has_next ? (const char*)g.A + (size_t)nxt.pm * tstepA : cA; const char* nB = has_next ? (const char*)g.Bt + (size_t)nxt.pn * tstep : cB;
;         for (int t = 0; t < nt; t += 2) {
;             const bool last = (t == nt - 2);
;             const char* a1 = cA + PG8_AOFF(t + 1);
;             const char* a2 = last ? nA : cA + PG8_AOFF(t + 2); const char* b2 = last ? nB : cB + (size_t)(t + 2) * kstep;
;             const char* a3 = a2 + kstep; const char* b3 = b2 + kstep;
;             if (last && has_next) S.a_ready(nxt);
;             if constexpr (SP2) {
;             PG8_LDB(B0, 0, 0); PG8_LDB(B1, 0, 1); PG8_SCHED; PG8_LDA(At, 0, 0); PG8_STAGE(PG8_SA(1, 1), a1 + hstepA, voffA);
;             PG8_WAIT_V(8); PG8_WAIT_L(0); PG8_BAR; PG8_MMA(0, 0, At, B0); PG8_MMA(0, 1, At, B1); PG8_BAR; PG8_SCHED;
;     ...
; #pragma unroll
;         for (int a = 0; a < 2; ++a)
; #pragma unroll
;             for (int b = 0; b < 2; ++b)
; #pragma unroll
;                 for (int m = 0; m < 4; ++m)
; #pragma unroll
;                     for (int n = 0; n < 2; ++n) acc[a][b][m][n] = (f32x4){0.f, 0.f, 0.f, 0.f};
;         cur = nxt; cA = nA; cB = nB; ++ui;
.LBB0_429:
	s_ashr_i32 s19, s18, 31
	s_lshl_b64 s[20:21], s[18:19], 17
	s_add_u32 s20, s42, s20
	s_addc_u32 s21, s43, s21
	s_and_b64 s[22:23], s[6:7], exec
	s_cselect_b32 s19, s21, s27
	s_cselect_b32 s61, s20, s26
	s_ashr_i32 s17, s16, 31
	s_lshl_b64 s[22:23], s[16:17], 20
	s_add_u32 s22, s44, s22
	s_addc_u32 s23, s45, s23
	s_and_b64 s[30:31], s[6:7], exec
	s_cselect_b32 s17, s23, s29
	s_cselect_b32 s62, s22, s28
	s_add_u32 s63, s28, 0x100
	v_mov_b32_e32 v2, 0
	s_addc_u32 s64, s29, 0
	s_mov_b32 s65, -2
	s_mov_b64 s[28:29], 0
	s_mov_b32 s66, 0x400000
	v_mov_b32_e32 v3, v2
	v_mov_b32_e32 v4, v2
	v_mov_b32_e32 v5, v2
	v_mov_b32_e32 v6, v2
	v_mov_b32_e32 v7, v2
	v_mov_b32_e32 v8, v2
	v_mov_b32_e32 v9, v2
	v_mov_b32_e32 v14, v2
	v_mov_b32_e32 v15, v2
	v_mov_b32_e32 v16, v2
	v_mov_b32_e32 v17, v2
	v_mov_b32_e32 v22, v2
	v_mov_b32_e32 v23, v2
	v_mov_b32_e32 v24, v2
	v_mov_b32_e32 v25, v2
	v_mov_b32_e32 v30, v2
	v_mov_b32_e32 v31, v2
	v_mov_b32_e32 v32, v2
	v_mov_b32_e32 v33, v2
	v_mov_b32_e32 v38, v2
	v_mov_b32_e32 v39, v2
	v_mov_b32_e32 v40, v2
	v_mov_b32_e32 v41, v2
	v_mov_b32_e32 v46, v2
	v_mov_b32_e32 v47, v2
	v_mov_b32_e32 v48, v2
	v_mov_b32_e32 v49, v2
	v_mov_b32_e32 v54, v2
	v_mov_b32_e32 v55, v2
	v_mov_b32_e32 v56, v2
	v_mov_b32_e32 v57, v2
	v_mov_b32_e32 v10, v2
	v_mov_b32_e32 v11, v2
	v_mov_b32_e32 v12, v2
	v_mov_b32_e32 v13, v2
	v_mov_b32_e32 v18, v2
	v_mov_b32_e32 v19, v2
	v_mov_b32_e32 v20, v2
	v_mov_b32_e32 v21, v2
	v_mov_b32_e32 v26, v2
	v_mov_b32_e32 v27, v2
	v_mov_b32_e32 v28, v2
	v_mov_b32_e32 v29, v2
	v_mov_b32_e32 v34, v2
	v_mov_b32_e32 v35, v2
	v_mov_b32_e32 v36, v2
	v_mov_b32_e32 v37, v2
	v_mov_b32_e32 v42, v2
	v_mov_b32_e32 v43, v2
	v_mov_b32_e32 v44, v2
	v_mov_b32_e32 v45, v2
	v_mov_b32_e32 v50, v2
	v_mov_b32_e32 v51, v2
	v_mov_b32_e32 v52, v2
	v_mov_b32_e32 v53, v2
	v_mov_b32_e32 v58, v2
	v_mov_b32_e32 v59, v2
	v_mov_b32_e32 v60, v2
	v_mov_b32_e32 v61, v2
	v_mov_b32_e32 v62, v2
	v_mov_b32_e32 v63, v2
	v_mov_b32_e32 v64, v2
	v_mov_b32_e32 v65, v2
	v_mov_b32_e32 v66, v2
	v_mov_b32_e32 v67, v2
	v_mov_b32_e32 v68, v2
	v_mov_b32_e32 v69, v2
	v_mov_b32_e32 v70, v2
	v_mov_b32_e32 v71, v2
	v_mov_b32_e32 v72, v2
	v_mov_b32_e32 v73, v2
	v_mov_b32_e32 v78, v2
	v_mov_b32_e32 v79, v2
	v_mov_b32_e32 v80, v2
	v_mov_b32_e32 v81, v2
	v_mov_b32_e32 v86, v2
	v_mov_b32_e32 v87, v2
	v_mov_b32_e32 v88, v2
	v_mov_b32_e32 v89, v2
	v_mov_b32_e32 v94, v2
	v_mov_b32_e32 v95, v2
	v_mov_b32_e32 v96, v2
	v_mov_b32_e32 v97, v2
	v_mov_b32_e32 v102, v2
	v_mov_b32_e32 v103, v2
	v_mov_b32_e32 v104, v2
	v_mov_b32_e32 v105, v2
	v_mov_b32_e32 v110, v2
	v_mov_b32_e32 v111, v2
	v_mov_b32_e32 v112, v2
	v_mov_b32_e32 v113, v2
	v_mov_b32_e32 v118, v2
	v_mov_b32_e32 v119, v2
	v_mov_b32_e32 v120, v2
	v_mov_b32_e32 v121, v2
	v_mov_b32_e32 v74, v2
	v_mov_b32_e32 v75, v2
	v_mov_b32_e32 v76, v2
	v_mov_b32_e32 v77, v2
	v_mov_b32_e32 v82, v2
	v_mov_b32_e32 v83, v2
	v_mov_b32_e32 v84, v2
	v_mov_b32_e32 v85, v2
	v_mov_b32_e32 v90, v2
	v_mov_b32_e32 v91, v2
	v_mov_b32_e32 v92, v2
	v_mov_b32_e32 v93, v2
	v_mov_b32_e32 v98, v2
	v_mov_b32_e32 v99, v2
	v_mov_b32_e32 v100, v2
	v_mov_b32_e32 v101, v2
	v_mov_b32_e32 v106, v2
	v_mov_b32_e32 v107, v2
	v_mov_b32_e32 v108, v2
	v_mov_b32_e32 v109, v2
	v_mov_b32_e32 v114, v2
	v_mov_b32_e32 v115, v2
	v_mov_b32_e32 v116, v2
	v_mov_b32_e32 v117, v2
	v_mov_b32_e32 v122, v2
	v_mov_b32_e32 v123, v2
	v_mov_b32_e32 v124, v2
	v_mov_b32_e32 v125, v2
	v_mov_b32_e32 v126, v2
	v_mov_b32_e32 v127, v2
	v_mov_b32_e32 v128, v2
	v_mov_b32_e32 v129, v2
	s_add_i32 s70, 0, 0x10000
	v_add_u32_e32 v139, s70, v165
	ds_read_b128 v[152:155], v139
	ds_read_b128 v[160:163], v139 offset:1024
	ds_read_b128 v[174:177], v139 offset:2048
	ds_read_b128 v[178:181], v139 offset:3072
	s_add_i32 s71, 0, 0x14000
	v_add_u32_e32 v139, s71, v165
	ds_read_b128 v[182:185], v139
	ds_read_b128 v[186:189], v139 offset:1024
	ds_read_b128 v[190:193], v139 offset:2048
	ds_read_b128 v[194:197], v139 offset:3072
	ds_read_b128 v[198:201], v173
	ds_read_b128 v[202:205], v173 offset:1024
	ds_read_b128 v[206:209], v173 offset:2048
	ds_read_b128 v[210:213], v173 offset:3072
	ds_read_b128 v[214:217], v173 offset:4096
	ds_read_b128 v[218:221], v173 offset:5120
	ds_read_b128 v[222:225], v173 offset:6144
	ds_read_b128 v[226:229], v173 offset:7168
	s_add_i32 s30, s66, 0xffc00000
	s_and_b32 s30, s30, 0x3800000
	s_and_b32 s31, s28, 0x100
	s_or_b32 s67, s31, s30
	s_and_b32 s34, s66, 0x7800000
	s_add_u32 s30, s28, 0x100
	s_addc_u32 s31, s29, 0
	s_and_b32 s35, s30, 0x100
	s_or_b32 s34, s34, s35
	s_add_u32 s34, s26, s34
	s_addc_u32 s35, s27, 0
	s_add_u32 s28, s63, s28
	s_addc_u32 s29, s64, s29
	s_cmp_eq_u32 s65, 28
	s_cselect_b32 s35, s19, s35
	s_cselect_b32 s34, s61, s34
	s_cselect_b32 s29, s17, s29
	s_cselect_b32 s28, s62, s28
	s_add_u32 s67, s26, s67
	s_addc_u32 s69, s27, 0
	s_add_u32 s68, s67, 0x10080
	s_addc_u32 s69, s69, 0
	s_add_i32 m0, s25, 0xc000
	s_nop 0
	global_load_lds_dwordx4 v136, s[68:69]
	s_add_i32 m0, s25, 0xe000
	s_nop 0
	global_load_lds_dwordx4 v132, s[68:69]
	s_waitcnt vmcnt(24)
	s_waitcnt lgkmcnt(0)
	s_barrier
; #define PG8_STAGE(bufoff, gbase, voff) do { _Pragma("unroll") for (int _i = 0; _i < 2; ++_i) \
;         __builtin_amdgcn_global_load_lds((const unsigned*)((const char*)(gbase) + (voff)[_i]), (LAS unsigned*)(lds + (bufoff) + ldsw + _i * 8192), 16, 0, 0); } while (0)
; #define PG8_LDA(dst, b, h) do { _Pragma("unroll") for (int m = 0; m < 4; ++m) _Pragma("unroll") for (int k = 0; k < 2; ++k) dst[m][k] = *(const LAS bf16x8*)(lds + PG8_SA(b, h) + aoff + m * 2048 + k * 1024); } while (0)
; #define PG8_MMA(ai, bj, At, Bt) do { __builtin_amdgcn_s_setprio(1); _Pragma("unroll") for (int m = 0; m < 4; ++m) _Pragma("unroll") for (int n = 0; n < 2; ++n) _Pragma("unroll") for (int k = 0; k < 2; ++k) \
;         acc[ai][bj][m][n] = __builtin_amdgcn_mfma_f32_16x16x32_bf16(Bt[n][k], At[m][k], acc[ai][bj][m][n], 0, 0, 0); __builtin_amdgcn_s_setprio(0); } while (0)
; #define PG8_WAIT_V(n) asm volatile("s_waitcnt vmcnt(" #n ")" ::: "memory")
; #define PG8_WAIT_L(n) asm volatile("s_waitcnt lgkmcnt(" #n ")" ::: "memory")
; #define PG8_BAR __builtin_amdgcn_s_barrier()
; #define PG8_SCHED __builtin_amdgcn_sched_barrier(0)
; template <class Epi, class Sched, int KC, bool ALIGN_EPI = false, bool SP2 = false, bool ATILED = false>
; __device__ __forceinline__ void gemm_phase(LAS unsigned char* lds, const Gemm g, const Sched& S, const Epi& E, int wave_s) {
;     ...
;             PG8_WAIT_V(8); PG8_WAIT_L(0); PG8_BAR; PG8_MMA(0, 0, At, B0); PG8_MMA(0, 1, At, B1); PG8_BAR; PG8_SCHED;
;             PG8_LDA(At, 0, 1); PG8_STAGE(PG8_SB(0, 0), b2, voffB); PG8_STAGE(PG8_SB(0, 1), b2 + hstepB, voffB); PG8_STAGE(PG8_SA(0, 0), a2, voffA);
;             PG8_WAIT_V(8); PG8_WAIT_L(0); PG8_BAR; PG8_MMA(1, 0, At, B0); PG8_MMA(1, 1, At, B1); PG8_BAR; PG8_SCHED;
	s_waitcnt lgkmcnt(0)
	v_mfma_f32_16x16x32_bf16 v[126:129], v[152:155], v[198:201], v[126:129]
	v_mfma_f32_16x16x32_bf16 v[122:125], v[174:177], v[198:201], v[122:125]
	v_mfma_f32_16x16x32_bf16 v[114:117], v[152:155], v[206:209], v[114:117]
	v_mfma_f32_16x16x32_bf16 v[106:109], v[174:177], v[206:209], v[106:109]
	v_mfma_f32_16x16x32_bf16 v[98:101], v[152:155], v[214:217], v[98:101]
	v_mfma_f32_16x16x32_bf16 v[90:93], v[174:177], v[214:217], v[90:93]
	v_mfma_f32_16x16x32_bf16 v[82:85], v[152:155], v[222:225], v[82:85]
	v_mfma_f32_16x16x32_bf16 v[74:77], v[174:177], v[222:225], v[74:77]
	v_mfma_f32_16x16x32_bf16 v[126:129], v[160:163], v[202:205], v[126:129]
	v_mfma_f32_16x16x32_bf16 v[122:125], v[178:181], v[202:205], v[122:125]
	v_mfma_f32_16x16x32_bf16 v[114:117], v[160:163], v[210:213], v[114:117]
	v_mfma_f32_16x16x32_bf16 v[106:109], v[178:181], v[210:213], v[106:109]
	v_mfma_f32_16x16x32_bf16 v[98:101], v[160:163], v[218:221], v[98:101]
	v_mfma_f32_16x16x32_bf16 v[90:93], v[178:181], v[218:221], v[90:93]
	v_mfma_f32_16x16x32_bf16 v[82:85], v[160:163], v[226:229], v[82:85]
	v_mfma_f32_16x16x32_bf16 v[74:77], v[178:181], v[226:229], v[74:77]
	v_mfma_f32_16x16x32_bf16 v[118:121], v[182:185], v[198:201], v[118:121]
	v_mfma_f32_16x16x32_bf16 v[110:113], v[190:193], v[198:201], v[110:113]
	v_mfma_f32_16x16x32_bf16 v[102:105], v[182:185], v[206:209], v[102:105]
	v_mfma_f32_16x16x32_bf16 v[94:97], v[190:193], v[206:209], v[94:97]
	v_mfma_f32_16x16x32_bf16 v[86:89], v[182:185], v[214:217], v[86:89]
	v_mfma_f32_16x16x32_bf16 v[78:81], v[190:193], v[214:217], v[78:81]
	v_mfma_f32_16x16x32_bf16 v[70:73], v[182:185], v[222:225], v[70:73]
	v_mfma_f32_16x16x32_bf16 v[66:69], v[190:193], v[222:225], v[66:69]
	v_mfma_f32_16x16x32_bf16 v[118:121], v[186:189], v[202:205], v[118:121]
	v_mfma_f32_16x16x32_bf16 v[110:113], v[194:197], v[202:205], v[110:113]
	v_mfma_f32_16x16x32_bf16 v[102:105], v[186:189], v[210:213], v[102:105]
	v_mfma_f32_16x16x32_bf16 v[94:97], v[194:197], v[210:213], v[94:97]
	v_mfma_f32_16x16x32_bf16 v[86:89], v[186:189], v[218:221], v[86:89]
	v_mfma_f32_16x16x32_bf16 v[78:81], v[194:197], v[218:221], v[78:81]
	v_mfma_f32_16x16x32_bf16 v[70:73], v[186:189], v[226:229], v[70:73]
	v_mfma_f32_16x16x32_bf16 v[66:69], v[194:197], v[226:229], v[66:69]
	s_barrier
	ds_read_b128 v[198:201], v173 offset:16384
	ds_read_b128 v[202:205], v173 offset:17408
	ds_read_b128 v[206:209], v173 offset:18432
	ds_read_b128 v[210:213], v173 offset:19456
	ds_read_b128 v[214:217], v173 offset:20480
	ds_read_b128 v[218:221], v173 offset:21504
	ds_read_b128 v[222:225], v173 offset:22528
	ds_read_b128 v[226:229], v173 offset:23552
	s_add_u32 s100, s34, 0x80
	s_addc_u32 s101, s35, 0
	s_add_i32 s67, s70, s41
	s_mov_b32 m0, s67
	s_nop 0
	global_load_lds_dwordx4 v134, s[28:29]
	s_add_i32 m0, s67, 0x2000
	s_add_u32 s68, s28, 0x80000
	s_addc_u32 s69, s29, 0
	s_add_i32 s67, s71, s41
	global_load_lds_dwordx4 v130, s[28:29]
	s_mov_b32 m0, s67
	s_nop 0
	global_load_lds_dwordx4 v134, s[68:69]
	s_add_i32 m0, s67, 0x2000
	s_nop 0
	global_load_lds_dwordx4 v130, s[68:69]
	s_mov_b32 m0, s25
	s_nop 0
	global_load_lds_dwordx4 v136, s[34:35]
	s_mov_b32 m0, s52
	s_nop 0
	global_load_lds_dwordx4 v132, s[34:35]
	s_waitcnt vmcnt(24)
	s_waitcnt lgkmcnt(0)
	s_barrier
	s_waitcnt lgkmcnt(0)
	v_mfma_f32_16x16x32_bf16 v[62:65], v[152:155], v[198:201], v[62:65]
	v_mfma_f32_16x16x32_bf16 v[58:61], v[174:177], v[198:201], v[58:61]
	v_mfma_f32_16x16x32_bf16 v[50:53], v[152:155], v[206:209], v[50:53]
	v_mfma_f32_16x16x32_bf16 v[42:45], v[174:177], v[206:209], v[42:45]
	v_mfma_f32_16x16x32_bf16 v[34:37], v[152:155], v[214:217], v[34:37]
	v_mfma_f32_16x16x32_bf16 v[26:29], v[174:177], v[214:217], v[26:29]
	v_mfma_f32_16x16x32_bf16 v[18:21], v[152:155], v[222:225], v[18:21]
	v_mfma_f32_16x16x32_bf16 v[10:13], v[174:177], v[222:225], v[10:13]
	v_mfma_f32_16x16x32_bf16 v[62:65], v[160:163], v[202:205], v[62:65]
	v_mfma_f32_16x16x32_bf16 v[58:61], v[178:181], v[202:205], v[58:61]
	v_mfma_f32_16x16x32_bf16 v[50:53], v[160:163], v[210:213], v[50:53]
	v_mfma_f32_16x16x32_bf16 v[42:45], v[178:181], v[210:213], v[42:45]
	v_mfma_f32_16x16x32_bf16 v[34:37], v[160:163], v[218:221], v[34:37]
	v_mfma_f32_16x16x32_bf16 v[26:29], v[178:181], v[218:221], v[26:29]
	v_mfma_f32_16x16x32_bf16 v[18:21], v[160:163], v[226:229], v[18:21]
	v_mfma_f32_16x16x32_bf16 v[10:13], v[178:181], v[226:229], v[10:13]
	v_mfma_f32_16x16x32_bf16 v[54:57], v[182:185], v[198:201], v[54:57]
	v_mfma_f32_16x16x32_bf16 v[46:49], v[190:193], v[198:201], v[46:49]
	v_mfma_f32_16x16x32_bf16 v[38:41], v[182:185], v[206:209], v[38:41]
	v_mfma_f32_16x16x32_bf16 v[30:33], v[190:193], v[206:209], v[30:33]
	v_mfma_f32_16x16x32_bf16 v[22:25], v[182:185], v[214:217], v[22:25]
	v_mfma_f32_16x16x32_bf16 v[14:17], v[190:193], v[214:217], v[14:17]
	v_mfma_f32_16x16x32_bf16 v[6:9], v[182:185], v[222:225], v[6:9]
	v_mfma_f32_16x16x32_bf16 v[2:5], v[190:193], v[222:225], v[2:5]
	v_mfma_f32_16x16x32_bf16 v[54:57], v[186:189], v[202:205], v[54:57]
	v_mfma_f32_16x16x32_bf16 v[46:49], v[194:197], v[202:205], v[46:49]
	v_mfma_f32_16x16x32_bf16 v[38:41], v[186:189], v[210:213], v[38:41]
	v_mfma_f32_16x16x32_bf16 v[30:33], v[194:197], v[210:213], v[30:33]
	v_mfma_f32_16x16x32_bf16 v[22:25], v[186:189], v[218:221], v[22:25]
	v_mfma_f32_16x16x32_bf16 v[14:17], v[194:197], v[218:221], v[14:17]
	v_mfma_f32_16x16x32_bf16 v[6:9], v[186:189], v[226:229], v[6:9]
	v_mfma_f32_16x16x32_bf16 v[2:5], v[194:197], v[226:229], v[2:5]
	s_barrier
; #define PG8_STAGE(bufoff, gbase, voff) do { _Pragma("unroll") for (int _i = 0; _i < 2; ++_i) \
;         __builtin_amdgcn_global_load_lds((const unsigned*)((const char*)(gbase) + (voff)[_i]), (LAS unsigned*)(lds + (bufoff) + ldsw + _i * 8192), 16, 0, 0); } while (0)
; #define PG8_LDA(dst, b, h) do { _Pragma("unroll") for (int m = 0; m < 4; ++m) _Pragma("unroll") for (int k = 0; k < 2; ++k) dst[m][k] = *(const LAS bf16x8*)(lds + PG8_SA(b, h) + aoff + m * 2048 + k * 1024); } while (0)
; #define PG8_LDB(dst, b, h) do { _Pragma("unroll") for (int n = 0; n < 2; ++n) _Pragma("unroll") for (int k = 0; k < 2; ++k) dst[n][k] = *(const LAS bf16x8*)(lds + PG8_SB(b, h) + boff + n * 2048 + k * 1024); } while (0)
; #define PG8_MMA(ai, bj, At, Bt) do { __builtin_amdgcn_s_setprio(1); _Pragma("unroll") for (int m = 0; m < 4; ++m) _Pragma("unroll") for (int n = 0; n < 2; ++n) _Pragma("unroll") for (int k = 0; k < 2; ++k) \
;         acc[ai][bj][m][n] = __builtin_amdgcn_mfma_f32_16x16x32_bf16(Bt[n][k], At[m][k], acc[ai][bj][m][n], 0, 0, 0); __builtin_amdgcn_s_setprio(0); } while (0)
; #define PG8_WAIT_V(n) asm volatile("s_waitcnt vmcnt(" #n ")" ::: "memory")
; #define PG8_WAIT_L(n) asm volatile("s_waitcnt lgkmcnt(" #n ")" ::: "memory")
; #define PG8_BAR __builtin_amdgcn_s_barrier()
; #define PG8_SCHED __builtin_amdgcn_sched_barrier(0)
; template <class Epi, class Sched, int KC, bool ALIGN_EPI = false, bool SP2 = false, bool ATILED = false>
; __device__ __forceinline__ void gemm_phase(LAS unsigned char* lds, const Gemm g, const Sched& S, const Epi& E, int wave_s) {
;     ...
;             PG8_LDB(B0, 1, 0); PG8_LDB(B1, 1, 1); PG8_SCHED; PG8_LDA(At, 1, 0); PG8_STAGE(PG8_SA(0, 1), a2 + hstepA, voffA);
;             PG8_WAIT_V(8); PG8_WAIT_L(0); PG8_BAR; PG8_MMA(0, 0, At, B0); PG8_MMA(0, 1, At, B1); PG8_BAR; PG8_SCHED;
;             PG8_LDA(At, 1, 1); PG8_STAGE(PG8_SB(1, 0), b3, voffB); PG8_STAGE(PG8_SB(1, 1), b3 + hstepB, voffB); PG8_STAGE(PG8_SA(1, 0), a3, voffA);
;             PG8_WAIT_V(8); PG8_WAIT_L(0); PG8_BAR; PG8_MMA(1, 0, At, B0); PG8_MMA(1, 1, At, B1); PG8_BAR; PG8_SCHED;
	s_add_i32 s67, 0, 0x18000
	v_add_u32_e32 v139, s67, v165
	ds_read_b128 v[152:155], v139
	ds_read_b128 v[160:163], v139 offset:1024
	ds_read_b128 v[174:177], v139 offset:2048
	ds_read_b128 v[178:181], v139 offset:3072
	s_add_i32 s68, 0, 0x1c000
	v_add_u32_e32 v139, s68, v165
	ds_read_b128 v[182:185], v139
	ds_read_b128 v[186:189], v139 offset:1024
	ds_read_b128 v[190:193], v139 offset:2048
	ds_read_b128 v[194:197], v139 offset:3072
	ds_read_b128 v[198:201], v173 offset:32768
	ds_read_b128 v[202:205], v173 offset:33792
	ds_read_b128 v[206:209], v173 offset:34816
	ds_read_b128 v[210:213], v173 offset:35840
	ds_read_b128 v[214:217], v173 offset:36864
	ds_read_b128 v[218:221], v173 offset:37888
	ds_read_b128 v[222:225], v173 offset:38912
	ds_read_b128 v[226:229], v173 offset:39936
	s_add_u32 s34, s34, 0x10000
	s_addc_u32 s35, s35, 0
	s_mov_b32 m0, s53
	s_nop 0
	global_load_lds_dwordx4 v136, s[34:35]
	s_mov_b32 m0, s54
	s_nop 0
	global_load_lds_dwordx4 v132, s[34:35]
	s_waitcnt vmcnt(8)
	s_waitcnt lgkmcnt(0)
	s_barrier
	s_waitcnt lgkmcnt(0)
	v_mfma_f32_16x16x32_bf16 v[126:129], v[152:155], v[198:201], v[126:129]
	v_mfma_f32_16x16x32_bf16 v[122:125], v[174:177], v[198:201], v[122:125]
	v_mfma_f32_16x16x32_bf16 v[114:117], v[152:155], v[206:209], v[114:117]
	v_mfma_f32_16x16x32_bf16 v[106:109], v[174:177], v[206:209], v[106:109]
	v_mfma_f32_16x16x32_bf16 v[98:101], v[152:155], v[214:217], v[98:101]
	v_mfma_f32_16x16x32_bf16 v[90:93], v[174:177], v[214:217], v[90:93]
	v_mfma_f32_16x16x32_bf16 v[82:85], v[152:155], v[222:225], v[82:85]
	v_mfma_f32_16x16x32_bf16 v[74:77], v[174:177], v[222:225], v[74:77]
	v_mfma_f32_16x16x32_bf16 v[126:129], v[160:163], v[202:205], v[126:129]
	v_mfma_f32_16x16x32_bf16 v[122:125], v[178:181], v[202:205], v[122:125]
	v_mfma_f32_16x16x32_bf16 v[114:117], v[160:163], v[210:213], v[114:117]
	v_mfma_f32_16x16x32_bf16 v[106:109], v[178:181], v[210:213], v[106:109]
	v_mfma_f32_16x16x32_bf16 v[98:101], v[160:163], v[218:221], v[98:101]
	v_mfma_f32_16x16x32_bf16 v[90:93], v[178:181], v[218:221], v[90:93]
	v_mfma_f32_16x16x32_bf16 v[82:85], v[160:163], v[226:229], v[82:85]
	v_mfma_f32_16x16x32_bf16 v[74:77], v[178:181], v[226:229], v[74:77]
	v_mfma_f32_16x16x32_bf16 v[118:121], v[182:185], v[198:201], v[118:121]
	v_mfma_f32_16x16x32_bf16 v[110:113], v[190:193], v[198:201], v[110:113]
	v_mfma_f32_16x16x32_bf16 v[102:105], v[182:185], v[206:209], v[102:105]
	v_mfma_f32_16x16x32_bf16 v[94:97], v[190:193], v[206:209], v[94:97]
	v_mfma_f32_16x16x32_bf16 v[86:89], v[182:185], v[214:217], v[86:89]
	v_mfma_f32_16x16x32_bf16 v[78:81], v[190:193], v[214:217], v[78:81]
	v_mfma_f32_16x16x32_bf16 v[70:73], v[182:185], v[222:225], v[70:73]
	v_mfma_f32_16x16x32_bf16 v[66:69], v[190:193], v[222:225], v[66:69]
	v_mfma_f32_16x16x32_bf16 v[118:121], v[186:189], v[202:205], v[118:121]
	v_mfma_f32_16x16x32_bf16 v[110:113], v[194:197], v[202:205], v[110:113]
	v_mfma_f32_16x16x32_bf16 v[102:105], v[186:189], v[210:213], v[102:105]
	v_mfma_f32_16x16x32_bf16 v[94:97], v[194:197], v[210:213], v[94:97]
	v_mfma_f32_16x16x32_bf16 v[86:89], v[186:189], v[218:221], v[86:89]
	v_mfma_f32_16x16x32_bf16 v[78:81], v[194:197], v[218:221], v[78:81]
	v_mfma_f32_16x16x32_bf16 v[70:73], v[186:189], v[226:229], v[70:73]
	v_mfma_f32_16x16x32_bf16 v[66:69], v[194:197], v[226:229], v[66:69]
	s_barrier
	ds_read_b128 v[198:201], v173 offset:49152
	ds_read_b128 v[202:205], v173 offset:50176
	ds_read_b128 v[206:209], v173 offset:51200
	ds_read_b128 v[210:213], v173 offset:52224
	ds_read_b128 v[214:217], v173 offset:53248
	ds_read_b128 v[218:221], v173 offset:54272
	ds_read_b128 v[222:225], v173 offset:55296
	ds_read_b128 v[226:229], v173 offset:56320
	s_add_u32 s98, s28, 0x80
	s_addc_u32 s99, s29, 0
	s_add_i32 s34, s67, s41
	s_mov_b32 m0, s34
	s_nop 0
	global_load_lds_dwordx4 v134, s[98:99]
	s_add_i32 m0, s34, 0x2000
	s_add_u32 s28, s28, 0x80080
	s_addc_u32 s29, s29, 0
	s_add_i32 s34, s68, s41
	global_load_lds_dwordx4 v130, s[98:99]
	s_mov_b32 m0, s34
	s_nop 0
	global_load_lds_dwordx4 v134, s[28:29]
	s_add_i32 m0, s34, 0x2000
	s_nop 0
	global_load_lds_dwordx4 v130, s[28:29]
	s_mov_b32 m0, s55
	s_nop 0
	global_load_lds_dwordx4 v136, s[100:101]
	s_mov_b32 m0, s56
	s_nop 0
	global_load_lds_dwordx4 v132, s[100:101]
	s_waitcnt vmcnt(8)
	s_waitcnt lgkmcnt(0)
	s_barrier
	s_waitcnt lgkmcnt(0)
	v_mfma_f32_16x16x32_bf16 v[62:65], v[152:155], v[198:201], v[62:65]
	v_mfma_f32_16x16x32_bf16 v[58:61], v[174:177], v[198:201], v[58:61]
	v_mfma_f32_16x16x32_bf16 v[50:53], v[152:155], v[206:209], v[50:53]
	v_mfma_f32_16x16x32_bf16 v[42:45], v[174:177], v[206:209], v[42:45]
	v_mfma_f32_16x16x32_bf16 v[34:37], v[152:155], v[214:217], v[34:37]
	v_mfma_f32_16x16x32_bf16 v[26:29], v[174:177], v[214:217], v[26:29]
	v_mfma_f32_16x16x32_bf16 v[18:21], v[152:155], v[222:225], v[18:21]
	v_mfma_f32_16x16x32_bf16 v[10:13], v[174:177], v[222:225], v[10:13]
	v_mfma_f32_16x16x32_bf16 v[62:65], v[160:163], v[202:205], v[62:65]
	v_mfma_f32_16x16x32_bf16 v[58:61], v[178:181], v[202:205], v[58:61]
	v_mfma_f32_16x16x32_bf16 v[50:53], v[160:163], v[210:213], v[50:53]
	v_mfma_f32_16x16x32_bf16 v[42:45], v[178:181], v[210:213], v[42:45]
	v_mfma_f32_16x16x32_bf16 v[34:37], v[160:163], v[218:221], v[34:37]
	v_mfma_f32_16x16x32_bf16 v[26:29], v[178:181], v[218:221], v[26:29]
	v_mfma_f32_16x16x32_bf16 v[18:21], v[160:163], v[226:229], v[18:21]
	v_mfma_f32_16x16x32_bf16 v[10:13], v[178:181], v[226:229], v[10:13]
	v_mfma_f32_16x16x32_bf16 v[54:57], v[182:185], v[198:201], v[54:57]
	v_mfma_f32_16x16x32_bf16 v[46:49], v[190:193], v[198:201], v[46:49]
	v_mfma_f32_16x16x32_bf16 v[38:41], v[182:185], v[206:209], v[38:41]
	v_mfma_f32_16x16x32_bf16 v[30:33], v[190:193], v[206:209], v[30:33]
	v_mfma_f32_16x16x32_bf16 v[22:25], v[182:185], v[214:217], v[22:25]
	v_mfma_f32_16x16x32_bf16 v[14:17], v[190:193], v[214:217], v[14:17]
	v_mfma_f32_16x16x32_bf16 v[6:9], v[182:185], v[222:225], v[6:9]
	v_mfma_f32_16x16x32_bf16 v[2:5], v[190:193], v[222:225], v[2:5]
	v_mfma_f32_16x16x32_bf16 v[54:57], v[186:189], v[202:205], v[54:57]
	v_mfma_f32_16x16x32_bf16 v[46:49], v[194:197], v[202:205], v[46:49]
	v_mfma_f32_16x16x32_bf16 v[38:41], v[186:189], v[210:213], v[38:41]
	v_mfma_f32_16x16x32_bf16 v[30:33], v[194:197], v[210:213], v[30:33]
	v_mfma_f32_16x16x32_bf16 v[22:25], v[186:189], v[218:221], v[22:25]
	v_mfma_f32_16x16x32_bf16 v[14:17], v[194:197], v[218:221], v[14:17]
	v_mfma_f32_16x16x32_bf16 v[6:9], v[186:189], v[226:229], v[6:9]
	v_mfma_f32_16x16x32_bf16 v[2:5], v[194:197], v[226:229], v[2:5]
	s_barrier
	s_add_i32 s65, s65, 2
	s_add_i32 s66, s66, 0x400000
	s_cmp_gt_u32 s65, 29
	s_mov_b64 s[28:29], s[30:31]
; #define PG8_STAGE(bufoff, gbase, voff) do { _Pragma("unroll") for (int _i = 0; _i < 2; ++_i) \
;         __builtin_amdgcn_global_load_lds((const unsigned*)((const char*)(gbase) + (voff)[_i]), (LAS unsigned*)(lds + (bufoff) + ldsw + _i * 8192), 16, 0, 0); } while (0)
; #define PG8_LDA(dst, b, h) do { _Pragma("unroll") for (int m = 0; m < 4; ++m) _Pragma("unroll") for (int k = 0; k < 2; ++k) dst[m][k] = *(const LAS bf16x8*)(lds + PG8_SA(b, h) + aoff + m * 2048 + k * 1024); } while (0)
; #define PG8_LDB(dst, b, h) do { _Pragma("unroll") for (int n = 0; n < 2; ++n) _Pragma("unroll") for (int k = 0; k < 2; ++k) dst[n][k] = *(const LAS bf16x8*)(lds + PG8_SB(b, h) + boff + n * 2048 + k * 1024); } while (0)
; #define PG8_MMA(ai, bj, At, Bt) do { __builtin_amdgcn_s_setprio(1); _Pragma("unroll") for (int m = 0; m < 4; ++m) _Pragma("unroll") for (int n = 0; n < 2; ++n) _Pragma("unroll") for (int k = 0; k < 2; ++k) \
;         acc[ai][bj][m][n] = __builtin_amdgcn_mfma_f32_16x16x32_bf16(Bt[n][k], At[m][k], acc[ai][bj][m][n], 0, 0, 0); __builtin_amdgcn_s_setprio(0); } while (0)
; #define PG8_WAIT_V(n) asm volatile("s_waitcnt vmcnt(" #n ")" ::: "memory")
; #define PG8_WAIT_L(n) asm volatile("s_waitcnt lgkmcnt(" #n ")" ::: "memory")
; #define PG8_BAR __builtin_amdgcn_s_barrier()
; #define PG8_SCHED __builtin_amdgcn_sched_barrier(0)
; template <class Epi, class Sched, int KC, bool ALIGN_EPI = false, bool SP2 = false, bool ATILED = false>
; __device__ __forceinline__ void gemm_phase(LAS unsigned char* lds, const Gemm g, const Sched& S, const Epi& E, int wave_s) {
;     ...
;             const bool last = (t == nt - 2);
;             const char* a1 = cA + PG8_AOFF(t + 1);
;             const char* a2 = last ? nA : cA + PG8_AOFF(t + 2); const char* b2 = last ? nB : cB + (size_t)(t + 2) * kstep;
;             const char* a3 = a2 + kstep; const char* b3 = b2 + kstep;
;             if (last && has_next) S.a_ready(nxt);
;             if constexpr (SP2) {
;             PG8_LDB(B0, 0, 0); PG8_LDB(B1, 0, 1); PG8_SCHED; PG8_LDA(At, 0, 0); PG8_STAGE(PG8_SA(1, 1), a1 + hstepA, voffA);
;             PG8_WAIT_V(8); PG8_WAIT_L(0); PG8_BAR; PG8_MMA(0, 0, At, B0); PG8_MMA(0, 1, At, B1); PG8_BAR; PG8_SCHED;
;             PG8_LDA(At, 0, 1); PG8_STAGE(PG8_SB(0, 0), b2, voffB); PG8_STAGE(PG8_SB(0, 1), b2 + hstepB, voffB); PG8_STAGE(PG8_SA(0, 0), a2, voffA);
.LBB0_430:
	s_add_i32 s70, 0, 0x10000
	v_add_u32_e32 v139, s70, v165
	ds_read_b128 v[152:155], v139
	ds_read_b128 v[160:163], v139 offset:1024
	ds_read_b128 v[174:177], v139 offset:2048
	ds_read_b128 v[178:181], v139 offset:3072
	s_add_i32 s71, 0, 0x14000
	v_add_u32_e32 v139, s71, v165
	ds_read_b128 v[182:185], v139
	ds_read_b128 v[186:189], v139 offset:1024
	ds_read_b128 v[190:193], v139 offset:2048
	ds_read_b128 v[194:197], v139 offset:3072
	ds_read_b128 v[198:201], v173
	ds_read_b128 v[202:205], v173 offset:1024
	ds_read_b128 v[206:209], v173 offset:2048
	ds_read_b128 v[210:213], v173 offset:3072
	ds_read_b128 v[214:217], v173 offset:4096
	ds_read_b128 v[218:221], v173 offset:5120
	ds_read_b128 v[222:225], v173 offset:6144
	ds_read_b128 v[226:229], v173 offset:7168
	s_add_i32 s30, s66, 0xffc00000
	s_and_b32 s30, s30, 0x3800000
	s_and_b32 s31, s28, 0x100
	s_or_b32 s67, s31, s30
	s_and_b32 s34, s66, 0x7800000
	s_add_u32 s30, s28, 0x100
	s_addc_u32 s31, s29, 0
	s_and_b32 s35, s30, 0x100
	s_or_b32 s34, s34, s35
	s_add_u32 s34, s26, s34
	s_addc_u32 s35, s27, 0
	s_add_u32 s28, s63, s28
	s_addc_u32 s29, s64, s29
	s_cmp_eq_u32 s65, 28
	s_cselect_b32 s35, s19, s35
	s_cselect_b32 s34, s61, s34
	s_cselect_b32 s29, s17, s29
	s_cselect_b32 s28, s62, s28
	s_add_u32 s67, s26, s67
	s_addc_u32 s69, s27, 0
	s_add_u32 s68, s67, 0x10080
	s_addc_u32 s69, s69, 0
	s_add_i32 m0, s25, 0xc000
	s_nop 0
	global_load_lds_dwordx4 v136, s[68:69]
	s_add_i32 m0, s25, 0xe000
	s_nop 0
	global_load_lds_dwordx4 v132, s[68:69]
	s_waitcnt vmcnt(8)
	s_waitcnt lgkmcnt(0)
	s_barrier
	s_waitcnt lgkmcnt(0)
	v_mfma_f32_16x16x32_bf16 v[126:129], v[152:155], v[198:201], v[126:129]
	v_mfma_f32_16x16x32_bf16 v[122:125], v[174:177], v[198:201], v[122:125]
	v_mfma_f32_16x16x32_bf16 v[114:117], v[152:155], v[206:209], v[114:117]
	v_mfma_f32_16x16x32_bf16 v[106:109], v[174:177], v[206:209], v[106:109]
	v_mfma_f32_16x16x32_bf16 v[98:101], v[152:155], v[214:217], v[98:101]
	v_mfma_f32_16x16x32_bf16 v[90:93], v[174:177], v[214:217], v[90:93]
	v_mfma_f32_16x16x32_bf16 v[82:85], v[152:155], v[222:225], v[82:85]
	v_mfma_f32_16x16x32_bf16 v[74:77], v[174:177], v[222:225], v[74:77]
	v_mfma_f32_16x16x32_bf16 v[126:129], v[160:163], v[202:205], v[126:129]
	v_mfma_f32_16x16x32_bf16 v[122:125], v[178:181], v[202:205], v[122:125]
	v_mfma_f32_16x16x32_bf16 v[114:117], v[160:163], v[210:213], v[114:117]
	v_mfma_f32_16x16x32_bf16 v[106:109], v[178:181], v[210:213], v[106:109]
	v_mfma_f32_16x16x32_bf16 v[98:101], v[160:163], v[218:221], v[98:101]
	v_mfma_f32_16x16x32_bf16 v[90:93], v[178:181], v[218:221], v[90:93]
	v_mfma_f32_16x16x32_bf16 v[82:85], v[160:163], v[226:229], v[82:85]
	v_mfma_f32_16x16x32_bf16 v[74:77], v[178:181], v[226:229], v[74:77]
	v_mfma_f32_16x16x32_bf16 v[118:121], v[182:185], v[198:201], v[118:121]
	v_mfma_f32_16x16x32_bf16 v[110:113], v[190:193], v[198:201], v[110:113]
	v_mfma_f32_16x16x32_bf16 v[102:105], v[182:185], v[206:209], v[102:105]
	v_mfma_f32_16x16x32_bf16 v[94:97], v[190:193], v[206:209], v[94:97]
	v_mfma_f32_16x16x32_bf16 v[86:89], v[182:185], v[214:217], v[86:89]
	v_mfma_f32_16x16x32_bf16 v[78:81], v[190:193], v[214:217], v[78:81]
	v_mfma_f32_16x16x32_bf16 v[70:73], v[182:185], v[222:225], v[70:73]
	v_mfma_f32_16x16x32_bf16 v[66:69], v[190:193], v[222:225], v[66:69]
	v_mfma_f32_16x16x32_bf16 v[118:121], v[186:189], v[202:205], v[118:121]
	v_mfma_f32_16x16x32_bf16 v[110:113], v[194:197], v[202:205], v[110:113]
	v_mfma_f32_16x16x32_bf16 v[102:105], v[186:189], v[210:213], v[102:105]
	v_mfma_f32_16x16x32_bf16 v[94:97], v[194:197], v[210:213], v[94:97]
	v_mfma_f32_16x16x32_bf16 v[86:89], v[186:189], v[218:221], v[86:89]
	v_mfma_f32_16x16x32_bf16 v[78:81], v[194:197], v[218:221], v[78:81]
	v_mfma_f32_16x16x32_bf16 v[70:73], v[186:189], v[226:229], v[70:73]
	v_mfma_f32_16x16x32_bf16 v[66:69], v[194:197], v[226:229], v[66:69]
	s_barrier
	ds_read_b128 v[198:201], v173 offset:16384
	ds_read_b128 v[202:205], v173 offset:17408
	ds_read_b128 v[206:209], v173 offset:18432
	ds_read_b128 v[210:213], v173 offset:19456
	ds_read_b128 v[214:217], v173 offset:20480
	ds_read_b128 v[218:221], v173 offset:21504
	ds_read_b128 v[222:225], v173 offset:22528
	ds_read_b128 v[226:229], v173 offset:23552
	s_add_u32 s100, s34, 0x80
	s_addc_u32 s101, s35, 0
	s_add_i32 s67, s70, s41
	s_mov_b32 m0, s67
	s_nop 0
	global_load_lds_dwordx4 v134, s[28:29]
	s_add_i32 m0, s67, 0x2000
	s_add_u32 s68, s28, 0x80000
	s_addc_u32 s69, s29, 0
	s_add_i32 s67, s71, s41
	global_load_lds_dwordx4 v130, s[28:29]
	s_mov_b32 m0, s67
	s_nop 0
	global_load_lds_dwordx4 v134, s[68:69]
	s_add_i32 m0, s67, 0x2000
	s_nop 0
	global_load_lds_dwordx4 v130, s[68:69]
	s_mov_b32 m0, s25
	s_nop 0
	global_load_lds_dwordx4 v136, s[34:35]
	s_mov_b32 m0, s52
	s_nop 0
	global_load_lds_dwordx4 v132, s[34:35]
	s_waitcnt vmcnt(8)
	s_waitcnt lgkmcnt(0)
	s_barrier
; #define PG8_STAGE(bufoff, gbase, voff) do { _Pragma("unroll") for (int _i = 0; _i < 2; ++_i) \
;         __builtin_amdgcn_global_load_lds((const unsigned*)((const char*)(gbase) + (voff)[_i]), (LAS unsigned*)(lds + (bufoff) + ldsw + _i * 8192), 16, 0, 0); } while (0)
; #define PG8_LDA(dst, b, h) do { _Pragma("unroll") for (int m = 0; m < 4; ++m) _Pragma("unroll") for (int k = 0; k < 2; ++k) dst[m][k] = *(const LAS bf16x8*)(lds + PG8_SA(b, h) + aoff + m * 2048 + k * 1024); } while (0)
; #define PG8_LDB(dst, b, h) do { _Pragma("unroll") for (int n = 0; n < 2; ++n) _Pragma("unroll") for (int k = 0; k < 2; ++k) dst[n][k] = *(const LAS bf16x8*)(lds + PG8_SB(b, h) + boff + n * 2048 + k * 1024); } while (0)
; #define PG8_MMA(ai, bj, At, Bt) do { __builtin_amdgcn_s_setprio(1); _Pragma("unroll") for (int m = 0; m < 4; ++m) _Pragma("unroll") for (int n = 0; n < 2; ++n) _Pragma("unroll") for (int k = 0; k < 2; ++k) \
;         acc[ai][bj][m][n] = __builtin_amdgcn_mfma_f32_16x16x32_bf16(Bt[n][k], At[m][k], acc[ai][bj][m][n], 0, 0, 0); __builtin_amdgcn_s_setprio(0); } while (0)
; #define PG8_WAIT_V(n) asm volatile("s_waitcnt vmcnt(" #n ")" ::: "memory")
; #define PG8_WAIT_L(n) asm volatile("s_waitcnt lgkmcnt(" #n ")" ::: "memory")
; #define PG8_BAR __builtin_amdgcn_s_barrier()
; #define PG8_SCHED __builtin_amdgcn_sched_barrier(0)
; template <class Epi, class Sched, int KC, bool ALIGN_EPI = false, bool SP2 = false, bool ATILED = false>
; __device__ __forceinline__ void gemm_phase(LAS unsigned char* lds, const Gemm g, const Sched& S, const Epi& E, int wave_s) {
;     ...
;             PG8_WAIT_V(8); PG8_WAIT_L(0); PG8_BAR; PG8_MMA(1, 0, At, B0); PG8_MMA(1, 1, At, B1); PG8_BAR; PG8_SCHED;
;             PG8_LDB(B0, 1, 0); PG8_LDB(B1, 1, 1); PG8_SCHED; PG8_LDA(At, 1, 0); PG8_STAGE(PG8_SA(0, 1), a2 + hstepA, voffA);
;             PG8_WAIT_V(8); PG8_WAIT_L(0); PG8_BAR; PG8_MMA(0, 0, At, B0); PG8_MMA(0, 1, At, B1); PG8_BAR; PG8_SCHED;
;             PG8_LDA(At, 1, 1); PG8_STAGE(PG8_SB(1, 0), b3, voffB); PG8_STAGE(PG8_SB(1, 1), b3 + hstepB, voffB); PG8_STAGE(PG8_SA(1, 0), a3, voffA);
	s_waitcnt lgkmcnt(0)
	v_mfma_f32_16x16x32_bf16 v[62:65], v[152:155], v[198:201], v[62:65]
	v_mfma_f32_16x16x32_bf16 v[58:61], v[174:177], v[198:201], v[58:61]
	v_mfma_f32_16x16x32_bf16 v[50:53], v[152:155], v[206:209], v[50:53]
	v_mfma_f32_16x16x32_bf16 v[42:45], v[174:177], v[206:209], v[42:45]
	v_mfma_f32_16x16x32_bf16 v[34:37], v[152:155], v[214:217], v[34:37]
	v_mfma_f32_16x16x32_bf16 v[26:29], v[174:177], v[214:217], v[26:29]
	v_mfma_f32_16x16x32_bf16 v[18:21], v[152:155], v[222:225], v[18:21]
	v_mfma_f32_16x16x32_bf16 v[10:13], v[174:177], v[222:225], v[10:13]
	v_mfma_f32_16x16x32_bf16 v[62:65], v[160:163], v[202:205], v[62:65]
	v_mfma_f32_16x16x32_bf16 v[58:61], v[178:181], v[202:205], v[58:61]
	v_mfma_f32_16x16x32_bf16 v[50:53], v[160:163], v[210:213], v[50:53]
	v_mfma_f32_16x16x32_bf16 v[42:45], v[178:181], v[210:213], v[42:45]
	v_mfma_f32_16x16x32_bf16 v[34:37], v[160:163], v[218:221], v[34:37]
	v_mfma_f32_16x16x32_bf16 v[26:29], v[178:181], v[218:221], v[26:29]
	v_mfma_f32_16x16x32_bf16 v[18:21], v[160:163], v[226:229], v[18:21]
	v_mfma_f32_16x16x32_bf16 v[10:13], v[178:181], v[226:229], v[10:13]
	v_mfma_f32_16x16x32_bf16 v[54:57], v[182:185], v[198:201], v[54:57]
	v_mfma_f32_16x16x32_bf16 v[46:49], v[190:193], v[198:201], v[46:49]
	v_mfma_f32_16x16x32_bf16 v[38:41], v[182:185], v[206:209], v[38:41]
	v_mfma_f32_16x16x32_bf16 v[30:33], v[190:193], v[206:209], v[30:33]
	v_mfma_f32_16x16x32_bf16 v[22:25], v[182:185], v[214:217], v[22:25]
	v_mfma_f32_16x16x32_bf16 v[14:17], v[190:193], v[214:217], v[14:17]
	v_mfma_f32_16x16x32_bf16 v[6:9], v[182:185], v[222:225], v[6:9]
	v_mfma_f32_16x16x32_bf16 v[2:5], v[190:193], v[222:225], v[2:5]
	v_mfma_f32_16x16x32_bf16 v[54:57], v[186:189], v[202:205], v[54:57]
	v_mfma_f32_16x16x32_bf16 v[46:49], v[194:197], v[202:205], v[46:49]
	v_mfma_f32_16x16x32_bf16 v[38:41], v[186:189], v[210:213], v[38:41]
	v_mfma_f32_16x16x32_bf16 v[30:33], v[194:197], v[210:213], v[30:33]
	v_mfma_f32_16x16x32_bf16 v[22:25], v[186:189], v[218:221], v[22:25]
	v_mfma_f32_16x16x32_bf16 v[14:17], v[194:197], v[218:221], v[14:17]
	v_mfma_f32_16x16x32_bf16 v[6:9], v[186:189], v[226:229], v[6:9]
	v_mfma_f32_16x16x32_bf16 v[2:5], v[194:197], v[226:229], v[2:5]
	s_barrier
	s_add_i32 s67, 0, 0x18000
	v_add_u32_e32 v139, s67, v165
	ds_read_b128 v[152:155], v139
	ds_read_b128 v[160:163], v139 offset:1024
	ds_read_b128 v[174:177], v139 offset:2048
	ds_read_b128 v[178:181], v139 offset:3072
	s_add_i32 s68, 0, 0x1c000
	v_add_u32_e32 v139, s68, v165
	ds_read_b128 v[182:185], v139
	ds_read_b128 v[186:189], v139 offset:1024
	ds_read_b128 v[190:193], v139 offset:2048
	ds_read_b128 v[194:197], v139 offset:3072
	ds_read_b128 v[198:201], v173 offset:32768
	ds_read_b128 v[202:205], v173 offset:33792
	ds_read_b128 v[206:209], v173 offset:34816
	ds_read_b128 v[210:213], v173 offset:35840
	ds_read_b128 v[214:217], v173 offset:36864
	ds_read_b128 v[218:221], v173 offset:37888
	ds_read_b128 v[222:225], v173 offset:38912
	ds_read_b128 v[226:229], v173 offset:39936
	s_add_u32 s34, s34, 0x10000
	s_addc_u32 s35, s35, 0
	s_mov_b32 m0, s53
	s_nop 0
	global_load_lds_dwordx4 v136, s[34:35]
	s_mov_b32 m0, s54
	s_nop 0
	global_load_lds_dwordx4 v132, s[34:35]
	s_waitcnt vmcnt(8)
	s_waitcnt lgkmcnt(0)
	s_barrier
	s_waitcnt lgkmcnt(0)
	v_mfma_f32_16x16x32_bf16 v[126:129], v[152:155], v[198:201], v[126:129]
	v_mfma_f32_16x16x32_bf16 v[122:125], v[174:177], v[198:201], v[122:125]
	v_mfma_f32_16x16x32_bf16 v[114:117], v[152:155], v[206:209], v[114:117]
	v_mfma_f32_16x16x32_bf16 v[106:109], v[174:177], v[206:209], v[106:109]
	v_mfma_f32_16x16x32_bf16 v[98:101], v[152:155], v[214:217], v[98:101]
	v_mfma_f32_16x16x32_bf16 v[90:93], v[174:177], v[214:217], v[90:93]
	v_mfma_f32_16x16x32_bf16 v[82:85], v[152:155], v[222:225], v[82:85]
	v_mfma_f32_16x16x32_bf16 v[74:77], v[174:177], v[222:225], v[74:77]
	v_mfma_f32_16x16x32_bf16 v[126:129], v[160:163], v[202:205], v[126:129]
	v_mfma_f32_16x16x32_bf16 v[122:125], v[178:181], v[202:205], v[122:125]
	v_mfma_f32_16x16x32_bf16 v[114:117], v[160:163], v[210:213], v[114:117]
	v_mfma_f32_16x16x32_bf16 v[106:109], v[178:181], v[210:213], v[106:109]
	v_mfma_f32_16x16x32_bf16 v[98:101], v[160:163], v[218:221], v[98:101]
	v_mfma_f32_16x16x32_bf16 v[90:93], v[178:181], v[218:221], v[90:93]
	v_mfma_f32_16x16x32_bf16 v[82:85], v[160:163], v[226:229], v[82:85]
	v_mfma_f32_16x16x32_bf16 v[74:77], v[178:181], v[226:229], v[74:77]
	v_mfma_f32_16x16x32_bf16 v[118:121], v[182:185], v[198:201], v[118:121]
	v_mfma_f32_16x16x32_bf16 v[110:113], v[190:193], v[198:201], v[110:113]
	v_mfma_f32_16x16x32_bf16 v[102:105], v[182:185], v[206:209], v[102:105]
	v_mfma_f32_16x16x32_bf16 v[94:97], v[190:193], v[206:209], v[94:97]
	v_mfma_f32_16x16x32_bf16 v[86:89], v[182:185], v[214:217], v[86:89]
	v_mfma_f32_16x16x32_bf16 v[78:81], v[190:193], v[214:217], v[78:81]
	v_mfma_f32_16x16x32_bf16 v[70:73], v[182:185], v[222:225], v[70:73]
	v_mfma_f32_16x16x32_bf16 v[66:69], v[190:193], v[222:225], v[66:69]
	v_mfma_f32_16x16x32_bf16 v[118:121], v[186:189], v[202:205], v[118:121]
	v_mfma_f32_16x16x32_bf16 v[110:113], v[194:197], v[202:205], v[110:113]
	v_mfma_f32_16x16x32_bf16 v[102:105], v[186:189], v[210:213], v[102:105]
	v_mfma_f32_16x16x32_bf16 v[94:97], v[194:197], v[210:213], v[94:97]
	v_mfma_f32_16x16x32_bf16 v[86:89], v[186:189], v[218:221], v[86:89]
	v_mfma_f32_16x16x32_bf16 v[78:81], v[194:197], v[218:221], v[78:81]
	v_mfma_f32_16x16x32_bf16 v[70:73], v[186:189], v[226:229], v[70:73]
	v_mfma_f32_16x16x32_bf16 v[66:69], v[194:197], v[226:229], v[66:69]
	s_barrier
; #define PG8_STAGE(bufoff, gbase, voff) do { _Pragma("unroll") for (int _i = 0; _i < 2; ++_i) \
;         __builtin_amdgcn_global_load_lds((const unsigned*)((const char*)(gbase) + (voff)[_i]), (LAS unsigned*)(lds + (bufoff) + ldsw + _i * 8192), 16, 0, 0); } while (0)
; #define PG8_LDA(dst, b, h) do { _Pragma("unroll") for (int m = 0; m < 4; ++m) _Pragma("unroll") for (int k = 0; k < 2; ++k) dst[m][k] = *(const LAS bf16x8*)(lds + PG8_SA(b, h) + aoff + m * 2048 + k * 1024); } while (0)
; #define PG8_MMA(ai, bj, At, Bt) do { __builtin_amdgcn_s_setprio(1); _Pragma("unroll") for (int m = 0; m < 4; ++m) _Pragma("unroll") for (int n = 0; n < 2; ++n) _Pragma("unroll") for (int k = 0; k < 2; ++k) \
;         acc[ai][bj][m][n] = __builtin_amdgcn_mfma_f32_16x16x32_bf16(Bt[n][k], At[m][k], acc[ai][bj][m][n], 0, 0, 0); __builtin_amdgcn_s_setprio(0); } while (0)
; #define PG8_WAIT_V(n) asm volatile("s_waitcnt vmcnt(" #n ")" ::: "memory")
; #define PG8_WAIT_L(n) asm volatile("s_waitcnt lgkmcnt(" #n ")" ::: "memory")
; #define PG8_BAR __builtin_amdgcn_s_barrier()
; #define PG8_SCHED __builtin_amdgcn_sched_barrier(0)
; template <class Epi, class Sched, int KC, bool ALIGN_EPI = false, bool SP2 = false, bool ATILED = false>
; __device__ __forceinline__ void gemm_phase(LAS unsigned char* lds, const Gemm g, const Sched& S, const Epi& E, int wave_s) {
;     ...
;             PG8_LDA(At, 1, 1); PG8_STAGE(PG8_SB(1, 0), b3, voffB); PG8_STAGE(PG8_SB(1, 1), b3 + hstepB, voffB); PG8_STAGE(PG8_SA(1, 0), a3, voffA);
;             PG8_WAIT_V(8); PG8_WAIT_L(0); PG8_BAR; PG8_MMA(1, 0, At, B0); PG8_MMA(1, 1, At, B1); PG8_BAR; PG8_SCHED;
;     ...
;         if constexpr (ALIGN_EPI) { if (wr == 0) PG8_BAR; }
	ds_read_b128 v[198:201], v173 offset:49152
	ds_read_b128 v[202:205], v173 offset:50176
	ds_read_b128 v[206:209], v173 offset:51200
	ds_read_b128 v[210:213], v173 offset:52224
	ds_read_b128 v[214:217], v173 offset:53248
	ds_read_b128 v[218:221], v173 offset:54272
	ds_read_b128 v[222:225], v173 offset:55296
	ds_read_b128 v[226:229], v173 offset:56320
	s_add_u32 s98, s28, 0x80
	s_addc_u32 s99, s29, 0
	s_add_i32 s34, s67, s41
	s_mov_b32 m0, s34
	s_nop 0
	global_load_lds_dwordx4 v134, s[98:99]
	s_add_i32 m0, s34, 0x2000
	s_add_u32 s28, s28, 0x80080
	s_addc_u32 s29, s29, 0
	s_add_i32 s34, s68, s41
	global_load_lds_dwordx4 v130, s[98:99]
	s_mov_b32 m0, s34
	s_nop 0
	global_load_lds_dwordx4 v134, s[28:29]
	s_add_i32 m0, s34, 0x2000
	s_nop 0
	global_load_lds_dwordx4 v130, s[28:29]
	s_mov_b32 m0, s55
	s_nop 0
	global_load_lds_dwordx4 v136, s[100:101]
	s_mov_b32 m0, s56
	s_nop 0
	global_load_lds_dwordx4 v132, s[100:101]
	s_waitcnt vmcnt(8)
	s_waitcnt lgkmcnt(0)
	s_barrier
	s_waitcnt lgkmcnt(0)
	v_mfma_f32_16x16x32_bf16 v[62:65], v[152:155], v[198:201], v[62:65]
	v_mfma_f32_16x16x32_bf16 v[58:61], v[174:177], v[198:201], v[58:61]
	v_mfma_f32_16x16x32_bf16 v[50:53], v[152:155], v[206:209], v[50:53]
	v_mfma_f32_16x16x32_bf16 v[42:45], v[174:177], v[206:209], v[42:45]
	v_mfma_f32_16x16x32_bf16 v[34:37], v[152:155], v[214:217], v[34:37]
	v_mfma_f32_16x16x32_bf16 v[26:29], v[174:177], v[214:217], v[26:29]
	v_mfma_f32_16x16x32_bf16 v[18:21], v[152:155], v[222:225], v[18:21]
	v_mfma_f32_16x16x32_bf16 v[10:13], v[174:177], v[222:225], v[10:13]
	v_mfma_f32_16x16x32_bf16 v[62:65], v[160:163], v[202:205], v[62:65]
	v_mfma_f32_16x16x32_bf16 v[58:61], v[178:181], v[202:205], v[58:61]
	v_mfma_f32_16x16x32_bf16 v[50:53], v[160:163], v[210:213], v[50:53]
	v_mfma_f32_16x16x32_bf16 v[42:45], v[178:181], v[210:213], v[42:45]
	v_mfma_f32_16x16x32_bf16 v[34:37], v[160:163], v[218:221], v[34:37]
	v_mfma_f32_16x16x32_bf16 v[26:29], v[178:181], v[218:221], v[26:29]
	v_mfma_f32_16x16x32_bf16 v[18:21], v[160:163], v[226:229], v[18:21]
	v_mfma_f32_16x16x32_bf16 v[10:13], v[178:181], v[226:229], v[10:13]
	v_mfma_f32_16x16x32_bf16 v[54:57], v[182:185], v[198:201], v[54:57]
	v_mfma_f32_16x16x32_bf16 v[46:49], v[190:193], v[198:201], v[46:49]
	v_mfma_f32_16x16x32_bf16 v[38:41], v[182:185], v[206:209], v[38:41]
	v_mfma_f32_16x16x32_bf16 v[30:33], v[190:193], v[206:209], v[30:33]
	v_mfma_f32_16x16x32_bf16 v[22:25], v[182:185], v[214:217], v[22:25]
	v_mfma_f32_16x16x32_bf16 v[14:17], v[190:193], v[214:217], v[14:17]
	v_mfma_f32_16x16x32_bf16 v[6:9], v[182:185], v[222:225], v[6:9]
	v_mfma_f32_16x16x32_bf16 v[2:5], v[190:193], v[222:225], v[2:5]
	v_mfma_f32_16x16x32_bf16 v[54:57], v[186:189], v[202:205], v[54:57]
	v_mfma_f32_16x16x32_bf16 v[46:49], v[194:197], v[202:205], v[46:49]
	v_mfma_f32_16x16x32_bf16 v[38:41], v[186:189], v[210:213], v[38:41]
	v_mfma_f32_16x16x32_bf16 v[30:33], v[194:197], v[210:213], v[30:33]
	v_mfma_f32_16x16x32_bf16 v[22:25], v[186:189], v[218:221], v[22:25]
	v_mfma_f32_16x16x32_bf16 v[14:17], v[194:197], v[218:221], v[14:17]
	v_mfma_f32_16x16x32_bf16 v[6:9], v[186:189], v[226:229], v[6:9]
	v_mfma_f32_16x16x32_bf16 v[2:5], v[194:197], v[226:229], v[2:5]
	s_barrier
	s_add_i32 s65, s65, 2
	s_add_i32 s66, s66, 0x400000
	s_cmp_gt_u32 s65, 29
	s_mov_b64 s[28:29], s[30:31]
	s_cbranch_scc0 .LBB0_430
	s_and_b64 vcc, exec, s[14:15]
	s_cbranch_vccz .LBB0_433
	s_barrier

; #define PG8_STAGE(bufoff, gbase, voff) do { _Pragma("unroll") for (int _i = 0; _i < 2; ++_i) \
;         __builtin_amdgcn_global_load_lds((const unsigned*)((const char*)(gbase) + (voff)[_i]), (LAS unsigned*)(lds + (bufoff) + ldsw + _i * 8192), 16, 0, 0); } while (0)
; #define PG8_LDA(dst, b, h) do { _Pragma("unroll") for (int m = 0; m < 4; ++m) _Pragma("unroll") for (int k = 0; k < 2; ++k) dst[m][k] = *(const LAS bf16x8*)(lds + PG8_SA(b, h) + aoff + m * 2048 + k * 1024); } while (0)
; #define PG8_LDB(dst, b, h) do { _Pragma("unroll") for (int n = 0; n < 2; ++n) _Pragma("unroll") for (int k = 0; k < 2; ++k) dst[n][k] = *(const LAS bf16x8*)(lds + PG8_SB(b, h) + boff + n * 2048 + k * 1024); } while (0)
; #define PG8_WAIT_V(n) asm volatile("s_waitcnt vmcnt(" #n ")" ::: "memory")
; #define PG8_WAIT_L(n) asm volatile("s_waitcnt lgkmcnt(" #n ")" ::: "memory")
; #define PG8_BAR __builtin_amdgcn_s_barrier()
; template <class Epi, class Sched, int KC, bool ALIGN_EPI = false, bool SP2 = false, bool ATILED = false>
; __device__ __forceinline__ void gemm_phase(LAS unsigned char* lds, const Gemm g, const Sched& S, const Epi& E, int wave_s) {
;     ...
;         const bool has_next = S.next(ui + 1, nxt);
;         const char* nA = has_next ? (const char*)g.A + (size_t)nxt.pm * tstepA : cA; const char* nB = has_next ? (const char*)g.Bt + (size_t)nxt.pn * tstep : cB;
;         for (int t = 0; t < nt; t += 2) {
;             const bool last = (t == nt - 2);
;             const char* a1 = cA + PG8_AOFF(t + 1);
;             const char* a2 = last ? nA : cA + PG8_AOFF(t + 2); const char* b2 = last ? nB : cB + (size_t)(t + 2) * kstep;
;             const char* a3 = a2 + kstep; const char* b3 = b2 + kstep;
;             if (last && has_next) S.a_ready(nxt);
;             if constexpr (SP2) {
;             PG8_LDB(B0, 0, 0); PG8_LDB(B1, 0, 1); PG8_SCHED; PG8_LDA(At, 0, 0); PG8_STAGE(PG8_SA(1, 1), a1 + hstepA, voffA);
;             PG8_WAIT_V(8); PG8_WAIT_L(0); PG8_BAR; PG8_MMA(0, 0, At, B0); PG8_MMA(0, 1, At, B1); PG8_BAR; PG8_SCHED;
;     ...
; #pragma unroll
;         for (int a = 0; a < 2; ++a)
; #pragma unroll
;             for (int b = 0; b < 2; ++b)
; #pragma unroll
;                 for (int m = 0; m < 4; ++m)
; #pragma unroll
;                     for (int n = 0; n < 2; ++n) acc[a][b][m][n] = (f32x4){0.f, 0.f, 0.f, 0.f};
;         cur = nxt; cA = nA; cB = nB; ++ui;
.LBB0_1020:
	v_mov_b64_e32 v[2:3], 0x200
	s_ashr_i32 s9, s8, 31
	v_cmp_lt_i64_e32 vcc, s[10:11], v[2:3]
	s_lshl_b64 s[10:11], s[8:9], 20
	s_add_u32 s10, s27, s10
	s_addc_u32 s11, s28, s11
	s_and_b64 s[12:13], vcc, exec
	s_cselect_b32 s9, s11, s21
	s_cselect_b32 s15, s10, s20
	s_ashr_i32 s3, s2, 31
	s_lshl_b64 s[12:13], s[2:3], 20
	s_add_u32 s12, s29, s12
	s_addc_u32 s13, s30, s13
	s_and_b64 s[22:23], vcc, exec
	s_cselect_b32 s3, s13, s19
	s_cselect_b32 s17, s12, s18
	s_add_u32 s46, s18, 0x100
	s_addc_u32 s47, s19, 0
	s_add_u32 s18, s20, 0x80080
	v_mov_b32_e32 v2, 0
	s_addc_u32 s19, s21, 0
	s_mov_b32 s48, -2
	v_mov_b32_e32 v3, v2
	v_mov_b32_e32 v4, v2
	v_mov_b32_e32 v5, v2
	v_mov_b32_e32 v6, v2
	v_mov_b32_e32 v7, v2
	v_mov_b32_e32 v8, v2
	v_mov_b32_e32 v9, v2
	v_mov_b32_e32 v18, v2
	v_mov_b32_e32 v19, v2
	v_mov_b32_e32 v20, v2
	v_mov_b32_e32 v21, v2
	v_mov_b32_e32 v22, v2
	v_mov_b32_e32 v23, v2
	v_mov_b32_e32 v24, v2
	v_mov_b32_e32 v25, v2
	v_mov_b32_e32 v34, v2
	v_mov_b32_e32 v35, v2
	v_mov_b32_e32 v36, v2
	v_mov_b32_e32 v37, v2
	v_mov_b32_e32 v38, v2
	v_mov_b32_e32 v39, v2
	v_mov_b32_e32 v40, v2
	v_mov_b32_e32 v41, v2
	v_mov_b32_e32 v50, v2
	v_mov_b32_e32 v51, v2
	v_mov_b32_e32 v52, v2
	v_mov_b32_e32 v53, v2
	v_mov_b32_e32 v54, v2
	v_mov_b32_e32 v55, v2
	v_mov_b32_e32 v56, v2
	v_mov_b32_e32 v57, v2
	v_mov_b32_e32 v10, v2
	v_mov_b32_e32 v11, v2
	v_mov_b32_e32 v12, v2
	v_mov_b32_e32 v13, v2
	v_mov_b32_e32 v14, v2
	v_mov_b32_e32 v15, v2
	v_mov_b32_e32 v16, v2
	v_mov_b32_e32 v17, v2
	v_mov_b32_e32 v26, v2
	v_mov_b32_e32 v27, v2
	v_mov_b32_e32 v28, v2
	v_mov_b32_e32 v29, v2
	v_mov_b32_e32 v30, v2
	v_mov_b32_e32 v31, v2
	v_mov_b32_e32 v32, v2
	v_mov_b32_e32 v33, v2
	v_mov_b32_e32 v42, v2
	v_mov_b32_e32 v43, v2
	v_mov_b32_e32 v44, v2
	v_mov_b32_e32 v45, v2
	v_mov_b32_e32 v46, v2
	v_mov_b32_e32 v47, v2
	v_mov_b32_e32 v48, v2
	v_mov_b32_e32 v49, v2
	v_mov_b32_e32 v58, v2
	v_mov_b32_e32 v59, v2
	v_mov_b32_e32 v60, v2
	v_mov_b32_e32 v61, v2
	v_mov_b32_e32 v62, v2
	v_mov_b32_e32 v63, v2
	v_mov_b32_e32 v64, v2
	v_mov_b32_e32 v65, v2
	v_mov_b32_e32 v66, v2
	v_mov_b32_e32 v67, v2
	v_mov_b32_e32 v68, v2
	v_mov_b32_e32 v69, v2
	v_mov_b32_e32 v70, v2
	v_mov_b32_e32 v71, v2
	v_mov_b32_e32 v72, v2
	v_mov_b32_e32 v73, v2
	s_waitcnt vmcnt(0)
	v_mov_b32_e32 v82, v2
	v_mov_b32_e32 v83, v2
	v_mov_b32_e32 v84, v2
	v_mov_b32_e32 v85, v2
	v_mov_b32_e32 v86, v2
	v_mov_b32_e32 v87, v2
	v_mov_b32_e32 v88, v2
	v_mov_b32_e32 v89, v2
	v_mov_b32_e32 v98, v2
	v_mov_b32_e32 v99, v2
	v_mov_b32_e32 v100, v2
	v_mov_b32_e32 v101, v2
	v_mov_b32_e32 v102, v2
	v_mov_b32_e32 v103, v2
	v_mov_b32_e32 v104, v2
	v_mov_b32_e32 v105, v2
	v_mov_b32_e32 v114, v2
	v_mov_b32_e32 v115, v2
	v_mov_b32_e32 v116, v2
	v_mov_b32_e32 v117, v2
	v_mov_b32_e32 v118, v2
	v_mov_b32_e32 v119, v2
	v_mov_b32_e32 v120, v2
	v_mov_b32_e32 v121, v2
	v_mov_b32_e32 v74, v2
	v_mov_b32_e32 v75, v2
	v_mov_b32_e32 v76, v2
	v_mov_b32_e32 v77, v2
	v_mov_b32_e32 v78, v2
	v_mov_b32_e32 v79, v2
	v_mov_b32_e32 v80, v2
	v_mov_b32_e32 v81, v2
	v_mov_b32_e32 v90, v2
	v_mov_b32_e32 v91, v2
	v_mov_b32_e32 v92, v2
	v_mov_b32_e32 v93, v2
	v_mov_b32_e32 v94, v2
	v_mov_b32_e32 v95, v2
	v_mov_b32_e32 v96, v2
	v_mov_b32_e32 v97, v2
	v_mov_b32_e32 v106, v2
	v_mov_b32_e32 v107, v2
	v_mov_b32_e32 v108, v2
	v_mov_b32_e32 v109, v2
	v_mov_b32_e32 v110, v2
	v_mov_b32_e32 v111, v2
	v_mov_b32_e32 v112, v2
	v_mov_b32_e32 v113, v2
	v_mov_b32_e32 v122, v2
	v_mov_b32_e32 v123, v2
	v_mov_b32_e32 v124, v2
	v_mov_b32_e32 v125, v2
	v_mov_b32_e32 v126, v2
	v_mov_b32_e32 v127, v2
	v_mov_b32_e32 v128, v2
	v_mov_b32_e32 v129, v2
	s_add_i32 s49, 0, 0x10000
	v_add_u32_e32 v142, s49, v229
	s_add_i32 s52, 0, 0x14000
	v_add_u32_e32 v158, s52, v229
	ds_read_b128 v[130:133], v142
	ds_read_b128 v[134:137], v142 offset:1024
	ds_read_b128 v[138:141], v142 offset:2048
	ds_read_b128 v[142:145], v142 offset:3072
	ds_read_b128 v[146:149], v158
	ds_read_b128 v[150:153], v158 offset:1024
	ds_read_b128 v[154:157], v158 offset:2048
	ds_read_b128 v[158:161], v158 offset:3072
	ds_read_b128 v[162:165], v230
	ds_read_b128 v[166:169], v230 offset:1024
	ds_read_b128 v[170:173], v230 offset:2048
	ds_read_b128 v[174:177], v230 offset:3072
	ds_read_b128 v[178:181], v230 offset:4096
	ds_read_b128 v[182:185], v230 offset:5120
	ds_read_b128 v[186:189], v230 offset:6144
	ds_read_b128 v[190:193], v230 offset:7168
	s_add_u32 s20, s18, 0xfff80080
	s_addc_u32 s21, s19, -1
	s_cmp_eq_u32 s48, 28
	s_cselect_b32 s23, s9, s21
	s_cselect_b32 s22, s15, s20
	s_cselect_b32 s21, s3, s47
	s_cselect_b32 s20, s17, s46
	s_add_i32 m0, s34, 0xc000
	s_nop 0
	global_load_lds_dwordx4 v208, s[18:19]
	s_add_i32 m0, s34, 0xe000
	s_nop 0
	global_load_lds_dwordx4 v206, s[18:19]
	s_waitcnt vmcnt(32)
	s_waitcnt lgkmcnt(0)
	s_barrier
; #define PG8_STAGE(bufoff, gbase, voff) do { _Pragma("unroll") for (int _i = 0; _i < 2; ++_i) \
;         __builtin_amdgcn_global_load_lds((const unsigned*)((const char*)(gbase) + (voff)[_i]), (LAS unsigned*)(lds + (bufoff) + ldsw + _i * 8192), 16, 0, 0); } while (0)
; #define PG8_LDA(dst, b, h) do { _Pragma("unroll") for (int m = 0; m < 4; ++m) _Pragma("unroll") for (int k = 0; k < 2; ++k) dst[m][k] = *(const LAS bf16x8*)(lds + PG8_SA(b, h) + aoff + m * 2048 + k * 1024); } while (0)
; #define PG8_MMA(ai, bj, At, Bt) do { __builtin_amdgcn_s_setprio(1); _Pragma("unroll") for (int m = 0; m < 4; ++m) _Pragma("unroll") for (int n = 0; n < 2; ++n) _Pragma("unroll") for (int k = 0; k < 2; ++k) \
;         acc[ai][bj][m][n] = __builtin_amdgcn_mfma_f32_16x16x32_bf16(Bt[n][k], At[m][k], acc[ai][bj][m][n], 0, 0, 0); __builtin_amdgcn_s_setprio(0); } while (0)
; #define PG8_WAIT_V(n) asm volatile("s_waitcnt vmcnt(" #n ")" ::: "memory")
; #define PG8_WAIT_L(n) asm volatile("s_waitcnt lgkmcnt(" #n ")" ::: "memory")
; #define PG8_BAR __builtin_amdgcn_s_barrier()
; #define PG8_SCHED __builtin_amdgcn_sched_barrier(0)
; template <class Epi, class Sched, int KC, bool ALIGN_EPI = false, bool SP2 = false, bool ATILED = false>
; __device__ __forceinline__ void gemm_phase(LAS unsigned char* lds, const Gemm g, const Sched& S, const Epi& E, int wave_s) {
;     ...
;             PG8_WAIT_V(8); PG8_WAIT_L(0); PG8_BAR; PG8_MMA(0, 0, At, B0); PG8_MMA(0, 1, At, B1); PG8_BAR; PG8_SCHED;
;             PG8_LDA(At, 0, 1); PG8_STAGE(PG8_SB(0, 0), b2, voffB); PG8_STAGE(PG8_SB(0, 1), b2 + hstepB, voffB); PG8_STAGE(PG8_SA(0, 0), a2, voffA);
;             PG8_WAIT_V(8); PG8_WAIT_L(0); PG8_BAR; PG8_MMA(1, 0, At, B0); PG8_MMA(1, 1, At, B1); PG8_BAR; PG8_SCHED;
	s_waitcnt lgkmcnt(0)
	v_mfma_f32_16x16x32_bf16 v[126:129], v[130:133], v[162:165], v[126:129]
	v_mfma_f32_16x16x32_bf16 v[122:125], v[138:141], v[162:165], v[122:125]
	v_mfma_f32_16x16x32_bf16 v[110:113], v[130:133], v[170:173], v[110:113]
	v_mfma_f32_16x16x32_bf16 v[106:109], v[138:141], v[170:173], v[106:109]
	v_mfma_f32_16x16x32_bf16 v[94:97], v[130:133], v[178:181], v[94:97]
	v_mfma_f32_16x16x32_bf16 v[90:93], v[138:141], v[178:181], v[90:93]
	v_mfma_f32_16x16x32_bf16 v[78:81], v[130:133], v[186:189], v[78:81]
	v_mfma_f32_16x16x32_bf16 v[74:77], v[138:141], v[186:189], v[74:77]
	v_mfma_f32_16x16x32_bf16 v[126:129], v[134:137], v[166:169], v[126:129]
	v_mfma_f32_16x16x32_bf16 v[122:125], v[142:145], v[166:169], v[122:125]
	v_mfma_f32_16x16x32_bf16 v[110:113], v[134:137], v[174:177], v[110:113]
	v_mfma_f32_16x16x32_bf16 v[106:109], v[142:145], v[174:177], v[106:109]
	v_mfma_f32_16x16x32_bf16 v[94:97], v[134:137], v[182:185], v[94:97]
	v_mfma_f32_16x16x32_bf16 v[90:93], v[142:145], v[182:185], v[90:93]
	v_mfma_f32_16x16x32_bf16 v[78:81], v[134:137], v[190:193], v[78:81]
	v_mfma_f32_16x16x32_bf16 v[74:77], v[142:145], v[190:193], v[74:77]
	v_mfma_f32_16x16x32_bf16 v[118:121], v[146:149], v[162:165], v[118:121]
	v_mfma_f32_16x16x32_bf16 v[114:117], v[154:157], v[162:165], v[114:117]
	v_mfma_f32_16x16x32_bf16 v[102:105], v[146:149], v[170:173], v[102:105]
	v_mfma_f32_16x16x32_bf16 v[98:101], v[154:157], v[170:173], v[98:101]
	v_mfma_f32_16x16x32_bf16 v[86:89], v[146:149], v[178:181], v[86:89]
	v_mfma_f32_16x16x32_bf16 v[82:85], v[154:157], v[178:181], v[82:85]
	v_mfma_f32_16x16x32_bf16 v[70:73], v[146:149], v[186:189], v[70:73]
	v_mfma_f32_16x16x32_bf16 v[66:69], v[154:157], v[186:189], v[66:69]
	v_mfma_f32_16x16x32_bf16 v[118:121], v[150:153], v[166:169], v[118:121]
	v_mfma_f32_16x16x32_bf16 v[114:117], v[158:161], v[166:169], v[114:117]
	v_mfma_f32_16x16x32_bf16 v[102:105], v[150:153], v[174:177], v[102:105]
	v_mfma_f32_16x16x32_bf16 v[98:101], v[158:161], v[174:177], v[98:101]
	v_mfma_f32_16x16x32_bf16 v[86:89], v[150:153], v[182:185], v[86:89]
	v_mfma_f32_16x16x32_bf16 v[82:85], v[158:161], v[182:185], v[82:85]
	v_mfma_f32_16x16x32_bf16 v[70:73], v[150:153], v[190:193], v[70:73]
	v_mfma_f32_16x16x32_bf16 v[66:69], v[158:161], v[190:193], v[66:69]
	s_barrier
	ds_read_b128 v[162:165], v230 offset:16384
	ds_read_b128 v[166:169], v230 offset:17408
	ds_read_b128 v[170:173], v230 offset:18432
	ds_read_b128 v[174:177], v230 offset:19456
	ds_read_b128 v[178:181], v230 offset:20480
	ds_read_b128 v[182:185], v230 offset:21504
	ds_read_b128 v[186:189], v230 offset:22528
	ds_read_b128 v[190:193], v230 offset:23552
	s_add_u32 s100, s22, 0x80
	s_addc_u32 s101, s23, 0
	s_add_i32 s49, s49, s31
	s_mov_b32 m0, s49
	s_nop 0
	global_load_lds_dwordx4 v0, s[20:21]
	s_add_i32 m0, s49, 0x2000
	s_add_u32 s50, s20, 0x20000
	s_addc_u32 s51, s21, 0
	s_add_i32 s49, s52, s31
	global_load_lds_dwordx4 v202, s[20:21]
	s_mov_b32 m0, s49
	s_nop 0
	global_load_lds_dwordx4 v0, s[50:51]
	s_add_i32 m0, s49, 0x2000
	s_nop 0
	global_load_lds_dwordx4 v202, s[50:51]
	s_mov_b32 m0, s34
	s_nop 0
	global_load_lds_dwordx4 v198, s[22:23]
	s_mov_b32 m0, s35
	s_nop 0
	global_load_lds_dwordx4 v200, s[22:23]
	s_waitcnt vmcnt(32)
	s_waitcnt lgkmcnt(0)
	s_barrier
	s_waitcnt lgkmcnt(0)
	v_mfma_f32_16x16x32_bf16 v[62:65], v[130:133], v[162:165], v[62:65]
	v_mfma_f32_16x16x32_bf16 v[58:61], v[138:141], v[162:165], v[58:61]
	v_mfma_f32_16x16x32_bf16 v[46:49], v[130:133], v[170:173], v[46:49]
	v_mfma_f32_16x16x32_bf16 v[42:45], v[138:141], v[170:173], v[42:45]
	v_mfma_f32_16x16x32_bf16 v[30:33], v[130:133], v[178:181], v[30:33]
	v_mfma_f32_16x16x32_bf16 v[26:29], v[138:141], v[178:181], v[26:29]
	v_mfma_f32_16x16x32_bf16 v[14:17], v[130:133], v[186:189], v[14:17]
	v_mfma_f32_16x16x32_bf16 v[10:13], v[138:141], v[186:189], v[10:13]
	v_mfma_f32_16x16x32_bf16 v[62:65], v[134:137], v[166:169], v[62:65]
	v_mfma_f32_16x16x32_bf16 v[58:61], v[142:145], v[166:169], v[58:61]
	v_mfma_f32_16x16x32_bf16 v[46:49], v[134:137], v[174:177], v[46:49]
	v_mfma_f32_16x16x32_bf16 v[42:45], v[142:145], v[174:177], v[42:45]
	v_mfma_f32_16x16x32_bf16 v[30:33], v[134:137], v[182:185], v[30:33]
	v_mfma_f32_16x16x32_bf16 v[26:29], v[142:145], v[182:185], v[26:29]
	v_mfma_f32_16x16x32_bf16 v[14:17], v[134:137], v[190:193], v[14:17]
	v_mfma_f32_16x16x32_bf16 v[10:13], v[142:145], v[190:193], v[10:13]
	v_mfma_f32_16x16x32_bf16 v[54:57], v[146:149], v[162:165], v[54:57]
	v_mfma_f32_16x16x32_bf16 v[50:53], v[154:157], v[162:165], v[50:53]
	v_mfma_f32_16x16x32_bf16 v[38:41], v[146:149], v[170:173], v[38:41]
	v_mfma_f32_16x16x32_bf16 v[34:37], v[154:157], v[170:173], v[34:37]
	v_mfma_f32_16x16x32_bf16 v[22:25], v[146:149], v[178:181], v[22:25]
	v_mfma_f32_16x16x32_bf16 v[18:21], v[154:157], v[178:181], v[18:21]
	v_mfma_f32_16x16x32_bf16 v[6:9], v[146:149], v[186:189], v[6:9]
	v_mfma_f32_16x16x32_bf16 v[2:5], v[154:157], v[186:189], v[2:5]
	v_mfma_f32_16x16x32_bf16 v[54:57], v[150:153], v[166:169], v[54:57]
	v_mfma_f32_16x16x32_bf16 v[50:53], v[158:161], v[166:169], v[50:53]
	v_mfma_f32_16x16x32_bf16 v[38:41], v[150:153], v[174:177], v[38:41]
	v_mfma_f32_16x16x32_bf16 v[34:37], v[158:161], v[174:177], v[34:37]
	v_mfma_f32_16x16x32_bf16 v[22:25], v[150:153], v[182:185], v[22:25]
	v_mfma_f32_16x16x32_bf16 v[18:21], v[158:161], v[182:185], v[18:21]
	v_mfma_f32_16x16x32_bf16 v[6:9], v[150:153], v[190:193], v[6:9]
	v_mfma_f32_16x16x32_bf16 v[2:5], v[158:161], v[190:193], v[2:5]
	s_barrier
; #define PG8_STAGE(bufoff, gbase, voff) do { _Pragma("unroll") for (int _i = 0; _i < 2; ++_i) \
;         __builtin_amdgcn_global_load_lds((const unsigned*)((const char*)(gbase) + (voff)[_i]), (LAS unsigned*)(lds + (bufoff) + ldsw + _i * 8192), 16, 0, 0); } while (0)
; #define PG8_LDA(dst, b, h) do { _Pragma("unroll") for (int m = 0; m < 4; ++m) _Pragma("unroll") for (int k = 0; k < 2; ++k) dst[m][k] = *(const LAS bf16x8*)(lds + PG8_SA(b, h) + aoff + m * 2048 + k * 1024); } while (0)
; #define PG8_LDB(dst, b, h) do { _Pragma("unroll") for (int n = 0; n < 2; ++n) _Pragma("unroll") for (int k = 0; k < 2; ++k) dst[n][k] = *(const LAS bf16x8*)(lds + PG8_SB(b, h) + boff + n * 2048 + k * 1024); } while (0)
; #define PG8_MMA(ai, bj, At, Bt) do { __builtin_amdgcn_s_setprio(1); _Pragma("unroll") for (int m = 0; m < 4; ++m) _Pragma("unroll") for (int n = 0; n < 2; ++n) _Pragma("unroll") for (int k = 0; k < 2; ++k) \
;         acc[ai][bj][m][n] = __builtin_amdgcn_mfma_f32_16x16x32_bf16(Bt[n][k], At[m][k], acc[ai][bj][m][n], 0, 0, 0); __builtin_amdgcn_s_setprio(0); } while (0)
; #define PG8_WAIT_V(n) asm volatile("s_waitcnt vmcnt(" #n ")" ::: "memory")
; #define PG8_WAIT_L(n) asm volatile("s_waitcnt lgkmcnt(" #n ")" ::: "memory")
; #define PG8_BAR __builtin_amdgcn_s_barrier()
; #define PG8_SCHED __builtin_amdgcn_sched_barrier(0)
; template <class Epi, class Sched, int KC, bool ALIGN_EPI = false, bool SP2 = false, bool ATILED = false>
; __device__ __forceinline__ void gemm_phase(LAS unsigned char* lds, const Gemm g, const Sched& S, const Epi& E, int wave_s) {
;     ...
;             PG8_LDB(B0, 1, 0); PG8_LDB(B1, 1, 1); PG8_SCHED; PG8_LDA(At, 1, 0); PG8_STAGE(PG8_SA(0, 1), a2 + hstepA, voffA);
;             PG8_WAIT_V(8); PG8_WAIT_L(0); PG8_BAR; PG8_MMA(0, 0, At, B0); PG8_MMA(0, 1, At, B1); PG8_BAR; PG8_SCHED;
;             PG8_LDA(At, 1, 1); PG8_STAGE(PG8_SB(1, 0), b3, voffB); PG8_STAGE(PG8_SB(1, 1), b3 + hstepB, voffB); PG8_STAGE(PG8_SA(1, 0), a3, voffA);
;             PG8_WAIT_V(8); PG8_WAIT_L(0); PG8_BAR; PG8_MMA(1, 0, At, B0); PG8_MMA(1, 1, At, B1); PG8_BAR; PG8_SCHED;
	s_add_i32 s49, 0, 0x18000
	v_add_u32_e32 v142, s49, v229
	s_add_i32 s50, 0, 0x1c000
	v_add_u32_e32 v158, s50, v229
	ds_read_b128 v[130:133], v142
	ds_read_b128 v[134:137], v142 offset:1024
	ds_read_b128 v[138:141], v142 offset:2048
	ds_read_b128 v[142:145], v142 offset:3072
	ds_read_b128 v[146:149], v158
	ds_read_b128 v[150:153], v158 offset:1024
	ds_read_b128 v[154:157], v158 offset:2048
	ds_read_b128 v[158:161], v158 offset:3072
	ds_read_b128 v[162:165], v230 offset:32768
	ds_read_b128 v[166:169], v230 offset:33792
	ds_read_b128 v[170:173], v230 offset:34816
	ds_read_b128 v[174:177], v230 offset:35840
	ds_read_b128 v[178:181], v230 offset:36864
	ds_read_b128 v[182:185], v230 offset:37888
	ds_read_b128 v[186:189], v230 offset:38912
	ds_read_b128 v[190:193], v230 offset:39936
	s_add_u32 s22, s22, 0x80000
	s_addc_u32 s23, s23, 0
	s_mov_b32 m0, s36
	s_nop 0
	global_load_lds_dwordx4 v198, s[22:23]
	s_mov_b32 m0, s37
	s_nop 0
	global_load_lds_dwordx4 v200, s[22:23]
	s_waitcnt vmcnt(8)
	s_waitcnt lgkmcnt(0)
	s_barrier
	s_waitcnt lgkmcnt(0)
	v_mfma_f32_16x16x32_bf16 v[126:129], v[130:133], v[162:165], v[126:129]
	v_mfma_f32_16x16x32_bf16 v[122:125], v[138:141], v[162:165], v[122:125]
	v_mfma_f32_16x16x32_bf16 v[110:113], v[130:133], v[170:173], v[110:113]
	v_mfma_f32_16x16x32_bf16 v[106:109], v[138:141], v[170:173], v[106:109]
	v_mfma_f32_16x16x32_bf16 v[94:97], v[130:133], v[178:181], v[94:97]
	v_mfma_f32_16x16x32_bf16 v[90:93], v[138:141], v[178:181], v[90:93]
	v_mfma_f32_16x16x32_bf16 v[78:81], v[130:133], v[186:189], v[78:81]
	v_mfma_f32_16x16x32_bf16 v[74:77], v[138:141], v[186:189], v[74:77]
	v_mfma_f32_16x16x32_bf16 v[126:129], v[134:137], v[166:169], v[126:129]
	v_mfma_f32_16x16x32_bf16 v[122:125], v[142:145], v[166:169], v[122:125]
	v_mfma_f32_16x16x32_bf16 v[110:113], v[134:137], v[174:177], v[110:113]
	v_mfma_f32_16x16x32_bf16 v[106:109], v[142:145], v[174:177], v[106:109]
	v_mfma_f32_16x16x32_bf16 v[94:97], v[134:137], v[182:185], v[94:97]
	v_mfma_f32_16x16x32_bf16 v[90:93], v[142:145], v[182:185], v[90:93]
	v_mfma_f32_16x16x32_bf16 v[78:81], v[134:137], v[190:193], v[78:81]
	v_mfma_f32_16x16x32_bf16 v[74:77], v[142:145], v[190:193], v[74:77]
	v_mfma_f32_16x16x32_bf16 v[118:121], v[146:149], v[162:165], v[118:121]
	v_mfma_f32_16x16x32_bf16 v[114:117], v[154:157], v[162:165], v[114:117]
	v_mfma_f32_16x16x32_bf16 v[102:105], v[146:149], v[170:173], v[102:105]
	v_mfma_f32_16x16x32_bf16 v[98:101], v[154:157], v[170:173], v[98:101]
	v_mfma_f32_16x16x32_bf16 v[86:89], v[146:149], v[178:181], v[86:89]
	v_mfma_f32_16x16x32_bf16 v[82:85], v[154:157], v[178:181], v[82:85]
	v_mfma_f32_16x16x32_bf16 v[70:73], v[146:149], v[186:189], v[70:73]
	v_mfma_f32_16x16x32_bf16 v[66:69], v[154:157], v[186:189], v[66:69]
	v_mfma_f32_16x16x32_bf16 v[118:121], v[150:153], v[166:169], v[118:121]
	v_mfma_f32_16x16x32_bf16 v[114:117], v[158:161], v[166:169], v[114:117]
	v_mfma_f32_16x16x32_bf16 v[102:105], v[150:153], v[174:177], v[102:105]
	v_mfma_f32_16x16x32_bf16 v[98:101], v[158:161], v[174:177], v[98:101]
	v_mfma_f32_16x16x32_bf16 v[86:89], v[150:153], v[182:185], v[86:89]
	v_mfma_f32_16x16x32_bf16 v[82:85], v[158:161], v[182:185], v[82:85]
	v_mfma_f32_16x16x32_bf16 v[70:73], v[150:153], v[190:193], v[70:73]
	v_mfma_f32_16x16x32_bf16 v[66:69], v[158:161], v[190:193], v[66:69]
	s_barrier
	ds_read_b128 v[162:165], v230 offset:49152
	ds_read_b128 v[166:169], v230 offset:50176
	ds_read_b128 v[170:173], v230 offset:51200
	ds_read_b128 v[174:177], v230 offset:52224
	ds_read_b128 v[178:181], v230 offset:53248
	ds_read_b128 v[182:185], v230 offset:54272
	ds_read_b128 v[186:189], v230 offset:55296
	ds_read_b128 v[190:193], v230 offset:56320
	s_add_u32 s98, s20, 0x80
	s_addc_u32 s99, s21, 0
	s_add_i32 s22, s49, s31
	s_mov_b32 m0, s22
	s_nop 0
	global_load_lds_dwordx4 v0, s[98:99]
	s_add_i32 m0, s22, 0x2000
	s_add_u32 s20, s20, 0x20080
	s_addc_u32 s21, s21, 0
	s_add_i32 s22, s50, s31
	global_load_lds_dwordx4 v202, s[98:99]
	s_mov_b32 m0, s22
	s_nop 0
	global_load_lds_dwordx4 v0, s[20:21]
	s_add_i32 m0, s22, 0x2000
	s_nop 0
	global_load_lds_dwordx4 v202, s[20:21]
	s_mov_b32 m0, s41
	s_nop 0
	global_load_lds_dwordx4 v198, s[100:101]
	s_mov_b32 m0, s42
	s_nop 0
	global_load_lds_dwordx4 v200, s[100:101]
	s_waitcnt vmcnt(8)
	s_waitcnt lgkmcnt(0)
	s_barrier
	s_waitcnt lgkmcnt(0)
	v_mfma_f32_16x16x32_bf16 v[62:65], v[130:133], v[162:165], v[62:65]
	v_mfma_f32_16x16x32_bf16 v[58:61], v[138:141], v[162:165], v[58:61]
	v_mfma_f32_16x16x32_bf16 v[46:49], v[130:133], v[170:173], v[46:49]
	v_mfma_f32_16x16x32_bf16 v[42:45], v[138:141], v[170:173], v[42:45]
	v_mfma_f32_16x16x32_bf16 v[30:33], v[130:133], v[178:181], v[30:33]
	v_mfma_f32_16x16x32_bf16 v[26:29], v[138:141], v[178:181], v[26:29]
	v_mfma_f32_16x16x32_bf16 v[14:17], v[130:133], v[186:189], v[14:17]
	v_mfma_f32_16x16x32_bf16 v[10:13], v[138:141], v[186:189], v[10:13]
	v_mfma_f32_16x16x32_bf16 v[62:65], v[134:137], v[166:169], v[62:65]
	v_mfma_f32_16x16x32_bf16 v[58:61], v[142:145], v[166:169], v[58:61]
	v_mfma_f32_16x16x32_bf16 v[46:49], v[134:137], v[174:177], v[46:49]
	v_mfma_f32_16x16x32_bf16 v[42:45], v[142:145], v[174:177], v[42:45]
	v_mfma_f32_16x16x32_bf16 v[30:33], v[134:137], v[182:185], v[30:33]
	v_mfma_f32_16x16x32_bf16 v[26:29], v[142:145], v[182:185], v[26:29]
	v_mfma_f32_16x16x32_bf16 v[14:17], v[134:137], v[190:193], v[14:17]
	v_mfma_f32_16x16x32_bf16 v[10:13], v[142:145], v[190:193], v[10:13]
	v_mfma_f32_16x16x32_bf16 v[54:57], v[146:149], v[162:165], v[54:57]
	v_mfma_f32_16x16x32_bf16 v[50:53], v[154:157], v[162:165], v[50:53]
	v_mfma_f32_16x16x32_bf16 v[38:41], v[146:149], v[170:173], v[38:41]
	v_mfma_f32_16x16x32_bf16 v[34:37], v[154:157], v[170:173], v[34:37]
	v_mfma_f32_16x16x32_bf16 v[22:25], v[146:149], v[178:181], v[22:25]
	v_mfma_f32_16x16x32_bf16 v[18:21], v[154:157], v[178:181], v[18:21]
	v_mfma_f32_16x16x32_bf16 v[6:9], v[146:149], v[186:189], v[6:9]
	v_mfma_f32_16x16x32_bf16 v[2:5], v[154:157], v[186:189], v[2:5]
	v_mfma_f32_16x16x32_bf16 v[54:57], v[150:153], v[166:169], v[54:57]
	v_mfma_f32_16x16x32_bf16 v[50:53], v[158:161], v[166:169], v[50:53]
	v_mfma_f32_16x16x32_bf16 v[38:41], v[150:153], v[174:177], v[38:41]
	v_mfma_f32_16x16x32_bf16 v[34:37], v[158:161], v[174:177], v[34:37]
	v_mfma_f32_16x16x32_bf16 v[22:25], v[150:153], v[182:185], v[22:25]
	v_mfma_f32_16x16x32_bf16 v[18:21], v[158:161], v[182:185], v[18:21]
	v_mfma_f32_16x16x32_bf16 v[6:9], v[150:153], v[190:193], v[6:9]
	v_mfma_f32_16x16x32_bf16 v[2:5], v[158:161], v[190:193], v[2:5]
	s_barrier
	s_add_i32 s48, s48, 2
	s_add_u32 s46, s46, 0x100
	s_addc_u32 s47, s47, 0
	s_add_u32 s18, s18, 0x100
	s_addc_u32 s19, s19, 0
	s_cmp_gt_u32 s48, 29
; #define PG8_STAGE(bufoff, gbase, voff) do { _Pragma("unroll") for (int _i = 0; _i < 2; ++_i) \
;         __builtin_amdgcn_global_load_lds((const unsigned*)((const char*)(gbase) + (voff)[_i]), (LAS unsigned*)(lds + (bufoff) + ldsw + _i * 8192), 16, 0, 0); } while (0)
; #define PG8_LDA(dst, b, h) do { _Pragma("unroll") for (int m = 0; m < 4; ++m) _Pragma("unroll") for (int k = 0; k < 2; ++k) dst[m][k] = *(const LAS bf16x8*)(lds + PG8_SA(b, h) + aoff + m * 2048 + k * 1024); } while (0)
; #define PG8_LDB(dst, b, h) do { _Pragma("unroll") for (int n = 0; n < 2; ++n) _Pragma("unroll") for (int k = 0; k < 2; ++k) dst[n][k] = *(const LAS bf16x8*)(lds + PG8_SB(b, h) + boff + n * 2048 + k * 1024); } while (0)
; #define PG8_MMA(ai, bj, At, Bt) do { __builtin_amdgcn_s_setprio(1); _Pragma("unroll") for (int m = 0; m < 4; ++m) _Pragma("unroll") for (int n = 0; n < 2; ++n) _Pragma("unroll") for (int k = 0; k < 2; ++k) \
;         acc[ai][bj][m][n] = __builtin_amdgcn_mfma_f32_16x16x32_bf16(Bt[n][k], At[m][k], acc[ai][bj][m][n], 0, 0, 0); __builtin_amdgcn_s_setprio(0); } while (0)
; #define PG8_WAIT_V(n) asm volatile("s_waitcnt vmcnt(" #n ")" ::: "memory")
; #define PG8_WAIT_L(n) asm volatile("s_waitcnt lgkmcnt(" #n ")" ::: "memory")
; #define PG8_BAR __builtin_amdgcn_s_barrier()
; #define PG8_SCHED __builtin_amdgcn_sched_barrier(0)
; template <class Epi, class Sched, int KC, bool ALIGN_EPI = false, bool SP2 = false, bool ATILED = false>
; __device__ __forceinline__ void gemm_phase(LAS unsigned char* lds, const Gemm g, const Sched& S, const Epi& E, int wave_s) {
;     ...
;             const bool last = (t == nt - 2);
;             const char* a1 = cA + PG8_AOFF(t + 1);
;             const char* a2 = last ? nA : cA + PG8_AOFF(t + 2); const char* b2 = last ? nB : cB + (size_t)(t + 2) * kstep;
;             const char* a3 = a2 + kstep; const char* b3 = b2 + kstep;
;             if (last && has_next) S.a_ready(nxt);
;             if constexpr (SP2) {
;             PG8_LDB(B0, 0, 0); PG8_LDB(B1, 0, 1); PG8_SCHED; PG8_LDA(At, 0, 0); PG8_STAGE(PG8_SA(1, 1), a1 + hstepA, voffA);
;             PG8_WAIT_V(8); PG8_WAIT_L(0); PG8_BAR; PG8_MMA(0, 0, At, B0); PG8_MMA(0, 1, At, B1); PG8_BAR; PG8_SCHED;
;             PG8_LDA(At, 0, 1); PG8_STAGE(PG8_SB(0, 0), b2, voffB); PG8_STAGE(PG8_SB(0, 1), b2 + hstepB, voffB); PG8_STAGE(PG8_SA(0, 0), a2, voffA);
.LBB0_1021:
	s_add_i32 s49, 0, 0x10000
	v_add_u32_e32 v142, s49, v229
	s_add_i32 s52, 0, 0x14000
	v_add_u32_e32 v158, s52, v229
	ds_read_b128 v[130:133], v142
	ds_read_b128 v[134:137], v142 offset:1024
	ds_read_b128 v[138:141], v142 offset:2048
	ds_read_b128 v[142:145], v142 offset:3072
	ds_read_b128 v[146:149], v158
	ds_read_b128 v[150:153], v158 offset:1024
	ds_read_b128 v[154:157], v158 offset:2048
	ds_read_b128 v[158:161], v158 offset:3072
	ds_read_b128 v[162:165], v230
	ds_read_b128 v[166:169], v230 offset:1024
	ds_read_b128 v[170:173], v230 offset:2048
	ds_read_b128 v[174:177], v230 offset:3072
	ds_read_b128 v[178:181], v230 offset:4096
	ds_read_b128 v[182:185], v230 offset:5120
	ds_read_b128 v[186:189], v230 offset:6144
	ds_read_b128 v[190:193], v230 offset:7168
	s_add_u32 s20, s18, 0xfff80080
	s_addc_u32 s21, s19, -1
	s_cmp_eq_u32 s48, 28
	s_cselect_b32 s23, s9, s21
	s_cselect_b32 s22, s15, s20
	s_cselect_b32 s21, s3, s47
	s_cselect_b32 s20, s17, s46
	s_add_i32 m0, s34, 0xc000
	s_nop 0
	global_load_lds_dwordx4 v208, s[18:19]
	s_add_i32 m0, s34, 0xe000
	s_nop 0
	global_load_lds_dwordx4 v206, s[18:19]
	s_waitcnt vmcnt(8)
	s_waitcnt lgkmcnt(0)
	s_barrier
	s_waitcnt lgkmcnt(0)
	v_mfma_f32_16x16x32_bf16 v[126:129], v[130:133], v[162:165], v[126:129]
	v_mfma_f32_16x16x32_bf16 v[122:125], v[138:141], v[162:165], v[122:125]
	v_mfma_f32_16x16x32_bf16 v[110:113], v[130:133], v[170:173], v[110:113]
	v_mfma_f32_16x16x32_bf16 v[106:109], v[138:141], v[170:173], v[106:109]
	v_mfma_f32_16x16x32_bf16 v[94:97], v[130:133], v[178:181], v[94:97]
	v_mfma_f32_16x16x32_bf16 v[90:93], v[138:141], v[178:181], v[90:93]
	v_mfma_f32_16x16x32_bf16 v[78:81], v[130:133], v[186:189], v[78:81]
	v_mfma_f32_16x16x32_bf16 v[74:77], v[138:141], v[186:189], v[74:77]
	v_mfma_f32_16x16x32_bf16 v[126:129], v[134:137], v[166:169], v[126:129]
	v_mfma_f32_16x16x32_bf16 v[122:125], v[142:145], v[166:169], v[122:125]
	v_mfma_f32_16x16x32_bf16 v[110:113], v[134:137], v[174:177], v[110:113]
	v_mfma_f32_16x16x32_bf16 v[106:109], v[142:145], v[174:177], v[106:109]
	v_mfma_f32_16x16x32_bf16 v[94:97], v[134:137], v[182:185], v[94:97]
	v_mfma_f32_16x16x32_bf16 v[90:93], v[142:145], v[182:185], v[90:93]
	v_mfma_f32_16x16x32_bf16 v[78:81], v[134:137], v[190:193], v[78:81]
	v_mfma_f32_16x16x32_bf16 v[74:77], v[142:145], v[190:193], v[74:77]
	v_mfma_f32_16x16x32_bf16 v[118:121], v[146:149], v[162:165], v[118:121]
	v_mfma_f32_16x16x32_bf16 v[114:117], v[154:157], v[162:165], v[114:117]
	v_mfma_f32_16x16x32_bf16 v[102:105], v[146:149], v[170:173], v[102:105]
	v_mfma_f32_16x16x32_bf16 v[98:101], v[154:157], v[170:173], v[98:101]
	v_mfma_f32_16x16x32_bf16 v[86:89], v[146:149], v[178:181], v[86:89]
	v_mfma_f32_16x16x32_bf16 v[82:85], v[154:157], v[178:181], v[82:85]
	v_mfma_f32_16x16x32_bf16 v[70:73], v[146:149], v[186:189], v[70:73]
	v_mfma_f32_16x16x32_bf16 v[66:69], v[154:157], v[186:189], v[66:69]
	v_mfma_f32_16x16x32_bf16 v[118:121], v[150:153], v[166:169], v[118:121]
	v_mfma_f32_16x16x32_bf16 v[114:117], v[158:161], v[166:169], v[114:117]
	v_mfma_f32_16x16x32_bf16 v[102:105], v[150:153], v[174:177], v[102:105]
	v_mfma_f32_16x16x32_bf16 v[98:101], v[158:161], v[174:177], v[98:101]
	v_mfma_f32_16x16x32_bf16 v[86:89], v[150:153], v[182:185], v[86:89]
	v_mfma_f32_16x16x32_bf16 v[82:85], v[158:161], v[182:185], v[82:85]
	v_mfma_f32_16x16x32_bf16 v[70:73], v[150:153], v[190:193], v[70:73]
	v_mfma_f32_16x16x32_bf16 v[66:69], v[158:161], v[190:193], v[66:69]
	s_barrier
	ds_read_b128 v[162:165], v230 offset:16384
	ds_read_b128 v[166:169], v230 offset:17408
	ds_read_b128 v[170:173], v230 offset:18432
	ds_read_b128 v[174:177], v230 offset:19456
	ds_read_b128 v[178:181], v230 offset:20480
	ds_read_b128 v[182:185], v230 offset:21504
	ds_read_b128 v[186:189], v230 offset:22528
	ds_read_b128 v[190:193], v230 offset:23552
	s_add_u32 s100, s22, 0x80
	s_addc_u32 s101, s23, 0
	s_add_i32 s49, s49, s31
	s_mov_b32 m0, s49
	s_nop 0
	global_load_lds_dwordx4 v0, s[20:21]
	s_add_i32 m0, s49, 0x2000
	s_add_u32 s50, s20, 0x20000
	s_addc_u32 s51, s21, 0
	s_add_i32 s49, s52, s31
	global_load_lds_dwordx4 v202, s[20:21]
	s_mov_b32 m0, s49
	s_nop 0
	global_load_lds_dwordx4 v0, s[50:51]
	s_add_i32 m0, s49, 0x2000
	s_nop 0
	global_load_lds_dwordx4 v202, s[50:51]
	s_mov_b32 m0, s34
	s_nop 0
	global_load_lds_dwordx4 v198, s[22:23]
	s_mov_b32 m0, s35
	s_nop 0
	global_load_lds_dwordx4 v200, s[22:23]
	s_waitcnt vmcnt(8)
	s_waitcnt lgkmcnt(0)
	s_barrier
	s_waitcnt lgkmcnt(0)
	v_mfma_f32_16x16x32_bf16 v[62:65], v[130:133], v[162:165], v[62:65]
	v_mfma_f32_16x16x32_bf16 v[58:61], v[138:141], v[162:165], v[58:61]
	v_mfma_f32_16x16x32_bf16 v[46:49], v[130:133], v[170:173], v[46:49]
	v_mfma_f32_16x16x32_bf16 v[42:45], v[138:141], v[170:173], v[42:45]
	v_mfma_f32_16x16x32_bf16 v[30:33], v[130:133], v[178:181], v[30:33]
	v_mfma_f32_16x16x32_bf16 v[26:29], v[138:141], v[178:181], v[26:29]
	v_mfma_f32_16x16x32_bf16 v[14:17], v[130:133], v[186:189], v[14:17]
	v_mfma_f32_16x16x32_bf16 v[10:13], v[138:141], v[186:189], v[10:13]
	v_mfma_f32_16x16x32_bf16 v[62:65], v[134:137], v[166:169], v[62:65]
	v_mfma_f32_16x16x32_bf16 v[58:61], v[142:145], v[166:169], v[58:61]
	v_mfma_f32_16x16x32_bf16 v[46:49], v[134:137], v[174:177], v[46:49]
	v_mfma_f32_16x16x32_bf16 v[42:45], v[142:145], v[174:177], v[42:45]
	v_mfma_f32_16x16x32_bf16 v[30:33], v[134:137], v[182:185], v[30:33]
	v_mfma_f32_16x16x32_bf16 v[26:29], v[142:145], v[182:185], v[26:29]
	v_mfma_f32_16x16x32_bf16 v[14:17], v[134:137], v[190:193], v[14:17]
	v_mfma_f32_16x16x32_bf16 v[10:13], v[142:145], v[190:193], v[10:13]
	v_mfma_f32_16x16x32_bf16 v[54:57], v[146:149], v[162:165], v[54:57]
	v_mfma_f32_16x16x32_bf16 v[50:53], v[154:157], v[162:165], v[50:53]
	v_mfma_f32_16x16x32_bf16 v[38:41], v[146:149], v[170:173], v[38:41]
	v_mfma_f32_16x16x32_bf16 v[34:37], v[154:157], v[170:173], v[34:37]
	v_mfma_f32_16x16x32_bf16 v[22:25], v[146:149], v[178:181], v[22:25]
	v_mfma_f32_16x16x32_bf16 v[18:21], v[154:157], v[178:181], v[18:21]
	v_mfma_f32_16x16x32_bf16 v[6:9], v[146:149], v[186:189], v[6:9]
	v_mfma_f32_16x16x32_bf16 v[2:5], v[154:157], v[186:189], v[2:5]
	v_mfma_f32_16x16x32_bf16 v[54:57], v[150:153], v[166:169], v[54:57]
	v_mfma_f32_16x16x32_bf16 v[50:53], v[158:161], v[166:169], v[50:53]
	v_mfma_f32_16x16x32_bf16 v[38:41], v[150:153], v[174:177], v[38:41]
	v_mfma_f32_16x16x32_bf16 v[34:37], v[158:161], v[174:177], v[34:37]
	v_mfma_f32_16x16x32_bf16 v[22:25], v[150:153], v[182:185], v[22:25]
	v_mfma_f32_16x16x32_bf16 v[18:21], v[158:161], v[182:185], v[18:21]
	v_mfma_f32_16x16x32_bf16 v[6:9], v[150:153], v[190:193], v[6:9]
	v_mfma_f32_16x16x32_bf16 v[2:5], v[158:161], v[190:193], v[2:5]
	s_barrier
; #define PG8_STAGE(bufoff, gbase, voff) do { _Pragma("unroll") for (int _i = 0; _i < 2; ++_i) \
;         __builtin_amdgcn_global_load_lds((const unsigned*)((const char*)(gbase) + (voff)[_i]), (LAS unsigned*)(lds + (bufoff) + ldsw + _i * 8192), 16, 0, 0); } while (0)
; #define PG8_LDA(dst, b, h) do { _Pragma("unroll") for (int m = 0; m < 4; ++m) _Pragma("unroll") for (int k = 0; k < 2; ++k) dst[m][k] = *(const LAS bf16x8*)(lds + PG8_SA(b, h) + aoff + m * 2048 + k * 1024); } while (0)
; #define PG8_LDB(dst, b, h) do { _Pragma("unroll") for (int n = 0; n < 2; ++n) _Pragma("unroll") for (int k = 0; k < 2; ++k) dst[n][k] = *(const LAS bf16x8*)(lds + PG8_SB(b, h) + boff + n * 2048 + k * 1024); } while (0)
; #define PG8_MMA(ai, bj, At, Bt) do { __builtin_amdgcn_s_setprio(1); _Pragma("unroll") for (int m = 0; m < 4; ++m) _Pragma("unroll") for (int n = 0; n < 2; ++n) _Pragma("unroll") for (int k = 0; k < 2; ++k) \
;         acc[ai][bj][m][n] = __builtin_amdgcn_mfma_f32_16x16x32_bf16(Bt[n][k], At[m][k], acc[ai][bj][m][n], 0, 0, 0); __builtin_amdgcn_s_setprio(0); } while (0)
; #define PG8_WAIT_V(n) asm volatile("s_waitcnt vmcnt(" #n ")" ::: "memory")
; #define PG8_WAIT_L(n) asm volatile("s_waitcnt lgkmcnt(" #n ")" ::: "memory")
; #define PG8_BAR __builtin_amdgcn_s_barrier()
; #define PG8_SCHED __builtin_amdgcn_sched_barrier(0)
; template <class Epi, class Sched, int KC, bool ALIGN_EPI = false, bool SP2 = false, bool ATILED = false>
; __device__ __forceinline__ void gemm_phase(LAS unsigned char* lds, const Gemm g, const Sched& S, const Epi& E, int wave_s) {
;     ...
;             PG8_LDB(B0, 1, 0); PG8_LDB(B1, 1, 1); PG8_SCHED; PG8_LDA(At, 1, 0); PG8_STAGE(PG8_SA(0, 1), a2 + hstepA, voffA);
;             PG8_WAIT_V(8); PG8_WAIT_L(0); PG8_BAR; PG8_MMA(0, 0, At, B0); PG8_MMA(0, 1, At, B1); PG8_BAR; PG8_SCHED;
;             PG8_LDA(At, 1, 1); PG8_STAGE(PG8_SB(1, 0), b3, voffB); PG8_STAGE(PG8_SB(1, 1), b3 + hstepB, voffB); PG8_STAGE(PG8_SA(1, 0), a3, voffA);
;             PG8_WAIT_V(8); PG8_WAIT_L(0); PG8_BAR; PG8_MMA(1, 0, At, B0); PG8_MMA(1, 1, At, B1); PG8_BAR; PG8_SCHED;
	s_add_i32 s49, 0, 0x18000
	v_add_u32_e32 v142, s49, v229
	s_add_i32 s50, 0, 0x1c000
	v_add_u32_e32 v158, s50, v229
	ds_read_b128 v[130:133], v142
	ds_read_b128 v[134:137], v142 offset:1024
	ds_read_b128 v[138:141], v142 offset:2048
	ds_read_b128 v[142:145], v142 offset:3072
	ds_read_b128 v[146:149], v158
	ds_read_b128 v[150:153], v158 offset:1024
	ds_read_b128 v[154:157], v158 offset:2048
	ds_read_b128 v[158:161], v158 offset:3072
	ds_read_b128 v[162:165], v230 offset:32768
	ds_read_b128 v[166:169], v230 offset:33792
	ds_read_b128 v[170:173], v230 offset:34816
	ds_read_b128 v[174:177], v230 offset:35840
	ds_read_b128 v[178:181], v230 offset:36864
	ds_read_b128 v[182:185], v230 offset:37888
	ds_read_b128 v[186:189], v230 offset:38912
	ds_read_b128 v[190:193], v230 offset:39936
	s_add_u32 s22, s22, 0x80000
	s_addc_u32 s23, s23, 0
	s_mov_b32 m0, s36
	s_nop 0
	global_load_lds_dwordx4 v198, s[22:23]
	s_mov_b32 m0, s37
	s_nop 0
	global_load_lds_dwordx4 v200, s[22:23]
	s_waitcnt vmcnt(8)
	s_waitcnt lgkmcnt(0)
	s_barrier
	s_waitcnt lgkmcnt(0)
	v_mfma_f32_16x16x32_bf16 v[126:129], v[130:133], v[162:165], v[126:129]
	v_mfma_f32_16x16x32_bf16 v[122:125], v[138:141], v[162:165], v[122:125]
	v_mfma_f32_16x16x32_bf16 v[110:113], v[130:133], v[170:173], v[110:113]
	v_mfma_f32_16x16x32_bf16 v[106:109], v[138:141], v[170:173], v[106:109]
	v_mfma_f32_16x16x32_bf16 v[94:97], v[130:133], v[178:181], v[94:97]
	v_mfma_f32_16x16x32_bf16 v[90:93], v[138:141], v[178:181], v[90:93]
	v_mfma_f32_16x16x32_bf16 v[78:81], v[130:133], v[186:189], v[78:81]
	v_mfma_f32_16x16x32_bf16 v[74:77], v[138:141], v[186:189], v[74:77]
	v_mfma_f32_16x16x32_bf16 v[126:129], v[134:137], v[166:169], v[126:129]
	v_mfma_f32_16x16x32_bf16 v[122:125], v[142:145], v[166:169], v[122:125]
	v_mfma_f32_16x16x32_bf16 v[110:113], v[134:137], v[174:177], v[110:113]
	v_mfma_f32_16x16x32_bf16 v[106:109], v[142:145], v[174:177], v[106:109]
	v_mfma_f32_16x16x32_bf16 v[94:97], v[134:137], v[182:185], v[94:97]
	v_mfma_f32_16x16x32_bf16 v[90:93], v[142:145], v[182:185], v[90:93]
	v_mfma_f32_16x16x32_bf16 v[78:81], v[134:137], v[190:193], v[78:81]
	v_mfma_f32_16x16x32_bf16 v[74:77], v[142:145], v[190:193], v[74:77]
	v_mfma_f32_16x16x32_bf16 v[118:121], v[146:149], v[162:165], v[118:121]
	v_mfma_f32_16x16x32_bf16 v[114:117], v[154:157], v[162:165], v[114:117]
	v_mfma_f32_16x16x32_bf16 v[102:105], v[146:149], v[170:173], v[102:105]
	v_mfma_f32_16x16x32_bf16 v[98:101], v[154:157], v[170:173], v[98:101]
	v_mfma_f32_16x16x32_bf16 v[86:89], v[146:149], v[178:181], v[86:89]
	v_mfma_f32_16x16x32_bf16 v[82:85], v[154:157], v[178:181], v[82:85]
	v_mfma_f32_16x16x32_bf16 v[70:73], v[146:149], v[186:189], v[70:73]
	v_mfma_f32_16x16x32_bf16 v[66:69], v[154:157], v[186:189], v[66:69]
	v_mfma_f32_16x16x32_bf16 v[118:121], v[150:153], v[166:169], v[118:121]
	v_mfma_f32_16x16x32_bf16 v[114:117], v[158:161], v[166:169], v[114:117]
	v_mfma_f32_16x16x32_bf16 v[102:105], v[150:153], v[174:177], v[102:105]
	v_mfma_f32_16x16x32_bf16 v[98:101], v[158:161], v[174:177], v[98:101]
	v_mfma_f32_16x16x32_bf16 v[86:89], v[150:153], v[182:185], v[86:89]
	v_mfma_f32_16x16x32_bf16 v[82:85], v[158:161], v[182:185], v[82:85]
	v_mfma_f32_16x16x32_bf16 v[70:73], v[150:153], v[190:193], v[70:73]
	v_mfma_f32_16x16x32_bf16 v[66:69], v[158:161], v[190:193], v[66:69]
	s_barrier
	ds_read_b128 v[162:165], v230 offset:49152
	ds_read_b128 v[166:169], v230 offset:50176
	ds_read_b128 v[170:173], v230 offset:51200
	ds_read_b128 v[174:177], v230 offset:52224
	ds_read_b128 v[178:181], v230 offset:53248
	ds_read_b128 v[182:185], v230 offset:54272
	ds_read_b128 v[186:189], v230 offset:55296
	ds_read_b128 v[190:193], v230 offset:56320
	s_add_u32 s98, s20, 0x80
	s_addc_u32 s99, s21, 0
	s_add_i32 s22, s49, s31
	s_mov_b32 m0, s22
	s_nop 0
	global_load_lds_dwordx4 v0, s[98:99]
	s_add_i32 m0, s22, 0x2000
	s_add_u32 s20, s20, 0x20080
	s_addc_u32 s21, s21, 0
	s_add_i32 s22, s50, s31
	global_load_lds_dwordx4 v202, s[98:99]
	s_mov_b32 m0, s22
	s_nop 0
	global_load_lds_dwordx4 v0, s[20:21]
	s_add_i32 m0, s22, 0x2000
	s_nop 0
	global_load_lds_dwordx4 v202, s[20:21]
	s_mov_b32 m0, s41
	s_nop 0
	global_load_lds_dwordx4 v198, s[100:101]
	s_mov_b32 m0, s42
	s_nop 0
	global_load_lds_dwordx4 v200, s[100:101]
	s_waitcnt vmcnt(8)
	s_waitcnt lgkmcnt(0)
	s_barrier
	s_waitcnt lgkmcnt(0)
	v_mfma_f32_16x16x32_bf16 v[62:65], v[130:133], v[162:165], v[62:65]
	v_mfma_f32_16x16x32_bf16 v[58:61], v[138:141], v[162:165], v[58:61]
	v_mfma_f32_16x16x32_bf16 v[46:49], v[130:133], v[170:173], v[46:49]
	v_mfma_f32_16x16x32_bf16 v[42:45], v[138:141], v[170:173], v[42:45]
	v_mfma_f32_16x16x32_bf16 v[30:33], v[130:133], v[178:181], v[30:33]
	v_mfma_f32_16x16x32_bf16 v[26:29], v[138:141], v[178:181], v[26:29]
	v_mfma_f32_16x16x32_bf16 v[14:17], v[130:133], v[186:189], v[14:17]
	v_mfma_f32_16x16x32_bf16 v[10:13], v[138:141], v[186:189], v[10:13]
	v_mfma_f32_16x16x32_bf16 v[62:65], v[134:137], v[166:169], v[62:65]
	v_mfma_f32_16x16x32_bf16 v[58:61], v[142:145], v[166:169], v[58:61]
	v_mfma_f32_16x16x32_bf16 v[46:49], v[134:137], v[174:177], v[46:49]
	v_mfma_f32_16x16x32_bf16 v[42:45], v[142:145], v[174:177], v[42:45]
	v_mfma_f32_16x16x32_bf16 v[30:33], v[134:137], v[182:185], v[30:33]
	v_mfma_f32_16x16x32_bf16 v[26:29], v[142:145], v[182:185], v[26:29]
	v_mfma_f32_16x16x32_bf16 v[14:17], v[134:137], v[190:193], v[14:17]
	v_mfma_f32_16x16x32_bf16 v[10:13], v[142:145], v[190:193], v[10:13]
	v_mfma_f32_16x16x32_bf16 v[54:57], v[146:149], v[162:165], v[54:57]
	v_mfma_f32_16x16x32_bf16 v[50:53], v[154:157], v[162:165], v[50:53]
	v_mfma_f32_16x16x32_bf16 v[38:41], v[146:149], v[170:173], v[38:41]
	v_mfma_f32_16x16x32_bf16 v[34:37], v[154:157], v[170:173], v[34:37]
	v_mfma_f32_16x16x32_bf16 v[22:25], v[146:149], v[178:181], v[22:25]
	v_mfma_f32_16x16x32_bf16 v[18:21], v[154:157], v[178:181], v[18:21]
	v_mfma_f32_16x16x32_bf16 v[6:9], v[146:149], v[186:189], v[6:9]
	v_mfma_f32_16x16x32_bf16 v[2:5], v[154:157], v[186:189], v[2:5]
	v_mfma_f32_16x16x32_bf16 v[54:57], v[150:153], v[166:169], v[54:57]
	v_mfma_f32_16x16x32_bf16 v[50:53], v[158:161], v[166:169], v[50:53]
	v_mfma_f32_16x16x32_bf16 v[38:41], v[150:153], v[174:177], v[38:41]
	v_mfma_f32_16x16x32_bf16 v[34:37], v[158:161], v[174:177], v[34:37]
	v_mfma_f32_16x16x32_bf16 v[22:25], v[150:153], v[182:185], v[22:25]
	v_mfma_f32_16x16x32_bf16 v[18:21], v[158:161], v[182:185], v[18:21]
	v_mfma_f32_16x16x32_bf16 v[6:9], v[150:153], v[190:193], v[6:9]
	v_mfma_f32_16x16x32_bf16 v[2:5], v[158:161], v[190:193], v[2:5]
	s_barrier
; #define GAS __attribute__((address_space(1)))
; DI unsigned cvtpk(float lo, float hi) { unsigned r; asm volatile("v_cvt_pk_bf16_f32 %0, %1, %2" : "=v"(r) : "v"(lo), "v"(hi)); return r; }
; DI float sum_xor16(float s) { auto r = __builtin_amdgcn_permlane16_swap(__float_as_uint(s), __float_as_uint(s), false, false); return __uint_as_float(r[0]) + __uint_as_float(r[1]); }
;     DI void operator()(const f32x4 (&acc)[2][2][4][2], const Unit& u, int wr, int wc, int fr, int fq) const {
;     ...
;         u32x4 H[2][4][2];
; #pragma unroll
;         for (int ai = 0; ai < 2; ++ai)
; #pragma unroll
;             for (int m = 0; m < 4; ++m)
; #pragma unroll
;                 for (int bj = 0; bj < 2; ++bj) H[ai][m][bj] = *(const GAS u32x4*)(hi + hbase + (size_t)(row0 + ai * HALF + m * 16) * 256 + bj * 32);
;         asm volatile("" ::: "memory");
; #pragma unroll
;         for (int ai = 0; ai < 2; ++ai) {
; #pragma unroll
;             for (int m = 0; m < 4; ++m) {
;                 const int r = row0 + ai * HALF + m * 16; const size_t off = (size_t)r * DM + col0; float ss = 0.f;
; #pragma unroll
;                 for (int bj = 0; bj < 2; ++bj) {
;                     const u32x4 h = H[ai][m][bj];
;                     const f32x4 a0 = acc[ai][bj][m][0], a1 = acc[ai][bj][m][1];
;                     float v[8];
;                     v[0] = bflo(h.x) + a0[0] * scale; v[1] = bfhi(h.x) + a0[1] * scale;
;                     v[2] = bflo(h.y) + a0[2] * scale; v[3] = bfhi(h.y) + a0[3] * scale;
;                     v[4] = bflo(h.z) + a1[0] * scale; v[5] = bfhi(h.z) + a1[1] * scale;
;                     v[6] = bflo(h.w) + a1[2] * scale; v[7] = bfhi(h.w) + a1[3] * scale;
; #pragma unroll
;                     for (int e = 0; e < 8; ++e) ss += v[e] * v[e];
;                     u32x4 nh;
;                     nh.x = cvtpk(v[0], v[1]); nh.y = cvtpk(v[2], v[3]); nh.z = cvtpk(v[4], v[5]); nh.w = cvtpk(v[6], v[7]);
;                     *(GAS u32x4*)(hi + hbase + (size_t)r * 256 + bj * 32) = nh;
;                     if (out) { *(GAS f32x4*)(out + off + bj * 32) = (f32x4){v[0], v[1], v[2], v[3]}; *(GAS f32x4*)(out + off + bj * 32 + 4) = (f32x4){v[4], v[5], v[6], v[7]}; }
;                 }
;                 ss = sum_xor32(sum_xor16(ss));
;                 if (fq == 0) ((GAS float*)rowss)[(size_t)(u.pn * 4 + wc) * M + r] = ss;
	s_add_i32 s48, s48, 2
	s_add_u32 s46, s46, 0x100
	s_addc_u32 s47, s47, 0
	s_add_u32 s18, s18, 0x100
	s_addc_u32 s19, s19, 0
	s_cmp_gt_u32 s48, 29
	s_cbranch_scc0 .LBB0_1021
	v_lshl_add_u32 v210, s16, 8, v228
	s_ashr_i32 s15, s14, 31
	s_lshl_b64 s[16:17], s[14:15], 23
	v_ashrrev_i32_e32 v211, 31, v210
	v_lshl_add_u64 v[130:131], v[204:205], 0, s[16:17]
	v_lshlrev_b64 v[132:133], 9, v[210:211]
	v_lshl_add_u64 v[226:227], v[130:131], 0, v[132:133]
	global_load_dwordx4 v[190:193], v[226:227], off
	global_load_dwordx4 v[186:189], v[226:227], off offset:64
	v_or_b32_e32 v132, 16, v210
	v_ashrrev_i32_e32 v133, 31, v132
	v_lshlrev_b64 v[132:133], 9, v[132:133]
	v_lshl_add_u64 v[224:225], v[130:131], 0, v[132:133]
	v_or_b32_e32 v132, 32, v210
	v_ashrrev_i32_e32 v133, 31, v132
	v_lshlrev_b64 v[132:133], 9, v[132:133]
	v_lshl_add_u64 v[222:223], v[130:131], 0, v[132:133]
	v_or_b32_e32 v132, 48, v210
	v_ashrrev_i32_e32 v133, 31, v132
	v_lshlrev_b64 v[132:133], 9, v[132:133]
	s_mov_b32 s3, 0x10000
	v_lshl_add_u64 v[220:221], v[130:131], 0, v[132:133]
	v_add_co_u32_e32 v130, vcc, s3, v226
	s_mov_b64 s[16:17], 0x10000
	s_nop 0
	v_addc_co_u32_e32 v131, vcc, 0, v227, vcc
	s_mov_b32 s3, 0x12000
	global_load_dwordx4 v[182:185], v[224:225], off
	global_load_dwordx4 v[178:181], v[224:225], off offset:64
	global_load_dwordx4 v[174:177], v[222:223], off
	global_load_dwordx4 v[170:173], v[222:223], off offset:64
	global_load_dwordx4 v[166:169], v[220:221], off
	global_load_dwordx4 v[162:165], v[220:221], off offset:64
	v_lshl_add_u64 v[218:219], v[226:227], 0, s[16:17]
	global_load_dwordx4 v[158:161], v[130:131], off
	global_load_dwordx4 v[150:153], v[218:219], off offset:64
	v_add_co_u32_e32 v130, vcc, s3, v226
	s_mov_b64 s[16:17], 0x12000
	s_nop 0
	v_addc_co_u32_e32 v131, vcc, 0, v227, vcc
	s_mov_b32 s3, 0x14000
	v_lshl_add_u64 v[216:217], v[226:227], 0, s[16:17]
	global_load_dwordx4 v[154:157], v[130:131], off
	global_load_dwordx4 v[146:149], v[216:217], off offset:64
	v_add_co_u32_e32 v130, vcc, s3, v226
	s_mov_b64 s[16:17], 0x14000
	s_nop 0
	v_addc_co_u32_e32 v131, vcc, 0, v227, vcc
	s_mov_b32 s3, 0x16000
	v_lshl_add_u64 v[214:215], v[226:227], 0, s[16:17]
	global_load_dwordx4 v[142:145], v[130:131], off
	global_load_dwordx4 v[134:137], v[214:215], off offset:64
	v_add_co_u32_e32 v130, vcc, s3, v226
	s_mov_b64 s[16:17], 0x16000
	s_nop 0
	v_addc_co_u32_e32 v131, vcc, 0, v227, vcc
	v_lshl_add_u64 v[212:213], v[226:227], 0, s[16:17]
	global_load_dwordx4 v[138:141], v[130:131], off
	s_nop 0
	global_load_dwordx4 v[130:133], v[212:213], off offset:64
	s_lshl_b32 s3, s14, 2
	s_or_b32 s14, s3, s40
	s_ashr_i32 s15, s14, 31
	s_lshl_b64 s[14:15], s[14:15], 16
	s_waitcnt vmcnt(0)
	v_lshlrev_b32_e32 v194, 16, v190
	v_and_b32_e32 v190, 0xffff0000, v190
	v_add_f32_e32 v127, v127, v190
	v_lshlrev_b32_e32 v190, 16, v191
	v_add_f32_e32 v128, v128, v190
	v_and_b32_e32 v190, 0xffff0000, v191
	v_add_f32_e32 v129, v129, v190
	v_lshlrev_b32_e32 v190, 16, v192
	v_add_f32_e32 v190, v122, v190
	v_and_b32_e32 v122, 0xffff0000, v192
	v_add_f32_e32 v191, v123, v122
	v_lshlrev_b32_e32 v122, 16, v193
	v_add_f32_e32 v126, v126, v194
	v_add_f32_e32 v192, v124, v122
	v_and_b32_e32 v122, 0xffff0000, v193
	v_mul_f32_e32 v193, v127, v127
	v_fmac_f32_e32 v193, v126, v126
	v_fmac_f32_e32 v193, v128, v128
	v_fmac_f32_e32 v193, v129, v129
	v_fmac_f32_e32 v193, v190, v190
	v_fmac_f32_e32 v193, v191, v191
	v_add_f32_e32 v125, v125, v122
	v_fmac_f32_e32 v193, v192, v192
	v_cvt_pk_bf16_f32 v122, v126, v127
	v_fmac_f32_e32 v193, v125, v125
	v_cvt_pk_bf16_f32 v123, v128, v129
	v_cvt_pk_bf16_f32 v124, v190, v191
	v_cvt_pk_bf16_f32 v125, v192, v125
	global_store_dwordx4 v[226:227], v[122:125], off
	s_nop 1
	v_lshlrev_b32_e32 v122, 16, v186
	v_add_f32_e32 v118, v118, v122
	v_and_b32_e32 v122, 0xffff0000, v186
	v_add_f32_e32 v119, v119, v122
	v_lshlrev_b32_e32 v122, 16, v187
	v_fmac_f32_e32 v193, v118, v118
	v_add_f32_e32 v120, v120, v122
	v_and_b32_e32 v122, 0xffff0000, v187
	v_fmac_f32_e32 v193, v119, v119
	v_add_f32_e32 v121, v121, v122
	v_lshlrev_b32_e32 v122, 16, v188
	v_fmac_f32_e32 v193, v120, v120
	v_add_f32_e32 v122, v114, v122
	v_and_b32_e32 v114, 0xffff0000, v188
	v_fmac_f32_e32 v193, v121, v121
	v_add_f32_e32 v123, v115, v114
	v_lshlrev_b32_e32 v114, 16, v189
	v_fmac_f32_e32 v193, v122, v122
	v_add_f32_e32 v124, v116, v114
	v_and_b32_e32 v114, 0xffff0000, v189
	v_fmac_f32_e32 v193, v123, v123
	v_add_f32_e32 v117, v117, v114
	v_fmac_f32_e32 v193, v124, v124
	v_fmac_f32_e32 v193, v117, v117
	v_cvt_pk_bf16_f32 v114, v118, v119
	v_cvt_pk_bf16_f32 v115, v120, v121
	v_cvt_pk_bf16_f32 v116, v122, v123
	v_cvt_pk_bf16_f32 v117, v124, v117
	global_store_dwordx4 v[226:227], v[114:117], off offset:64
	s_nop 1
	v_mov_b32_e32 v114, v193
	s_nop 1
	v_permlane16_swap_b32_e32 v193, v114
	v_add_f32_e32 v114, v193, v114
	v_mov_b32_e32 v115, v114
	s_nop 1
	v_permlane32_swap_b32_e32 v114, v115
	s_and_saveexec_b64 s[16:17], s[4:5]
	s_cbranch_execz .LBB0_1024
	s_add_u32 s18, s38, s14
	s_addc_u32 s19, s39, s15
	v_lshl_add_u64 v[116:117], v[210:211], 2, s[18:19]
	v_add_f32_e32 v114, v114, v115
	global_store_dword v[116:117], v114, off
